# GEMM main loops: the 32 MFMAs of a super-phase issue along a Gray path: every neighbour shares the accumulator or one operand fragment
# baseline (speedup 1.0000x reference)
.LBB0_472:
	ds_read_b128 v[152:155], v148
	ds_read_b128 v[156:159], v148 offset:1024
	ds_read_b128 v[166:169], v148 offset:2048
	ds_read_b128 v[170:173], v148 offset:3072
	ds_read_b128 v[174:177], v149
	ds_read_b128 v[178:181], v149 offset:1024
	ds_read_b128 v[182:185], v149 offset:2048
	ds_read_b128 v[186:189], v149 offset:3072
	s_add_u32 s44, s54, 0xfff00080
	s_addc_u32 s56, s55, -1
	s_cmp_eq_u32 s72, 60
	s_cselect_b32 s59, s17, s56
	s_cselect_b32 s58, s68, s44
	s_cselect_b32 s57, s15, s71
	s_cselect_b32 s56, s69, s70
	v_lshl_add_u64 v[160:161], s[54:55], 0, v[138:139]
	s_add_i32 m0, s41, 0xc000
	ds_read_b128 v[190:193], v150
	ds_read_b128 v[194:197], v150 offset:1024
	ds_read_b128 v[198:201], v150 offset:2048
	ds_read_b128 v[202:205], v150 offset:3072
	ds_read_b128 v[206:209], v150 offset:4096
	ds_read_b128 v[210:213], v150 offset:5120
	ds_read_b128 v[214:217], v150 offset:6144
	ds_read_b128 v[218:221], v150 offset:7168
	global_load_lds_dwordx4 v[160:161], off
	v_lshl_add_u64 v[160:161], s[54:55], 0, v[140:141]
	s_add_i32 m0, s41, 0xe000
	s_nop 0
	global_load_lds_dwordx4 v[160:161], off
	s_waitcnt vmcnt(8)
	s_waitcnt lgkmcnt(0)
	s_barrier
	s_setprio 1
	s_waitcnt lgkmcnt(0)
	v_mfma_f32_16x16x32_bf16 v[126:129], v[152:155], v[190:193], v[126:129]
	v_mfma_f32_16x16x32_bf16 v[126:129], v[156:159], v[194:197], v[126:129]
	v_mfma_f32_16x16x32_bf16 v[122:125], v[170:173], v[194:197], v[122:125]
	v_mfma_f32_16x16x32_bf16 v[122:125], v[166:169], v[190:193], v[122:125]
	v_mfma_f32_16x16x32_bf16 v[114:117], v[174:177], v[190:193], v[114:117]
	v_mfma_f32_16x16x32_bf16 v[114:117], v[178:181], v[194:197], v[114:117]
	v_mfma_f32_16x16x32_bf16 v[106:109], v[186:189], v[194:197], v[106:109]
	v_mfma_f32_16x16x32_bf16 v[106:109], v[182:185], v[190:193], v[106:109]
	v_mfma_f32_16x16x32_bf16 v[90:93], v[182:185], v[198:201], v[90:93]
	v_mfma_f32_16x16x32_bf16 v[90:93], v[186:189], v[202:205], v[90:93]
	v_mfma_f32_16x16x32_bf16 v[98:101], v[178:181], v[202:205], v[98:101]
	v_mfma_f32_16x16x32_bf16 v[98:101], v[174:177], v[198:201], v[98:101]
	v_mfma_f32_16x16x32_bf16 v[110:113], v[166:169], v[198:201], v[110:113]
	v_mfma_f32_16x16x32_bf16 v[110:113], v[170:173], v[202:205], v[110:113]
	v_mfma_f32_16x16x32_bf16 v[118:121], v[156:159], v[202:205], v[118:121]
	v_mfma_f32_16x16x32_bf16 v[118:121], v[152:155], v[198:201], v[118:121]
	v_mfma_f32_16x16x32_bf16 v[102:105], v[152:155], v[206:209], v[102:105]
	v_mfma_f32_16x16x32_bf16 v[102:105], v[156:159], v[210:213], v[102:105]
	v_mfma_f32_16x16x32_bf16 v[94:97], v[170:173], v[210:213], v[94:97]
	v_mfma_f32_16x16x32_bf16 v[94:97], v[166:169], v[206:209], v[94:97]
	v_mfma_f32_16x16x32_bf16 v[82:85], v[174:177], v[206:209], v[82:85]
	v_mfma_f32_16x16x32_bf16 v[82:85], v[178:181], v[210:213], v[82:85]
	v_mfma_f32_16x16x32_bf16 v[74:77], v[186:189], v[210:213], v[74:77]
	v_mfma_f32_16x16x32_bf16 v[74:77], v[182:185], v[206:209], v[74:77]
	v_mfma_f32_16x16x32_bf16 v[66:69], v[182:185], v[214:217], v[66:69]
	v_mfma_f32_16x16x32_bf16 v[66:69], v[186:189], v[218:221], v[66:69]
	v_mfma_f32_16x16x32_bf16 v[70:73], v[178:181], v[218:221], v[70:73]
	v_mfma_f32_16x16x32_bf16 v[70:73], v[174:177], v[214:217], v[70:73]
	v_mfma_f32_16x16x32_bf16 v[78:81], v[166:169], v[214:217], v[78:81]
	v_mfma_f32_16x16x32_bf16 v[78:81], v[170:173], v[218:221], v[78:81]
	v_mfma_f32_16x16x32_bf16 v[86:89], v[156:159], v[218:221], v[86:89]
	v_mfma_f32_16x16x32_bf16 v[86:89], v[152:155], v[214:217], v[86:89]
	s_setprio 0
	s_barrier
	s_add_i32 s44, s64, s27
	v_lshl_add_u64 v[160:161], s[56:57], 0, v[134:135]
	s_mov_b32 m0, s44
	ds_read_b128 v[190:193], v150 offset:16384
	ds_read_b128 v[194:197], v150 offset:17408
	ds_read_b128 v[198:201], v150 offset:18432
	ds_read_b128 v[202:205], v150 offset:19456
	ds_read_b128 v[206:209], v150 offset:20480
	ds_read_b128 v[210:213], v150 offset:21504
	ds_read_b128 v[214:217], v150 offset:22528
	ds_read_b128 v[218:221], v150 offset:23552
	global_load_lds_dwordx4 v[160:161], off
	s_add_i32 m0, s44, 0x2000
	s_add_u32 s74, s56, 0x100000
	v_lshl_add_u64 v[222:223], s[56:57], 0, v[130:131]
	s_addc_u32 s75, s57, 0
	s_add_i32 s44, s65, s27
	global_load_lds_dwordx4 v[222:223], off
	v_lshl_add_u64 v[224:225], s[74:75], 0, v[134:135]
	s_mov_b32 m0, s44
	v_lshl_add_u64 v[226:227], s[58:59], 0, v[132:133]
	global_load_lds_dwordx4 v[224:225], off
	v_lshl_add_u64 v[224:225], s[74:75], 0, v[130:131]
	s_add_i32 m0, s44, 0x2000
	s_nop 0
	global_load_lds_dwordx4 v[224:225], off
	v_lshl_add_u64 v[224:225], s[58:59], 0, v[136:137]
	s_mov_b32 m0, s41
	s_nop 0
	global_load_lds_dwordx4 v[224:225], off
	s_mov_b32 m0, s43
	s_nop 0
	global_load_lds_dwordx4 v[226:227], off
	s_waitcnt vmcnt(8)
	s_waitcnt lgkmcnt(0)
	s_barrier
	s_setprio 1
	s_waitcnt lgkmcnt(0)
	v_mfma_f32_16x16x32_bf16 v[62:65], v[152:155], v[190:193], v[62:65]
	v_mfma_f32_16x16x32_bf16 v[62:65], v[156:159], v[194:197], v[62:65]
	v_mfma_f32_16x16x32_bf16 v[58:61], v[170:173], v[194:197], v[58:61]
	v_mfma_f32_16x16x32_bf16 v[58:61], v[166:169], v[190:193], v[58:61]
	v_mfma_f32_16x16x32_bf16 v[50:53], v[174:177], v[190:193], v[50:53]
	v_mfma_f32_16x16x32_bf16 v[50:53], v[178:181], v[194:197], v[50:53]
	v_mfma_f32_16x16x32_bf16 v[42:45], v[186:189], v[194:197], v[42:45]
	v_mfma_f32_16x16x32_bf16 v[42:45], v[182:185], v[190:193], v[42:45]
	v_mfma_f32_16x16x32_bf16 v[26:29], v[182:185], v[198:201], v[26:29]
	v_mfma_f32_16x16x32_bf16 v[26:29], v[186:189], v[202:205], v[26:29]
	v_mfma_f32_16x16x32_bf16 v[34:37], v[178:181], v[202:205], v[34:37]
	v_mfma_f32_16x16x32_bf16 v[34:37], v[174:177], v[198:201], v[34:37]
	v_mfma_f32_16x16x32_bf16 v[46:49], v[166:169], v[198:201], v[46:49]
	v_mfma_f32_16x16x32_bf16 v[46:49], v[170:173], v[202:205], v[46:49]
	v_mfma_f32_16x16x32_bf16 v[54:57], v[156:159], v[202:205], v[54:57]
	v_mfma_f32_16x16x32_bf16 v[54:57], v[152:155], v[198:201], v[54:57]
	v_mfma_f32_16x16x32_bf16 v[38:41], v[152:155], v[206:209], v[38:41]
	v_mfma_f32_16x16x32_bf16 v[38:41], v[156:159], v[210:213], v[38:41]
	v_mfma_f32_16x16x32_bf16 v[30:33], v[170:173], v[210:213], v[30:33]
	v_mfma_f32_16x16x32_bf16 v[30:33], v[166:169], v[206:209], v[30:33]
	v_mfma_f32_16x16x32_bf16 v[18:21], v[174:177], v[206:209], v[18:21]
	v_mfma_f32_16x16x32_bf16 v[18:21], v[178:181], v[210:213], v[18:21]
	v_mfma_f32_16x16x32_bf16 v[10:13], v[186:189], v[210:213], v[10:13]
	v_mfma_f32_16x16x32_bf16 v[10:13], v[182:185], v[206:209], v[10:13]
	v_mfma_f32_16x16x32_bf16 v[2:5], v[182:185], v[214:217], v[2:5]
	v_mfma_f32_16x16x32_bf16 v[2:5], v[186:189], v[218:221], v[2:5]
	v_mfma_f32_16x16x32_bf16 v[6:9], v[178:181], v[218:221], v[6:9]
	v_mfma_f32_16x16x32_bf16 v[6:9], v[174:177], v[214:217], v[6:9]
	v_mfma_f32_16x16x32_bf16 v[14:17], v[166:169], v[214:217], v[14:17]
	v_mfma_f32_16x16x32_bf16 v[14:17], v[170:173], v[218:221], v[14:17]
	v_mfma_f32_16x16x32_bf16 v[22:25], v[156:159], v[218:221], v[22:25]
	v_mfma_f32_16x16x32_bf16 v[22:25], v[152:155], v[214:217], v[22:25]
	s_setprio 0
	s_barrier
	s_add_i32 s44, 0, 0x18000
	v_add_u32_e32 v151, s44, v146
	s_add_i32 s73, 0, 0x1c000
	ds_read_b128 v[152:155], v151
	ds_read_b128 v[156:159], v151 offset:1024
	ds_read_b128 v[166:169], v151 offset:2048
	ds_read_b128 v[170:173], v151 offset:3072
	v_add_u32_e32 v151, s73, v146
	ds_read_b128 v[174:177], v151
	ds_read_b128 v[178:181], v151 offset:1024
	ds_read_b128 v[182:185], v151 offset:2048
	ds_read_b128 v[186:189], v151 offset:3072
	s_add_u32 s58, s58, 0x100000
	s_addc_u32 s59, s59, 0
	s_mov_b32 m0, s45
	v_lshl_add_u64 v[228:229], s[58:59], 0, v[136:137]
	ds_read_b128 v[190:193], v150 offset:32768
	ds_read_b128 v[194:197], v150 offset:33792
	ds_read_b128 v[198:201], v150 offset:34816
	ds_read_b128 v[202:205], v150 offset:35840
	ds_read_b128 v[206:209], v150 offset:36864
	ds_read_b128 v[210:213], v150 offset:37888
	ds_read_b128 v[214:217], v150 offset:38912
	ds_read_b128 v[218:221], v150 offset:39936
	global_load_lds_dwordx4 v[228:229], off
	v_lshl_add_u64 v[228:229], s[58:59], 0, v[132:133]
	s_mov_b32 m0, s53
	s_nop 0
	global_load_lds_dwordx4 v[228:229], off
	s_waitcnt vmcnt(8)
	s_waitcnt lgkmcnt(0)
	s_barrier
	s_setprio 1
	s_waitcnt lgkmcnt(0)
	v_mfma_f32_16x16x32_bf16 v[126:129], v[152:155], v[190:193], v[126:129]
	v_mfma_f32_16x16x32_bf16 v[126:129], v[156:159], v[194:197], v[126:129]
	v_mfma_f32_16x16x32_bf16 v[122:125], v[170:173], v[194:197], v[122:125]
	v_mfma_f32_16x16x32_bf16 v[122:125], v[166:169], v[190:193], v[122:125]
	v_mfma_f32_16x16x32_bf16 v[114:117], v[174:177], v[190:193], v[114:117]
	v_mfma_f32_16x16x32_bf16 v[114:117], v[178:181], v[194:197], v[114:117]
	v_mfma_f32_16x16x32_bf16 v[106:109], v[186:189], v[194:197], v[106:109]
	v_mfma_f32_16x16x32_bf16 v[106:109], v[182:185], v[190:193], v[106:109]
	v_mfma_f32_16x16x32_bf16 v[90:93], v[182:185], v[198:201], v[90:93]
	v_mfma_f32_16x16x32_bf16 v[90:93], v[186:189], v[202:205], v[90:93]
	v_mfma_f32_16x16x32_bf16 v[98:101], v[178:181], v[202:205], v[98:101]
	v_mfma_f32_16x16x32_bf16 v[98:101], v[174:177], v[198:201], v[98:101]
	v_mfma_f32_16x16x32_bf16 v[110:113], v[166:169], v[198:201], v[110:113]
	v_mfma_f32_16x16x32_bf16 v[110:113], v[170:173], v[202:205], v[110:113]
	v_mfma_f32_16x16x32_bf16 v[118:121], v[156:159], v[202:205], v[118:121]
	v_mfma_f32_16x16x32_bf16 v[118:121], v[152:155], v[198:201], v[118:121]
	v_mfma_f32_16x16x32_bf16 v[102:105], v[152:155], v[206:209], v[102:105]
	v_mfma_f32_16x16x32_bf16 v[102:105], v[156:159], v[210:213], v[102:105]
	v_mfma_f32_16x16x32_bf16 v[94:97], v[170:173], v[210:213], v[94:97]
	v_mfma_f32_16x16x32_bf16 v[94:97], v[166:169], v[206:209], v[94:97]
	v_mfma_f32_16x16x32_bf16 v[82:85], v[174:177], v[206:209], v[82:85]
	v_mfma_f32_16x16x32_bf16 v[82:85], v[178:181], v[210:213], v[82:85]
	v_mfma_f32_16x16x32_bf16 v[74:77], v[186:189], v[210:213], v[74:77]
	v_mfma_f32_16x16x32_bf16 v[74:77], v[182:185], v[206:209], v[74:77]
	v_mfma_f32_16x16x32_bf16 v[66:69], v[182:185], v[214:217], v[66:69]
	v_mfma_f32_16x16x32_bf16 v[66:69], v[186:189], v[218:221], v[66:69]
	v_mfma_f32_16x16x32_bf16 v[70:73], v[178:181], v[218:221], v[70:73]
	v_mfma_f32_16x16x32_bf16 v[70:73], v[174:177], v[214:217], v[70:73]
	v_mfma_f32_16x16x32_bf16 v[78:81], v[166:169], v[214:217], v[78:81]
	v_mfma_f32_16x16x32_bf16 v[78:81], v[170:173], v[218:221], v[78:81]
	v_mfma_f32_16x16x32_bf16 v[86:89], v[156:159], v[218:221], v[86:89]
	v_mfma_f32_16x16x32_bf16 v[86:89], v[152:155], v[214:217], v[86:89]
	s_setprio 0
	s_barrier
	s_add_i32 s44, s44, s27
	v_lshl_add_u64 v[160:161], v[160:161], 0, s[10:11]
	s_mov_b32 m0, s44
	ds_read_b128 v[190:193], v150 offset:49152
	ds_read_b128 v[194:197], v150 offset:50176
	ds_read_b128 v[198:201], v150 offset:51200
	ds_read_b128 v[202:205], v150 offset:52224
	ds_read_b128 v[206:209], v150 offset:53248
	ds_read_b128 v[210:213], v150 offset:54272
	ds_read_b128 v[214:217], v150 offset:55296
	ds_read_b128 v[218:221], v150 offset:56320
	global_load_lds_dwordx4 v[160:161], off
	s_add_i32 m0, s44, 0x2000
	s_add_u32 s56, s56, 0x100080
	v_lshl_add_u64 v[160:161], v[222:223], 0, s[10:11]
	s_addc_u32 s57, s57, 0
	s_add_i32 s44, s73, s27
	global_load_lds_dwordx4 v[160:161], off
	v_lshl_add_u64 v[160:161], s[56:57], 0, v[134:135]
	s_mov_b32 m0, s44
	s_nop 0
	global_load_lds_dwordx4 v[160:161], off
	v_lshl_add_u64 v[160:161], s[56:57], 0, v[130:131]
	s_add_i32 m0, s44, 0x2000
	s_nop 0
	global_load_lds_dwordx4 v[160:161], off
	v_lshl_add_u64 v[160:161], v[224:225], 0, s[10:11]
	s_mov_b32 m0, s61
	s_nop 0
	global_load_lds_dwordx4 v[160:161], off
	v_lshl_add_u64 v[160:161], v[226:227], 0, s[10:11]
	s_mov_b32 m0, s62
	s_nop 0
	global_load_lds_dwordx4 v[160:161], off
	s_waitcnt vmcnt(8)
	s_waitcnt lgkmcnt(0)
	s_barrier
	s_setprio 1
	s_waitcnt lgkmcnt(0)
	v_mfma_f32_16x16x32_bf16 v[62:65], v[152:155], v[190:193], v[62:65]
	v_mfma_f32_16x16x32_bf16 v[62:65], v[156:159], v[194:197], v[62:65]
	v_mfma_f32_16x16x32_bf16 v[58:61], v[170:173], v[194:197], v[58:61]
	v_mfma_f32_16x16x32_bf16 v[58:61], v[166:169], v[190:193], v[58:61]
	v_mfma_f32_16x16x32_bf16 v[50:53], v[174:177], v[190:193], v[50:53]
	v_mfma_f32_16x16x32_bf16 v[50:53], v[178:181], v[194:197], v[50:53]
	v_mfma_f32_16x16x32_bf16 v[42:45], v[186:189], v[194:197], v[42:45]
	v_mfma_f32_16x16x32_bf16 v[42:45], v[182:185], v[190:193], v[42:45]
	v_mfma_f32_16x16x32_bf16 v[26:29], v[182:185], v[198:201], v[26:29]
	v_mfma_f32_16x16x32_bf16 v[26:29], v[186:189], v[202:205], v[26:29]
	v_mfma_f32_16x16x32_bf16 v[34:37], v[178:181], v[202:205], v[34:37]
	v_mfma_f32_16x16x32_bf16 v[34:37], v[174:177], v[198:201], v[34:37]
	v_mfma_f32_16x16x32_bf16 v[46:49], v[166:169], v[198:201], v[46:49]
	v_mfma_f32_16x16x32_bf16 v[46:49], v[170:173], v[202:205], v[46:49]
	v_mfma_f32_16x16x32_bf16 v[54:57], v[156:159], v[202:205], v[54:57]
	v_mfma_f32_16x16x32_bf16 v[54:57], v[152:155], v[198:201], v[54:57]
	v_mfma_f32_16x16x32_bf16 v[38:41], v[152:155], v[206:209], v[38:41]
	v_mfma_f32_16x16x32_bf16 v[38:41], v[156:159], v[210:213], v[38:41]
	v_mfma_f32_16x16x32_bf16 v[30:33], v[170:173], v[210:213], v[30:33]
	v_mfma_f32_16x16x32_bf16 v[30:33], v[166:169], v[206:209], v[30:33]
	v_mfma_f32_16x16x32_bf16 v[18:21], v[174:177], v[206:209], v[18:21]
	v_mfma_f32_16x16x32_bf16 v[18:21], v[178:181], v[210:213], v[18:21]
	v_mfma_f32_16x16x32_bf16 v[10:13], v[186:189], v[210:213], v[10:13]
	v_mfma_f32_16x16x32_bf16 v[10:13], v[182:185], v[206:209], v[10:13]
	v_mfma_f32_16x16x32_bf16 v[2:5], v[182:185], v[214:217], v[2:5]
	v_mfma_f32_16x16x32_bf16 v[2:5], v[186:189], v[218:221], v[2:5]
	v_mfma_f32_16x16x32_bf16 v[6:9], v[178:181], v[218:221], v[6:9]
	v_mfma_f32_16x16x32_bf16 v[6:9], v[174:177], v[214:217], v[6:9]
	v_mfma_f32_16x16x32_bf16 v[14:17], v[166:169], v[214:217], v[14:17]
	v_mfma_f32_16x16x32_bf16 v[14:17], v[170:173], v[218:221], v[14:17]
	v_mfma_f32_16x16x32_bf16 v[22:25], v[156:159], v[218:221], v[22:25]
	v_mfma_f32_16x16x32_bf16 v[22:25], v[152:155], v[214:217], v[22:25]
	s_setprio 0
	s_barrier
	s_add_i32 s72, s72, 2
	s_add_u32 s54, s54, 0x100
	s_addc_u32 s55, s55, 0
	s_add_u32 s70, s70, 0x100
	s_addc_u32 s71, s71, 0
	s_cmp_gt_u32 s72, 61
	s_cbranch_scc0 .LBB0_472
	s_and_b64 vcc, exec, s[12:13]
	s_cbranch_vccz .LBB0_475
	s_barrier

.LBB0_706:
	s_add_u32 s72, s60, s44
	s_addc_u32 s73, s61, 0
	s_add_u32 s68, s72, 0x100
	s_addc_u32 s69, s73, 0
	s_and_b64 s[66:67], s[64:65], exec
	s_cselect_b32 s69, s17, s69
	s_cselect_b32 s68, s86, s68
	s_add_u32 s44, s56, s44
	s_addc_u32 s66, s57, 0
	s_add_u32 s44, s44, 0x100
	s_addc_u32 s66, s66, 0
	s_and_b64 s[64:65], s[64:65], exec
	s_cselect_b32 s71, s15, s66
	s_cselect_b32 s70, s87, s44
	s_add_u32 s74, s72, 0x10080
	s_addc_u32 s75, s73, 0
	s_add_i32 vcc_hi, s82, s27
	ds_read_b128 v[150:153], v147
	ds_read_b128 v[154:157], v147 offset:1024
	ds_read_b128 v[158:161], v147 offset:2048
	ds_read_b128 v[166:169], v147 offset:3072
	ds_read_b128 v[170:173], v148
	ds_read_b128 v[174:177], v148 offset:1024
	ds_read_b128 v[178:181], v148 offset:2048
	ds_read_b128 v[182:185], v148 offset:3072
	s_add_i32 m0, s36, 0xc000
	s_add_i32 s45, s36, 0xe000
	s_add_i32 s96, vcc_hi, 0x2000
	s_add_u32 s72, s70, 0x10000
	s_addc_u32 s73, s71, 0
	s_add_i32 vcc_lo, s83, s27
	s_add_i32 s97, vcc_lo, 0x2000
	s_add_i32 s95, 0, 0x18000
	s_add_i32 s94, 0, 0x1c000
	s_add_u32 s66, s68, 0x10000
	s_addc_u32 s67, s69, 0
	s_add_i32 s93, s95, s27
	s_add_i32 s89, s93, 0x2000
	s_add_u32 s64, s70, 0x10080
	s_addc_u32 s65, s71, 0
	s_add_i32 s92, s94, s27
	s_add_i32 s44, s92, 0x2000
	v_lshl_add_u64 v[198:199], s[74:75], 0, v[130:131]
	ds_read_b128 v[186:189], v149
	ds_read_b128 v[190:193], v149 offset:1024
	ds_read_b128 v[194:197], v149 offset:2048
	ds_read_b128 v[202:205], v149 offset:3072
	ds_read_b128 v[206:209], v149 offset:4096
	ds_read_b128 v[210:213], v149 offset:5120
	ds_read_b128 v[214:217], v149 offset:6144
	ds_read_b128 v[218:221], v149 offset:7168
	global_load_lds_dwordx4 v[198:199], off
	v_lshl_add_u64 v[198:199], s[74:75], 0, v[134:135]
	s_mov_b32 m0, s45
	s_nop 0
	global_load_lds_dwordx4 v[198:199], off
	s_waitcnt vmcnt(8)
	s_waitcnt lgkmcnt(0)
	s_barrier
	s_setprio 1
	s_waitcnt lgkmcnt(0)
	v_mfma_f32_16x16x32_bf16 v[126:129], v[150:153], v[186:189], v[126:129]
	v_mfma_f32_16x16x32_bf16 v[126:129], v[154:157], v[190:193], v[126:129]
	v_mfma_f32_16x16x32_bf16 v[122:125], v[166:169], v[190:193], v[122:125]
	v_mfma_f32_16x16x32_bf16 v[122:125], v[158:161], v[186:189], v[122:125]
	v_mfma_f32_16x16x32_bf16 v[114:117], v[170:173], v[186:189], v[114:117]
	v_mfma_f32_16x16x32_bf16 v[114:117], v[174:177], v[190:193], v[114:117]
	v_mfma_f32_16x16x32_bf16 v[106:109], v[182:185], v[190:193], v[106:109]
	v_mfma_f32_16x16x32_bf16 v[106:109], v[178:181], v[186:189], v[106:109]
	v_mfma_f32_16x16x32_bf16 v[90:93], v[178:181], v[194:197], v[90:93]
	v_mfma_f32_16x16x32_bf16 v[90:93], v[182:185], v[202:205], v[90:93]
	v_mfma_f32_16x16x32_bf16 v[98:101], v[174:177], v[202:205], v[98:101]
	v_mfma_f32_16x16x32_bf16 v[98:101], v[170:173], v[194:197], v[98:101]
	v_mfma_f32_16x16x32_bf16 v[110:113], v[158:161], v[194:197], v[110:113]
	v_mfma_f32_16x16x32_bf16 v[110:113], v[166:169], v[202:205], v[110:113]
	v_mfma_f32_16x16x32_bf16 v[118:121], v[154:157], v[202:205], v[118:121]
	v_mfma_f32_16x16x32_bf16 v[118:121], v[150:153], v[194:197], v[118:121]
	v_mfma_f32_16x16x32_bf16 v[102:105], v[150:153], v[206:209], v[102:105]
	v_mfma_f32_16x16x32_bf16 v[102:105], v[154:157], v[210:213], v[102:105]
	v_mfma_f32_16x16x32_bf16 v[94:97], v[166:169], v[210:213], v[94:97]
	v_mfma_f32_16x16x32_bf16 v[94:97], v[158:161], v[206:209], v[94:97]
	v_mfma_f32_16x16x32_bf16 v[82:85], v[170:173], v[206:209], v[82:85]
	v_mfma_f32_16x16x32_bf16 v[82:85], v[174:177], v[210:213], v[82:85]
	v_mfma_f32_16x16x32_bf16 v[74:77], v[182:185], v[210:213], v[74:77]
	v_mfma_f32_16x16x32_bf16 v[74:77], v[178:181], v[206:209], v[74:77]
	v_mfma_f32_16x16x32_bf16 v[66:69], v[178:181], v[214:217], v[66:69]
	v_mfma_f32_16x16x32_bf16 v[66:69], v[182:185], v[218:221], v[66:69]
	v_mfma_f32_16x16x32_bf16 v[70:73], v[174:177], v[218:221], v[70:73]
	v_mfma_f32_16x16x32_bf16 v[70:73], v[170:173], v[214:217], v[70:73]
	v_mfma_f32_16x16x32_bf16 v[78:81], v[158:161], v[214:217], v[78:81]
	v_mfma_f32_16x16x32_bf16 v[78:81], v[166:169], v[218:221], v[78:81]
	v_mfma_f32_16x16x32_bf16 v[86:89], v[154:157], v[218:221], v[86:89]
	v_mfma_f32_16x16x32_bf16 v[86:89], v[150:153], v[214:217], v[86:89]
	s_setprio 0
	s_barrier
	s_mov_b32 m0, vcc_hi
	v_lshl_add_u64 v[198:199], s[70:71], 0, v[132:133]
	ds_read_b128 v[186:189], v149 offset:16384
	ds_read_b128 v[190:193], v149 offset:17408
	ds_read_b128 v[194:197], v149 offset:18432
	ds_read_b128 v[202:205], v149 offset:19456
	ds_read_b128 v[206:209], v149 offset:20480
	ds_read_b128 v[210:213], v149 offset:21504
	ds_read_b128 v[214:217], v149 offset:22528
	ds_read_b128 v[218:221], v149 offset:23552
	global_load_lds_dwordx4 v[198:199], off
	v_lshl_add_u64 v[222:223], s[70:71], 0, v[136:137]
	s_mov_b32 m0, s96
	v_lshl_add_u64 v[224:225], s[72:73], 0, v[132:133]
	global_load_lds_dwordx4 v[222:223], off
	s_mov_b32 m0, vcc_lo
	v_lshl_add_u64 v[226:227], s[68:69], 0, v[134:135]
	global_load_lds_dwordx4 v[224:225], off
	v_lshl_add_u64 v[224:225], s[72:73], 0, v[136:137]
	s_mov_b32 m0, s97
	s_nop 0
	global_load_lds_dwordx4 v[224:225], off
	v_lshl_add_u64 v[224:225], s[68:69], 0, v[130:131]
	s_mov_b32 m0, s36
	s_nop 0
	global_load_lds_dwordx4 v[224:225], off
	s_mov_b32 m0, s55
	s_nop 0
	global_load_lds_dwordx4 v[226:227], off
	s_waitcnt vmcnt(8)
	s_waitcnt lgkmcnt(0)
	s_barrier
	s_setprio 1
	s_waitcnt lgkmcnt(0)
	v_mfma_f32_16x16x32_bf16 v[62:65], v[150:153], v[186:189], v[62:65]
	v_mfma_f32_16x16x32_bf16 v[62:65], v[154:157], v[190:193], v[62:65]
	v_mfma_f32_16x16x32_bf16 v[58:61], v[166:169], v[190:193], v[58:61]
	v_mfma_f32_16x16x32_bf16 v[58:61], v[158:161], v[186:189], v[58:61]
	v_mfma_f32_16x16x32_bf16 v[50:53], v[170:173], v[186:189], v[50:53]
	v_mfma_f32_16x16x32_bf16 v[50:53], v[174:177], v[190:193], v[50:53]
	v_mfma_f32_16x16x32_bf16 v[42:45], v[182:185], v[190:193], v[42:45]
	v_mfma_f32_16x16x32_bf16 v[42:45], v[178:181], v[186:189], v[42:45]
	v_mfma_f32_16x16x32_bf16 v[26:29], v[178:181], v[194:197], v[26:29]
	v_mfma_f32_16x16x32_bf16 v[26:29], v[182:185], v[202:205], v[26:29]
	v_mfma_f32_16x16x32_bf16 v[34:37], v[174:177], v[202:205], v[34:37]
	v_mfma_f32_16x16x32_bf16 v[34:37], v[170:173], v[194:197], v[34:37]
	v_mfma_f32_16x16x32_bf16 v[46:49], v[158:161], v[194:197], v[46:49]
	v_mfma_f32_16x16x32_bf16 v[46:49], v[166:169], v[202:205], v[46:49]
	v_mfma_f32_16x16x32_bf16 v[54:57], v[154:157], v[202:205], v[54:57]
	v_mfma_f32_16x16x32_bf16 v[54:57], v[150:153], v[194:197], v[54:57]
	v_mfma_f32_16x16x32_bf16 v[38:41], v[150:153], v[206:209], v[38:41]
	v_mfma_f32_16x16x32_bf16 v[38:41], v[154:157], v[210:213], v[38:41]
	v_mfma_f32_16x16x32_bf16 v[30:33], v[166:169], v[210:213], v[30:33]
	v_mfma_f32_16x16x32_bf16 v[30:33], v[158:161], v[206:209], v[30:33]
	v_mfma_f32_16x16x32_bf16 v[18:21], v[170:173], v[206:209], v[18:21]
	v_mfma_f32_16x16x32_bf16 v[18:21], v[174:177], v[210:213], v[18:21]
	v_mfma_f32_16x16x32_bf16 v[10:13], v[182:185], v[210:213], v[10:13]
	v_mfma_f32_16x16x32_bf16 v[10:13], v[178:181], v[206:209], v[10:13]
	v_mfma_f32_16x16x32_bf16 v[2:5], v[178:181], v[214:217], v[2:5]
	v_mfma_f32_16x16x32_bf16 v[2:5], v[182:185], v[218:221], v[2:5]
	v_mfma_f32_16x16x32_bf16 v[6:9], v[174:177], v[218:221], v[6:9]
	v_mfma_f32_16x16x32_bf16 v[6:9], v[170:173], v[214:217], v[6:9]
	v_mfma_f32_16x16x32_bf16 v[14:17], v[158:161], v[214:217], v[14:17]
	v_mfma_f32_16x16x32_bf16 v[14:17], v[166:169], v[218:221], v[14:17]
	v_mfma_f32_16x16x32_bf16 v[22:25], v[154:157], v[218:221], v[22:25]
	v_mfma_f32_16x16x32_bf16 v[22:25], v[150:153], v[214:217], v[22:25]
	s_setprio 0
	s_barrier
	v_add_u32_e32 v166, s95, v145
	v_add_u32_e32 v182, s94, v145
	ds_read_b128 v[150:153], v166
	ds_read_b128 v[154:157], v166 offset:1024
	ds_read_b128 v[158:161], v166 offset:2048
	ds_read_b128 v[166:169], v166 offset:3072
	ds_read_b128 v[170:173], v182
	ds_read_b128 v[174:177], v182 offset:1024
	ds_read_b128 v[178:181], v182 offset:2048
	ds_read_b128 v[182:185], v182 offset:3072
	s_mov_b32 m0, s76
	v_lshl_add_u64 v[228:229], s[66:67], 0, v[130:131]
	ds_read_b128 v[186:189], v149 offset:32768
	ds_read_b128 v[190:193], v149 offset:33792
	ds_read_b128 v[194:197], v149 offset:34816
	ds_read_b128 v[202:205], v149 offset:35840
	ds_read_b128 v[206:209], v149 offset:36864
	ds_read_b128 v[210:213], v149 offset:37888
	ds_read_b128 v[214:217], v149 offset:38912
	ds_read_b128 v[218:221], v149 offset:39936
	global_load_lds_dwordx4 v[228:229], off
	v_lshl_add_u64 v[228:229], s[66:67], 0, v[134:135]
	s_mov_b32 m0, s77
	s_nop 0
	global_load_lds_dwordx4 v[228:229], off
	s_waitcnt vmcnt(8)
	s_waitcnt lgkmcnt(0)
	s_barrier
	s_setprio 1
	s_waitcnt lgkmcnt(0)
	v_mfma_f32_16x16x32_bf16 v[126:129], v[150:153], v[186:189], v[126:129]
	v_mfma_f32_16x16x32_bf16 v[126:129], v[154:157], v[190:193], v[126:129]
	v_mfma_f32_16x16x32_bf16 v[122:125], v[166:169], v[190:193], v[122:125]
	v_mfma_f32_16x16x32_bf16 v[122:125], v[158:161], v[186:189], v[122:125]
	v_mfma_f32_16x16x32_bf16 v[114:117], v[170:173], v[186:189], v[114:117]
	v_mfma_f32_16x16x32_bf16 v[114:117], v[174:177], v[190:193], v[114:117]
	v_mfma_f32_16x16x32_bf16 v[106:109], v[182:185], v[190:193], v[106:109]
	v_mfma_f32_16x16x32_bf16 v[106:109], v[178:181], v[186:189], v[106:109]
	v_mfma_f32_16x16x32_bf16 v[90:93], v[178:181], v[194:197], v[90:93]
	v_mfma_f32_16x16x32_bf16 v[90:93], v[182:185], v[202:205], v[90:93]
	v_mfma_f32_16x16x32_bf16 v[98:101], v[174:177], v[202:205], v[98:101]
	v_mfma_f32_16x16x32_bf16 v[98:101], v[170:173], v[194:197], v[98:101]
	v_mfma_f32_16x16x32_bf16 v[110:113], v[158:161], v[194:197], v[110:113]
	v_mfma_f32_16x16x32_bf16 v[110:113], v[166:169], v[202:205], v[110:113]
	v_mfma_f32_16x16x32_bf16 v[118:121], v[154:157], v[202:205], v[118:121]
	v_mfma_f32_16x16x32_bf16 v[118:121], v[150:153], v[194:197], v[118:121]
	v_mfma_f32_16x16x32_bf16 v[102:105], v[150:153], v[206:209], v[102:105]
	v_mfma_f32_16x16x32_bf16 v[102:105], v[154:157], v[210:213], v[102:105]
	v_mfma_f32_16x16x32_bf16 v[94:97], v[166:169], v[210:213], v[94:97]
	v_mfma_f32_16x16x32_bf16 v[94:97], v[158:161], v[206:209], v[94:97]
	v_mfma_f32_16x16x32_bf16 v[82:85], v[170:173], v[206:209], v[82:85]
	v_mfma_f32_16x16x32_bf16 v[82:85], v[174:177], v[210:213], v[82:85]
	v_mfma_f32_16x16x32_bf16 v[74:77], v[182:185], v[210:213], v[74:77]
	v_mfma_f32_16x16x32_bf16 v[74:77], v[178:181], v[206:209], v[74:77]
	v_mfma_f32_16x16x32_bf16 v[66:69], v[178:181], v[214:217], v[66:69]
	v_mfma_f32_16x16x32_bf16 v[66:69], v[182:185], v[218:221], v[66:69]
	v_mfma_f32_16x16x32_bf16 v[70:73], v[174:177], v[218:221], v[70:73]
	v_mfma_f32_16x16x32_bf16 v[70:73], v[170:173], v[214:217], v[70:73]
	v_mfma_f32_16x16x32_bf16 v[78:81], v[158:161], v[214:217], v[78:81]
	v_mfma_f32_16x16x32_bf16 v[78:81], v[166:169], v[218:221], v[78:81]
	v_mfma_f32_16x16x32_bf16 v[86:89], v[154:157], v[218:221], v[86:89]
	v_mfma_f32_16x16x32_bf16 v[86:89], v[150:153], v[214:217], v[86:89]
	s_setprio 0
	s_barrier
	s_mov_b32 m0, s93
	v_lshl_add_u64 v[198:199], v[198:199], 0, s[10:11]
	ds_read_b128 v[186:189], v149 offset:49152
	ds_read_b128 v[190:193], v149 offset:50176
	ds_read_b128 v[194:197], v149 offset:51200
	ds_read_b128 v[202:205], v149 offset:52224
	ds_read_b128 v[206:209], v149 offset:53248
	ds_read_b128 v[210:213], v149 offset:54272
	ds_read_b128 v[214:217], v149 offset:55296
	ds_read_b128 v[218:221], v149 offset:56320
	global_load_lds_dwordx4 v[198:199], off
	v_lshl_add_u64 v[198:199], v[222:223], 0, s[10:11]
	s_mov_b32 m0, s89
	s_nop 0
	global_load_lds_dwordx4 v[198:199], off
	v_lshl_add_u64 v[198:199], s[64:65], 0, v[132:133]
	s_mov_b32 m0, s92
	s_nop 0
	global_load_lds_dwordx4 v[198:199], off
	v_lshl_add_u64 v[198:199], s[64:65], 0, v[136:137]
	s_mov_b32 m0, s44
	s_nop 0
	global_load_lds_dwordx4 v[198:199], off
	v_lshl_add_u64 v[198:199], v[224:225], 0, s[10:11]
	s_mov_b32 m0, s79
	s_nop 0
	global_load_lds_dwordx4 v[198:199], off
	v_lshl_add_u64 v[198:199], v[226:227], 0, s[10:11]
	s_mov_b32 m0, s80
	s_nop 0
	global_load_lds_dwordx4 v[198:199], off
	s_waitcnt vmcnt(8)
	s_waitcnt lgkmcnt(0)
	s_barrier
	s_setprio 1
	s_waitcnt lgkmcnt(0)
	v_mfma_f32_16x16x32_bf16 v[62:65], v[150:153], v[186:189], v[62:65]
	v_mfma_f32_16x16x32_bf16 v[62:65], v[154:157], v[190:193], v[62:65]
	v_mfma_f32_16x16x32_bf16 v[58:61], v[166:169], v[190:193], v[58:61]
	v_mfma_f32_16x16x32_bf16 v[58:61], v[158:161], v[186:189], v[58:61]
	v_mfma_f32_16x16x32_bf16 v[50:53], v[170:173], v[186:189], v[50:53]
	v_mfma_f32_16x16x32_bf16 v[50:53], v[174:177], v[190:193], v[50:53]
	v_mfma_f32_16x16x32_bf16 v[42:45], v[182:185], v[190:193], v[42:45]
	v_mfma_f32_16x16x32_bf16 v[42:45], v[178:181], v[186:189], v[42:45]
	v_mfma_f32_16x16x32_bf16 v[26:29], v[178:181], v[194:197], v[26:29]
	v_mfma_f32_16x16x32_bf16 v[26:29], v[182:185], v[202:205], v[26:29]
	v_mfma_f32_16x16x32_bf16 v[34:37], v[174:177], v[202:205], v[34:37]
	v_mfma_f32_16x16x32_bf16 v[34:37], v[170:173], v[194:197], v[34:37]
	v_mfma_f32_16x16x32_bf16 v[46:49], v[158:161], v[194:197], v[46:49]
	v_mfma_f32_16x16x32_bf16 v[46:49], v[166:169], v[202:205], v[46:49]
	v_mfma_f32_16x16x32_bf16 v[54:57], v[154:157], v[202:205], v[54:57]
	v_mfma_f32_16x16x32_bf16 v[54:57], v[150:153], v[194:197], v[54:57]
	v_mfma_f32_16x16x32_bf16 v[38:41], v[150:153], v[206:209], v[38:41]
	v_mfma_f32_16x16x32_bf16 v[38:41], v[154:157], v[210:213], v[38:41]
	v_mfma_f32_16x16x32_bf16 v[30:33], v[166:169], v[210:213], v[30:33]
	v_mfma_f32_16x16x32_bf16 v[30:33], v[158:161], v[206:209], v[30:33]
	v_mfma_f32_16x16x32_bf16 v[18:21], v[170:173], v[206:209], v[18:21]
	v_mfma_f32_16x16x32_bf16 v[18:21], v[174:177], v[210:213], v[18:21]
	v_mfma_f32_16x16x32_bf16 v[10:13], v[182:185], v[210:213], v[10:13]
	v_mfma_f32_16x16x32_bf16 v[10:13], v[178:181], v[206:209], v[10:13]
	v_mfma_f32_16x16x32_bf16 v[2:5], v[178:181], v[214:217], v[2:5]
	v_mfma_f32_16x16x32_bf16 v[2:5], v[182:185], v[218:221], v[2:5]
	v_mfma_f32_16x16x32_bf16 v[6:9], v[174:177], v[218:221], v[6:9]
	v_mfma_f32_16x16x32_bf16 v[6:9], v[170:173], v[214:217], v[6:9]
	v_mfma_f32_16x16x32_bf16 v[14:17], v[158:161], v[214:217], v[14:17]
	v_mfma_f32_16x16x32_bf16 v[14:17], v[166:169], v[218:221], v[14:17]
	v_mfma_f32_16x16x32_bf16 v[22:25], v[154:157], v[218:221], v[22:25]
	v_mfma_f32_16x16x32_bf16 v[22:25], v[150:153], v[214:217], v[22:25]
	s_setprio 0
	s_barrier
	s_movk_i32 s44, 0x100
	s_andn2_b64 vcc, exec, s[62:63]
	s_mov_b64 s[64:65], -1
	s_mov_b64 s[62:63], 0
	s_cbranch_vccz .LBB0_706
	s_and_b64 vcc, exec, s[12:13]
	s_cbranch_vccz .LBB0_709
	s_barrier

.LBB0_722:
	s_add_u32 s36, s56, s44
	s_addc_u32 s37, s57, 0
	s_add_u32 s66, s36, 0x100
	s_addc_u32 s67, s37, 0
	s_and_b64 s[64:65], s[62:63], exec
	s_cselect_b32 s67, s17, s67
	s_cselect_b32 s66, s83, s66
	s_add_u32 s44, s54, s44
	s_addc_u32 s64, s55, 0
	s_add_u32 s44, s44, 0x100
	s_addc_u32 s64, s64, 0
	s_and_b64 s[62:63], s[62:63], exec
	s_cselect_b32 s69, s15, s64
	s_cselect_b32 s68, s84, s44
	s_add_u32 s72, s36, 0x10080
	s_addc_u32 s73, s37, 0
	s_add_i32 s96, s79, s27
	ds_read_b128 v[148:151], v143
	ds_read_b128 v[152:155], v143 offset:1024
	ds_read_b128 v[156:159], v143 offset:2048
	ds_read_b128 v[166:169], v143 offset:3072
	ds_read_b128 v[170:173], v145
	ds_read_b128 v[174:177], v145 offset:1024
	ds_read_b128 v[178:181], v145 offset:2048
	ds_read_b128 v[182:185], v145 offset:3072
	s_add_i32 m0, s43, 0xc000
	s_add_i32 s97, s43, 0xe000
	s_add_i32 s93, s96, 0x2000
	s_add_u32 s70, s68, 0x10000
	s_addc_u32 s71, s69, 0
	s_add_i32 s95, s80, s27
	s_add_i32 s94, s95, 0x2000
	s_add_i32 s92, 0, 0x18000
	s_add_i32 s89, 0, 0x1c000
	s_add_u32 s64, s66, 0x10000
	s_addc_u32 s65, s67, 0
	s_add_i32 s87, s92, s27
	s_add_i32 s85, s87, 0x2000
	s_add_u32 s62, s68, 0x10080
	s_addc_u32 s63, s69, 0
	s_add_i32 s86, s89, s27
	s_add_i32 s44, s86, 0x2000
	v_lshl_add_u64 v[160:161], s[72:73], 0, v[130:131]
	ds_read_b128 v[186:189], v146
	ds_read_b128 v[190:193], v146 offset:1024
	ds_read_b128 v[194:197], v146 offset:2048
	ds_read_b128 v[202:205], v146 offset:3072
	ds_read_b128 v[206:209], v146 offset:4096
	ds_read_b128 v[210:213], v146 offset:5120
	ds_read_b128 v[214:217], v146 offset:6144
	ds_read_b128 v[218:221], v146 offset:7168
	global_load_lds_dwordx4 v[160:161], off
	v_lshl_add_u64 v[160:161], s[72:73], 0, v[134:135]
	s_mov_b32 m0, s97
	s_nop 0
	global_load_lds_dwordx4 v[160:161], off
	s_waitcnt vmcnt(8)
	s_waitcnt lgkmcnt(0)
	s_barrier
	s_setprio 1
	s_waitcnt lgkmcnt(0)
	v_mfma_f32_16x16x32_bf16 v[126:129], v[148:151], v[186:189], v[126:129]
	v_mfma_f32_16x16x32_bf16 v[126:129], v[152:155], v[190:193], v[126:129]
	v_mfma_f32_16x16x32_bf16 v[122:125], v[166:169], v[190:193], v[122:125]
	v_mfma_f32_16x16x32_bf16 v[122:125], v[156:159], v[186:189], v[122:125]
	v_mfma_f32_16x16x32_bf16 v[114:117], v[170:173], v[186:189], v[114:117]
	v_mfma_f32_16x16x32_bf16 v[114:117], v[174:177], v[190:193], v[114:117]
	v_mfma_f32_16x16x32_bf16 v[106:109], v[182:185], v[190:193], v[106:109]
	v_mfma_f32_16x16x32_bf16 v[106:109], v[178:181], v[186:189], v[106:109]
	v_mfma_f32_16x16x32_bf16 v[90:93], v[178:181], v[194:197], v[90:93]
	v_mfma_f32_16x16x32_bf16 v[90:93], v[182:185], v[202:205], v[90:93]
	v_mfma_f32_16x16x32_bf16 v[98:101], v[174:177], v[202:205], v[98:101]
	v_mfma_f32_16x16x32_bf16 v[98:101], v[170:173], v[194:197], v[98:101]
	v_mfma_f32_16x16x32_bf16 v[110:113], v[156:159], v[194:197], v[110:113]
	v_mfma_f32_16x16x32_bf16 v[110:113], v[166:169], v[202:205], v[110:113]
	v_mfma_f32_16x16x32_bf16 v[118:121], v[152:155], v[202:205], v[118:121]
	v_mfma_f32_16x16x32_bf16 v[118:121], v[148:151], v[194:197], v[118:121]
	v_mfma_f32_16x16x32_bf16 v[102:105], v[148:151], v[206:209], v[102:105]
	v_mfma_f32_16x16x32_bf16 v[102:105], v[152:155], v[210:213], v[102:105]
	v_mfma_f32_16x16x32_bf16 v[94:97], v[166:169], v[210:213], v[94:97]
	v_mfma_f32_16x16x32_bf16 v[94:97], v[156:159], v[206:209], v[94:97]
	v_mfma_f32_16x16x32_bf16 v[82:85], v[170:173], v[206:209], v[82:85]
	v_mfma_f32_16x16x32_bf16 v[82:85], v[174:177], v[210:213], v[82:85]
	v_mfma_f32_16x16x32_bf16 v[74:77], v[182:185], v[210:213], v[74:77]
	v_mfma_f32_16x16x32_bf16 v[74:77], v[178:181], v[206:209], v[74:77]
	v_mfma_f32_16x16x32_bf16 v[66:69], v[178:181], v[214:217], v[66:69]
	v_mfma_f32_16x16x32_bf16 v[66:69], v[182:185], v[218:221], v[66:69]
	v_mfma_f32_16x16x32_bf16 v[70:73], v[174:177], v[218:221], v[70:73]
	v_mfma_f32_16x16x32_bf16 v[70:73], v[170:173], v[214:217], v[70:73]
	v_mfma_f32_16x16x32_bf16 v[78:81], v[156:159], v[214:217], v[78:81]
	v_mfma_f32_16x16x32_bf16 v[78:81], v[166:169], v[218:221], v[78:81]
	v_mfma_f32_16x16x32_bf16 v[86:89], v[152:155], v[218:221], v[86:89]
	v_mfma_f32_16x16x32_bf16 v[86:89], v[148:151], v[214:217], v[86:89]
	s_setprio 0
	s_barrier
	s_mov_b32 m0, s96
	v_lshl_add_u64 v[160:161], s[68:69], 0, v[132:133]
	ds_read_b128 v[186:189], v146 offset:16384
	ds_read_b128 v[190:193], v146 offset:17408
	ds_read_b128 v[194:197], v146 offset:18432
	ds_read_b128 v[202:205], v146 offset:19456
	ds_read_b128 v[206:209], v146 offset:20480
	ds_read_b128 v[210:213], v146 offset:21504
	ds_read_b128 v[214:217], v146 offset:22528
	ds_read_b128 v[218:221], v146 offset:23552
	global_load_lds_dwordx4 v[160:161], off
	v_lshl_add_u64 v[198:199], s[68:69], 0, v[136:137]
	s_mov_b32 m0, s93
	v_lshl_add_u64 v[222:223], s[70:71], 0, v[132:133]
	global_load_lds_dwordx4 v[198:199], off
	s_mov_b32 m0, s95
	v_lshl_add_u64 v[224:225], s[66:67], 0, v[134:135]
	global_load_lds_dwordx4 v[222:223], off
	v_lshl_add_u64 v[222:223], s[70:71], 0, v[136:137]
	s_mov_b32 m0, s94
	s_nop 0
	global_load_lds_dwordx4 v[222:223], off
	v_lshl_add_u64 v[222:223], s[66:67], 0, v[130:131]
	s_mov_b32 m0, s43
	s_nop 0
	global_load_lds_dwordx4 v[222:223], off
	s_mov_b32 m0, s45
	s_nop 0
	global_load_lds_dwordx4 v[224:225], off
	s_waitcnt vmcnt(8)
	s_waitcnt lgkmcnt(0)
	s_barrier
	s_setprio 1
	s_waitcnt lgkmcnt(0)
	v_mfma_f32_16x16x32_bf16 v[62:65], v[148:151], v[186:189], v[62:65]
	v_mfma_f32_16x16x32_bf16 v[62:65], v[152:155], v[190:193], v[62:65]
	v_mfma_f32_16x16x32_bf16 v[58:61], v[166:169], v[190:193], v[58:61]
	v_mfma_f32_16x16x32_bf16 v[58:61], v[156:159], v[186:189], v[58:61]
	v_mfma_f32_16x16x32_bf16 v[50:53], v[170:173], v[186:189], v[50:53]
	v_mfma_f32_16x16x32_bf16 v[50:53], v[174:177], v[190:193], v[50:53]
	v_mfma_f32_16x16x32_bf16 v[42:45], v[182:185], v[190:193], v[42:45]
	v_mfma_f32_16x16x32_bf16 v[42:45], v[178:181], v[186:189], v[42:45]
	v_mfma_f32_16x16x32_bf16 v[26:29], v[178:181], v[194:197], v[26:29]
	v_mfma_f32_16x16x32_bf16 v[26:29], v[182:185], v[202:205], v[26:29]
	v_mfma_f32_16x16x32_bf16 v[34:37], v[174:177], v[202:205], v[34:37]
	v_mfma_f32_16x16x32_bf16 v[34:37], v[170:173], v[194:197], v[34:37]
	v_mfma_f32_16x16x32_bf16 v[46:49], v[156:159], v[194:197], v[46:49]
	v_mfma_f32_16x16x32_bf16 v[46:49], v[166:169], v[202:205], v[46:49]
	v_mfma_f32_16x16x32_bf16 v[54:57], v[152:155], v[202:205], v[54:57]
	v_mfma_f32_16x16x32_bf16 v[54:57], v[148:151], v[194:197], v[54:57]
	v_mfma_f32_16x16x32_bf16 v[38:41], v[148:151], v[206:209], v[38:41]
	v_mfma_f32_16x16x32_bf16 v[38:41], v[152:155], v[210:213], v[38:41]
	v_mfma_f32_16x16x32_bf16 v[30:33], v[166:169], v[210:213], v[30:33]
	v_mfma_f32_16x16x32_bf16 v[30:33], v[156:159], v[206:209], v[30:33]
	v_mfma_f32_16x16x32_bf16 v[18:21], v[170:173], v[206:209], v[18:21]
	v_mfma_f32_16x16x32_bf16 v[18:21], v[174:177], v[210:213], v[18:21]
	v_mfma_f32_16x16x32_bf16 v[10:13], v[182:185], v[210:213], v[10:13]
	v_mfma_f32_16x16x32_bf16 v[10:13], v[178:181], v[206:209], v[10:13]
	v_mfma_f32_16x16x32_bf16 v[2:5], v[178:181], v[214:217], v[2:5]
	v_mfma_f32_16x16x32_bf16 v[2:5], v[182:185], v[218:221], v[2:5]
	v_mfma_f32_16x16x32_bf16 v[6:9], v[174:177], v[218:221], v[6:9]
	v_mfma_f32_16x16x32_bf16 v[6:9], v[170:173], v[214:217], v[6:9]
	v_mfma_f32_16x16x32_bf16 v[14:17], v[156:159], v[214:217], v[14:17]
	v_mfma_f32_16x16x32_bf16 v[14:17], v[166:169], v[218:221], v[14:17]
	v_mfma_f32_16x16x32_bf16 v[22:25], v[152:155], v[218:221], v[22:25]
	v_mfma_f32_16x16x32_bf16 v[22:25], v[148:151], v[214:217], v[22:25]
	s_setprio 0
	s_barrier
	v_add_u32_e32 v147, s92, v142
	ds_read_b128 v[148:151], v147
	ds_read_b128 v[152:155], v147 offset:1024
	ds_read_b128 v[156:159], v147 offset:2048
	ds_read_b128 v[166:169], v147 offset:3072
	v_add_u32_e32 v147, s89, v142
	ds_read_b128 v[170:173], v147
	ds_read_b128 v[174:177], v147 offset:1024
	ds_read_b128 v[178:181], v147 offset:2048
	ds_read_b128 v[182:185], v147 offset:3072
	s_mov_b32 m0, s49
	v_lshl_add_u64 v[226:227], s[64:65], 0, v[130:131]
	ds_read_b128 v[186:189], v146 offset:32768
	ds_read_b128 v[190:193], v146 offset:33792
	ds_read_b128 v[194:197], v146 offset:34816
	ds_read_b128 v[202:205], v146 offset:35840
	ds_read_b128 v[206:209], v146 offset:36864
	ds_read_b128 v[210:213], v146 offset:37888
	ds_read_b128 v[214:217], v146 offset:38912
	ds_read_b128 v[218:221], v146 offset:39936
	global_load_lds_dwordx4 v[226:227], off
	v_lshl_add_u64 v[226:227], s[64:65], 0, v[134:135]
	s_mov_b32 m0, s74
	s_nop 0
	global_load_lds_dwordx4 v[226:227], off
	s_waitcnt vmcnt(8)
	s_waitcnt lgkmcnt(0)
	s_barrier
	s_setprio 1
	s_waitcnt lgkmcnt(0)
	v_mfma_f32_16x16x32_bf16 v[126:129], v[148:151], v[186:189], v[126:129]
	v_mfma_f32_16x16x32_bf16 v[126:129], v[152:155], v[190:193], v[126:129]
	v_mfma_f32_16x16x32_bf16 v[122:125], v[166:169], v[190:193], v[122:125]
	v_mfma_f32_16x16x32_bf16 v[122:125], v[156:159], v[186:189], v[122:125]
	v_mfma_f32_16x16x32_bf16 v[114:117], v[170:173], v[186:189], v[114:117]
	v_mfma_f32_16x16x32_bf16 v[114:117], v[174:177], v[190:193], v[114:117]
	v_mfma_f32_16x16x32_bf16 v[106:109], v[182:185], v[190:193], v[106:109]
	v_mfma_f32_16x16x32_bf16 v[106:109], v[178:181], v[186:189], v[106:109]
	v_mfma_f32_16x16x32_bf16 v[90:93], v[178:181], v[194:197], v[90:93]
	v_mfma_f32_16x16x32_bf16 v[90:93], v[182:185], v[202:205], v[90:93]
	v_mfma_f32_16x16x32_bf16 v[98:101], v[174:177], v[202:205], v[98:101]
	v_mfma_f32_16x16x32_bf16 v[98:101], v[170:173], v[194:197], v[98:101]
	v_mfma_f32_16x16x32_bf16 v[110:113], v[156:159], v[194:197], v[110:113]
	v_mfma_f32_16x16x32_bf16 v[110:113], v[166:169], v[202:205], v[110:113]
	v_mfma_f32_16x16x32_bf16 v[118:121], v[152:155], v[202:205], v[118:121]
	v_mfma_f32_16x16x32_bf16 v[118:121], v[148:151], v[194:197], v[118:121]
	v_mfma_f32_16x16x32_bf16 v[102:105], v[148:151], v[206:209], v[102:105]
	v_mfma_f32_16x16x32_bf16 v[102:105], v[152:155], v[210:213], v[102:105]
	v_mfma_f32_16x16x32_bf16 v[94:97], v[166:169], v[210:213], v[94:97]
	v_mfma_f32_16x16x32_bf16 v[94:97], v[156:159], v[206:209], v[94:97]
	v_mfma_f32_16x16x32_bf16 v[82:85], v[170:173], v[206:209], v[82:85]
	v_mfma_f32_16x16x32_bf16 v[82:85], v[174:177], v[210:213], v[82:85]
	v_mfma_f32_16x16x32_bf16 v[74:77], v[182:185], v[210:213], v[74:77]
	v_mfma_f32_16x16x32_bf16 v[74:77], v[178:181], v[206:209], v[74:77]
	v_mfma_f32_16x16x32_bf16 v[66:69], v[178:181], v[214:217], v[66:69]
	v_mfma_f32_16x16x32_bf16 v[66:69], v[182:185], v[218:221], v[66:69]
	v_mfma_f32_16x16x32_bf16 v[70:73], v[174:177], v[218:221], v[70:73]
	v_mfma_f32_16x16x32_bf16 v[70:73], v[170:173], v[214:217], v[70:73]
	v_mfma_f32_16x16x32_bf16 v[78:81], v[156:159], v[214:217], v[78:81]
	v_mfma_f32_16x16x32_bf16 v[78:81], v[166:169], v[218:221], v[78:81]
	v_mfma_f32_16x16x32_bf16 v[86:89], v[152:155], v[218:221], v[86:89]
	v_mfma_f32_16x16x32_bf16 v[86:89], v[148:151], v[214:217], v[86:89]
	s_setprio 0
	s_barrier
	s_mov_b32 m0, s87
	v_lshl_add_u64 v[160:161], v[160:161], 0, s[10:11]
	ds_read_b128 v[186:189], v146 offset:49152
	ds_read_b128 v[190:193], v146 offset:50176
	ds_read_b128 v[194:197], v146 offset:51200
	ds_read_b128 v[202:205], v146 offset:52224
	ds_read_b128 v[206:209], v146 offset:53248
	ds_read_b128 v[210:213], v146 offset:54272
	ds_read_b128 v[214:217], v146 offset:55296
	ds_read_b128 v[218:221], v146 offset:56320
	global_load_lds_dwordx4 v[160:161], off
	v_lshl_add_u64 v[160:161], v[198:199], 0, s[10:11]
	s_mov_b32 m0, s85
	s_nop 0
	global_load_lds_dwordx4 v[160:161], off
	v_lshl_add_u64 v[160:161], s[62:63], 0, v[132:133]
	s_mov_b32 m0, s86
	s_nop 0
	global_load_lds_dwordx4 v[160:161], off
	v_lshl_add_u64 v[160:161], s[62:63], 0, v[136:137]
	s_mov_b32 m0, s44
	s_nop 0
	global_load_lds_dwordx4 v[160:161], off
	v_lshl_add_u64 v[160:161], v[222:223], 0, s[10:11]
	s_mov_b32 m0, s76
	s_nop 0
	global_load_lds_dwordx4 v[160:161], off
	v_lshl_add_u64 v[160:161], v[224:225], 0, s[10:11]
	s_mov_b32 m0, s77
	s_nop 0
	global_load_lds_dwordx4 v[160:161], off
	s_waitcnt vmcnt(8)
	s_waitcnt lgkmcnt(0)
	s_barrier
	s_setprio 1
	s_waitcnt lgkmcnt(0)
	v_mfma_f32_16x16x32_bf16 v[62:65], v[148:151], v[186:189], v[62:65]
	v_mfma_f32_16x16x32_bf16 v[62:65], v[152:155], v[190:193], v[62:65]
	v_mfma_f32_16x16x32_bf16 v[58:61], v[166:169], v[190:193], v[58:61]
	v_mfma_f32_16x16x32_bf16 v[58:61], v[156:159], v[186:189], v[58:61]
	v_mfma_f32_16x16x32_bf16 v[50:53], v[170:173], v[186:189], v[50:53]
	v_mfma_f32_16x16x32_bf16 v[50:53], v[174:177], v[190:193], v[50:53]
	v_mfma_f32_16x16x32_bf16 v[42:45], v[182:185], v[190:193], v[42:45]
	v_mfma_f32_16x16x32_bf16 v[42:45], v[178:181], v[186:189], v[42:45]
	v_mfma_f32_16x16x32_bf16 v[26:29], v[178:181], v[194:197], v[26:29]
	v_mfma_f32_16x16x32_bf16 v[26:29], v[182:185], v[202:205], v[26:29]
	v_mfma_f32_16x16x32_bf16 v[34:37], v[174:177], v[202:205], v[34:37]
	v_mfma_f32_16x16x32_bf16 v[34:37], v[170:173], v[194:197], v[34:37]
	v_mfma_f32_16x16x32_bf16 v[46:49], v[156:159], v[194:197], v[46:49]
	v_mfma_f32_16x16x32_bf16 v[46:49], v[166:169], v[202:205], v[46:49]
	v_mfma_f32_16x16x32_bf16 v[54:57], v[152:155], v[202:205], v[54:57]
	v_mfma_f32_16x16x32_bf16 v[54:57], v[148:151], v[194:197], v[54:57]
	v_mfma_f32_16x16x32_bf16 v[38:41], v[148:151], v[206:209], v[38:41]
	v_mfma_f32_16x16x32_bf16 v[38:41], v[152:155], v[210:213], v[38:41]
	v_mfma_f32_16x16x32_bf16 v[30:33], v[166:169], v[210:213], v[30:33]
	v_mfma_f32_16x16x32_bf16 v[30:33], v[156:159], v[206:209], v[30:33]
	v_mfma_f32_16x16x32_bf16 v[18:21], v[170:173], v[206:209], v[18:21]
	v_mfma_f32_16x16x32_bf16 v[18:21], v[174:177], v[210:213], v[18:21]
	v_mfma_f32_16x16x32_bf16 v[10:13], v[182:185], v[210:213], v[10:13]
	v_mfma_f32_16x16x32_bf16 v[10:13], v[178:181], v[206:209], v[10:13]
	v_mfma_f32_16x16x32_bf16 v[2:5], v[178:181], v[214:217], v[2:5]
	v_mfma_f32_16x16x32_bf16 v[2:5], v[182:185], v[218:221], v[2:5]
	v_mfma_f32_16x16x32_bf16 v[6:9], v[174:177], v[218:221], v[6:9]
	v_mfma_f32_16x16x32_bf16 v[6:9], v[170:173], v[214:217], v[6:9]
	v_mfma_f32_16x16x32_bf16 v[14:17], v[156:159], v[214:217], v[14:17]
	v_mfma_f32_16x16x32_bf16 v[14:17], v[166:169], v[218:221], v[14:17]
	v_mfma_f32_16x16x32_bf16 v[22:25], v[152:155], v[218:221], v[22:25]
	v_mfma_f32_16x16x32_bf16 v[22:25], v[148:151], v[214:217], v[22:25]
	s_setprio 0
	s_barrier
	s_movk_i32 s44, 0x100
	s_andn2_b64 vcc, exec, s[60:61]
	s_mov_b64 s[62:63], -1
	s_mov_b64 s[60:61], 0
	s_cbranch_vccz .LBB0_722
	s_and_b64 vcc, exec, s[12:13]
	s_cbranch_vccz .LBB0_725
	s_barrier

.LBB0_1226:
	v_add_u32_e32 v3, s71, v165
	ds_read_b128 v[150:153], v3
	ds_read_b128 v[154:157], v3 offset:1024
	ds_read_b128 v[158:161], v3 offset:2048
	ds_read_b128 v[170:173], v3 offset:3072
	v_add_u32_e32 v3, s72, v165
	ds_read_b128 v[174:177], v3
	ds_read_b128 v[178:181], v3 offset:1024
	ds_read_b128 v[182:185], v3 offset:2048
	ds_read_b128 v[186:189], v3 offset:3072
	s_add_u32 s36, s52, 0xfff80080
	s_addc_u32 s37, s53, -1
	s_cmp_eq_u32 s78, 28
	s_cselect_b32 s59, s21, s37
	s_cselect_b32 s58, s44, s36
	s_cselect_b32 s57, s19, s77
	s_cselect_b32 s56, s55, s76
	v_lshl_add_u64 v[4:5], s[52:53], 0, v[142:143]
	s_add_i32 m0, s63, 0xc000
	ds_read_b128 v[190:193], v169
	ds_read_b128 v[194:197], v169 offset:1024
	ds_read_b128 v[202:205], v169 offset:2048
	ds_read_b128 v[206:209], v169 offset:3072
	ds_read_b128 v[210:213], v169 offset:4096
	ds_read_b128 v[214:217], v169 offset:5120
	ds_read_b128 v[218:221], v169 offset:6144
	ds_read_b128 v[222:225], v169 offset:7168
	global_load_lds_dwordx4 v[4:5], off
	v_lshl_add_u64 v[4:5], s[52:53], 0, v[144:145]
	s_add_i32 m0, s63, 0xe000
	s_nop 0
	global_load_lds_dwordx4 v[4:5], off
	s_waitcnt vmcnt(8)
	s_waitcnt lgkmcnt(0)
	s_barrier
	s_setprio 1
	s_waitcnt lgkmcnt(0)
	v_mfma_f32_16x16x32_bf16 v[130:133], v[150:153], v[190:193], v[130:133]
	v_mfma_f32_16x16x32_bf16 v[130:133], v[154:157], v[194:197], v[130:133]
	v_mfma_f32_16x16x32_bf16 v[126:129], v[170:173], v[194:197], v[126:129]
	v_mfma_f32_16x16x32_bf16 v[126:129], v[158:161], v[190:193], v[126:129]
	v_mfma_f32_16x16x32_bf16 v[98:101], v[174:177], v[190:193], v[98:101]
	v_mfma_f32_16x16x32_bf16 v[98:101], v[178:181], v[194:197], v[98:101]
	v_mfma_f32_16x16x32_bf16 v[94:97], v[186:189], v[194:197], v[94:97]
	v_mfma_f32_16x16x32_bf16 v[94:97], v[182:185], v[190:193], v[94:97]
	v_mfma_f32_16x16x32_bf16 v[86:89], v[182:185], v[202:205], v[86:89]
	v_mfma_f32_16x16x32_bf16 v[86:89], v[186:189], v[206:209], v[86:89]
	v_mfma_f32_16x16x32_bf16 v[90:93], v[178:181], v[206:209], v[90:93]
	v_mfma_f32_16x16x32_bf16 v[90:93], v[174:177], v[202:205], v[90:93]
	v_mfma_f32_16x16x32_bf16 v[118:121], v[158:161], v[202:205], v[118:121]
	v_mfma_f32_16x16x32_bf16 v[118:121], v[170:173], v[206:209], v[118:121]
	v_mfma_f32_16x16x32_bf16 v[122:125], v[154:157], v[206:209], v[122:125]
	v_mfma_f32_16x16x32_bf16 v[122:125], v[150:153], v[202:205], v[122:125]
	v_mfma_f32_16x16x32_bf16 v[114:117], v[150:153], v[210:213], v[114:117]
	v_mfma_f32_16x16x32_bf16 v[114:117], v[154:157], v[214:217], v[114:117]
	v_mfma_f32_16x16x32_bf16 v[110:113], v[170:173], v[214:217], v[110:113]
	v_mfma_f32_16x16x32_bf16 v[110:113], v[158:161], v[210:213], v[110:113]
	v_mfma_f32_16x16x32_bf16 v[82:85], v[174:177], v[210:213], v[82:85]
	v_mfma_f32_16x16x32_bf16 v[82:85], v[178:181], v[214:217], v[82:85]
	v_mfma_f32_16x16x32_bf16 v[78:81], v[186:189], v[214:217], v[78:81]
	v_mfma_f32_16x16x32_bf16 v[78:81], v[182:185], v[210:213], v[78:81]
	v_mfma_f32_16x16x32_bf16 v[70:73], v[182:185], v[218:221], v[70:73]
	v_mfma_f32_16x16x32_bf16 v[70:73], v[186:189], v[222:225], v[70:73]
	v_mfma_f32_16x16x32_bf16 v[74:77], v[178:181], v[222:225], v[74:77]
	v_mfma_f32_16x16x32_bf16 v[74:77], v[174:177], v[218:221], v[74:77]
	v_mfma_f32_16x16x32_bf16 v[102:105], v[158:161], v[218:221], v[102:105]
	v_mfma_f32_16x16x32_bf16 v[102:105], v[170:173], v[222:225], v[102:105]
	v_mfma_f32_16x16x32_bf16 v[106:109], v[154:157], v[222:225], v[106:109]
	v_mfma_f32_16x16x32_bf16 v[106:109], v[150:153], v[218:221], v[106:109]
	s_setprio 0
	s_barrier
	s_add_i32 s36, s71, s43
	v_lshl_add_u64 v[166:167], s[56:57], 0, v[138:139]
	s_mov_b32 m0, s36
	ds_read_b128 v[190:193], v169 offset:16384
	ds_read_b128 v[194:197], v169 offset:17408
	ds_read_b128 v[202:205], v169 offset:18432
	ds_read_b128 v[206:209], v169 offset:19456
	ds_read_b128 v[210:213], v169 offset:20480
	ds_read_b128 v[214:217], v169 offset:21504
	ds_read_b128 v[218:221], v169 offset:22528
	ds_read_b128 v[222:225], v169 offset:23552
	global_load_lds_dwordx4 v[166:167], off
	s_add_i32 m0, s36, 0x2000
	s_add_u32 s80, s56, 0x80000
	v_lshl_add_u64 v[198:199], s[56:57], 0, v[134:135]
	s_addc_u32 s81, s57, 0
	s_add_i32 s36, s72, s43
	global_load_lds_dwordx4 v[198:199], off
	v_lshl_add_u64 v[4:5], s[80:81], 0, v[138:139]
	s_mov_b32 m0, s36
	v_lshl_add_u64 v[226:227], s[58:59], 0, v[140:141]
	global_load_lds_dwordx4 v[4:5], off
	v_lshl_add_u64 v[4:5], s[80:81], 0, v[134:135]
	s_add_i32 m0, s36, 0x2000
	v_lshl_add_u64 v[228:229], s[58:59], 0, v[136:137]
	global_load_lds_dwordx4 v[4:5], off
	s_mov_b32 m0, s63
	s_nop 0
	global_load_lds_dwordx4 v[226:227], off
	s_mov_b32 m0, s64
	s_nop 0
	global_load_lds_dwordx4 v[228:229], off
	s_waitcnt vmcnt(8)
	s_waitcnt lgkmcnt(0)
	s_barrier
	s_setprio 1
	s_waitcnt lgkmcnt(0)
	v_mfma_f32_16x16x32_bf16 v[66:69], v[150:153], v[190:193], v[66:69]
	v_mfma_f32_16x16x32_bf16 v[62:65], v[158:161], v[190:193], v[62:65]
	v_mfma_f32_16x16x32_bf16 v[58:61], v[150:153], v[202:205], v[58:61]
	v_mfma_f32_16x16x32_bf16 v[54:57], v[158:161], v[202:205], v[54:57]
	v_mfma_f32_16x16x32_bf16 v[50:53], v[150:153], v[210:213], v[50:53]
	v_mfma_f32_16x16x32_bf16 v[46:49], v[158:161], v[210:213], v[46:49]
	v_mfma_f32_16x16x32_bf16 v[42:45], v[150:153], v[218:221], v[42:45]
	v_mfma_f32_16x16x32_bf16 v[38:41], v[158:161], v[218:221], v[38:41]
	v_mfma_f32_16x16x32_bf16 v[66:69], v[154:157], v[194:197], v[66:69]
	v_mfma_f32_16x16x32_bf16 v[62:65], v[170:173], v[194:197], v[62:65]
	v_mfma_f32_16x16x32_bf16 v[58:61], v[154:157], v[206:209], v[58:61]
	v_mfma_f32_16x16x32_bf16 v[54:57], v[170:173], v[206:209], v[54:57]
	v_mfma_f32_16x16x32_bf16 v[50:53], v[154:157], v[214:217], v[50:53]
	v_mfma_f32_16x16x32_bf16 v[46:49], v[170:173], v[214:217], v[46:49]
	v_mfma_f32_16x16x32_bf16 v[42:45], v[154:157], v[222:225], v[42:45]
	v_mfma_f32_16x16x32_bf16 v[38:41], v[170:173], v[222:225], v[38:41]
	s_setprio 0
	s_setprio 1
	v_mfma_f32_16x16x32_bf16 v[34:37], v[174:177], v[190:193], v[34:37]
	v_mfma_f32_16x16x32_bf16 v[30:33], v[182:185], v[190:193], v[30:33]
	v_mfma_f32_16x16x32_bf16 v[26:29], v[174:177], v[202:205], v[26:29]
	v_mfma_f32_16x16x32_bf16 v[22:25], v[182:185], v[202:205], v[22:25]
	v_mfma_f32_16x16x32_bf16 v[18:21], v[174:177], v[210:213], v[18:21]
	v_mfma_f32_16x16x32_bf16 v[14:17], v[182:185], v[210:213], v[14:17]
	v_mfma_f32_16x16x32_bf16 v[10:13], v[174:177], v[218:221], v[10:13]
	v_mfma_f32_16x16x32_bf16 v[4:7], v[182:185], v[218:221], v[6:9]
	v_mfma_f32_16x16x32_bf16 v[34:37], v[178:181], v[194:197], v[34:37]
	v_mfma_f32_16x16x32_bf16 v[30:33], v[186:189], v[194:197], v[30:33]
	v_mfma_f32_16x16x32_bf16 v[26:29], v[178:181], v[206:209], v[26:29]
	v_mfma_f32_16x16x32_bf16 v[22:25], v[186:189], v[206:209], v[22:25]
	v_mfma_f32_16x16x32_bf16 v[18:21], v[178:181], v[214:217], v[18:21]
	v_mfma_f32_16x16x32_bf16 v[14:17], v[186:189], v[214:217], v[14:17]
	v_mfma_f32_16x16x32_bf16 v[10:13], v[178:181], v[222:225], v[10:13]
	v_mfma_f32_16x16x32_bf16 v[4:7], v[186:189], v[222:225], v[4:7]
	s_setprio 0
	s_barrier
	s_add_i32 s36, 0, 0x18000
	v_add_u32_e32 v3, s36, v165
	s_add_i32 s37, 0, 0x1c000
	ds_read_b128 v[150:153], v3
	ds_read_b128 v[154:157], v3 offset:1024
	ds_read_b128 v[158:161], v3 offset:2048
	ds_read_b128 v[170:173], v3 offset:3072
	v_add_u32_e32 v3, s37, v165
	ds_read_b128 v[174:177], v3
	ds_read_b128 v[178:181], v3 offset:1024
	ds_read_b128 v[182:185], v3 offset:2048
	ds_read_b128 v[186:189], v3 offset:3072
	s_add_u32 s58, s58, 0x80000
	s_addc_u32 s59, s59, 0
	s_mov_b32 m0, s65
	v_lshl_add_u64 v[8:9], s[58:59], 0, v[140:141]
	ds_read_b128 v[190:193], v169 offset:32768
	ds_read_b128 v[194:197], v169 offset:33792
	ds_read_b128 v[202:205], v169 offset:34816
	ds_read_b128 v[206:209], v169 offset:35840
	ds_read_b128 v[210:213], v169 offset:36864
	ds_read_b128 v[214:217], v169 offset:37888
	ds_read_b128 v[218:221], v169 offset:38912
	ds_read_b128 v[222:225], v169 offset:39936
	global_load_lds_dwordx4 v[8:9], off
	v_lshl_add_u64 v[8:9], s[58:59], 0, v[136:137]
	s_mov_b32 m0, s66
	s_nop 0
	global_load_lds_dwordx4 v[8:9], off
	s_waitcnt vmcnt(8)
	s_waitcnt lgkmcnt(0)
	s_barrier
	s_setprio 1
	s_waitcnt lgkmcnt(0)
	v_mfma_f32_16x16x32_bf16 v[130:133], v[150:153], v[190:193], v[130:133]
	v_mfma_f32_16x16x32_bf16 v[130:133], v[154:157], v[194:197], v[130:133]
	v_mfma_f32_16x16x32_bf16 v[126:129], v[170:173], v[194:197], v[126:129]
	v_mfma_f32_16x16x32_bf16 v[126:129], v[158:161], v[190:193], v[126:129]
	v_mfma_f32_16x16x32_bf16 v[98:101], v[174:177], v[190:193], v[98:101]
	v_mfma_f32_16x16x32_bf16 v[98:101], v[178:181], v[194:197], v[98:101]
	v_mfma_f32_16x16x32_bf16 v[94:97], v[186:189], v[194:197], v[94:97]
	v_mfma_f32_16x16x32_bf16 v[94:97], v[182:185], v[190:193], v[94:97]
	v_mfma_f32_16x16x32_bf16 v[86:89], v[182:185], v[202:205], v[86:89]
	v_mfma_f32_16x16x32_bf16 v[86:89], v[186:189], v[206:209], v[86:89]
	v_mfma_f32_16x16x32_bf16 v[90:93], v[178:181], v[206:209], v[90:93]
	v_mfma_f32_16x16x32_bf16 v[90:93], v[174:177], v[202:205], v[90:93]
	v_mfma_f32_16x16x32_bf16 v[118:121], v[158:161], v[202:205], v[118:121]
	v_mfma_f32_16x16x32_bf16 v[118:121], v[170:173], v[206:209], v[118:121]
	v_mfma_f32_16x16x32_bf16 v[122:125], v[154:157], v[206:209], v[122:125]
	v_mfma_f32_16x16x32_bf16 v[122:125], v[150:153], v[202:205], v[122:125]
	v_mfma_f32_16x16x32_bf16 v[114:117], v[150:153], v[210:213], v[114:117]
	v_mfma_f32_16x16x32_bf16 v[114:117], v[154:157], v[214:217], v[114:117]
	v_mfma_f32_16x16x32_bf16 v[110:113], v[170:173], v[214:217], v[110:113]
	v_mfma_f32_16x16x32_bf16 v[110:113], v[158:161], v[210:213], v[110:113]
	v_mfma_f32_16x16x32_bf16 v[82:85], v[174:177], v[210:213], v[82:85]
	v_mfma_f32_16x16x32_bf16 v[82:85], v[178:181], v[214:217], v[82:85]
	v_mfma_f32_16x16x32_bf16 v[78:81], v[186:189], v[214:217], v[78:81]
	v_mfma_f32_16x16x32_bf16 v[78:81], v[182:185], v[210:213], v[78:81]
	v_mfma_f32_16x16x32_bf16 v[70:73], v[182:185], v[218:221], v[70:73]
	v_mfma_f32_16x16x32_bf16 v[70:73], v[186:189], v[222:225], v[70:73]
	v_mfma_f32_16x16x32_bf16 v[74:77], v[178:181], v[222:225], v[74:77]
	v_mfma_f32_16x16x32_bf16 v[74:77], v[174:177], v[218:221], v[74:77]
	v_mfma_f32_16x16x32_bf16 v[102:105], v[158:161], v[218:221], v[102:105]
	v_mfma_f32_16x16x32_bf16 v[102:105], v[170:173], v[222:225], v[102:105]
	v_mfma_f32_16x16x32_bf16 v[106:109], v[154:157], v[222:225], v[106:109]
	v_mfma_f32_16x16x32_bf16 v[106:109], v[150:153], v[218:221], v[106:109]
	s_setprio 0
	s_barrier
	s_add_i32 s36, s36, s43
	v_lshl_add_u64 v[8:9], v[166:167], 0, s[10:11]
	s_mov_b32 m0, s36
	ds_read_b128 v[190:193], v169 offset:49152
	ds_read_b128 v[194:197], v169 offset:50176
	ds_read_b128 v[202:205], v169 offset:51200
	ds_read_b128 v[206:209], v169 offset:52224
	ds_read_b128 v[210:213], v169 offset:53248
	ds_read_b128 v[214:217], v169 offset:54272
	ds_read_b128 v[218:221], v169 offset:55296
	ds_read_b128 v[222:225], v169 offset:56320
	global_load_lds_dwordx4 v[8:9], off
	s_add_i32 m0, s36, 0x2000
	s_add_u32 s56, s56, 0x80080
	v_lshl_add_u64 v[8:9], v[198:199], 0, s[10:11]
	s_addc_u32 s57, s57, 0
	s_add_i32 s36, s37, s43
	global_load_lds_dwordx4 v[8:9], off
	v_lshl_add_u64 v[8:9], s[56:57], 0, v[138:139]
	s_mov_b32 m0, s36
	s_nop 0
	global_load_lds_dwordx4 v[8:9], off
	v_lshl_add_u64 v[8:9], s[56:57], 0, v[134:135]
	s_add_i32 m0, s36, 0x2000
	s_nop 0
	global_load_lds_dwordx4 v[8:9], off
	v_lshl_add_u64 v[8:9], v[226:227], 0, s[10:11]
	s_mov_b32 m0, s69
	s_nop 0
	global_load_lds_dwordx4 v[8:9], off
	v_lshl_add_u64 v[8:9], v[228:229], 0, s[10:11]
	s_mov_b32 m0, s70
	s_nop 0
	global_load_lds_dwordx4 v[8:9], off
	s_waitcnt vmcnt(8)
	s_waitcnt lgkmcnt(0)
	s_barrier
	s_setprio 1
	s_waitcnt lgkmcnt(0)
	v_mfma_f32_16x16x32_bf16 v[66:69], v[150:153], v[190:193], v[66:69]
	v_mfma_f32_16x16x32_bf16 v[62:65], v[158:161], v[190:193], v[62:65]
	v_mfma_f32_16x16x32_bf16 v[58:61], v[150:153], v[202:205], v[58:61]
	v_mfma_f32_16x16x32_bf16 v[54:57], v[158:161], v[202:205], v[54:57]
	v_mfma_f32_16x16x32_bf16 v[50:53], v[150:153], v[210:213], v[50:53]
	v_mfma_f32_16x16x32_bf16 v[46:49], v[158:161], v[210:213], v[46:49]
	v_mfma_f32_16x16x32_bf16 v[42:45], v[150:153], v[218:221], v[42:45]
	v_mfma_f32_16x16x32_bf16 v[38:41], v[158:161], v[218:221], v[38:41]
	v_mfma_f32_16x16x32_bf16 v[66:69], v[154:157], v[194:197], v[66:69]
	v_mfma_f32_16x16x32_bf16 v[62:65], v[170:173], v[194:197], v[62:65]
	v_mfma_f32_16x16x32_bf16 v[58:61], v[154:157], v[206:209], v[58:61]
	v_mfma_f32_16x16x32_bf16 v[54:57], v[170:173], v[206:209], v[54:57]
	v_mfma_f32_16x16x32_bf16 v[50:53], v[154:157], v[214:217], v[50:53]
	v_mfma_f32_16x16x32_bf16 v[46:49], v[170:173], v[214:217], v[46:49]
	v_mfma_f32_16x16x32_bf16 v[42:45], v[154:157], v[222:225], v[42:45]
	v_mfma_f32_16x16x32_bf16 v[38:41], v[170:173], v[222:225], v[38:41]
	s_setprio 0
	s_setprio 1
	v_mfma_f32_16x16x32_bf16 v[34:37], v[174:177], v[190:193], v[34:37]
	v_mfma_f32_16x16x32_bf16 v[30:33], v[182:185], v[190:193], v[30:33]
	v_mfma_f32_16x16x32_bf16 v[26:29], v[174:177], v[202:205], v[26:29]
	v_mfma_f32_16x16x32_bf16 v[22:25], v[182:185], v[202:205], v[22:25]
	v_mfma_f32_16x16x32_bf16 v[18:21], v[174:177], v[210:213], v[18:21]
	v_mfma_f32_16x16x32_bf16 v[14:17], v[182:185], v[210:213], v[14:17]
	v_mfma_f32_16x16x32_bf16 v[8:11], v[174:177], v[218:221], v[10:13]
	v_mfma_f32_16x16x32_bf16 v[4:7], v[182:185], v[218:221], v[4:7]
	v_mfma_f32_16x16x32_bf16 v[34:37], v[178:181], v[194:197], v[34:37]
	v_mfma_f32_16x16x32_bf16 v[30:33], v[186:189], v[194:197], v[30:33]
	v_mfma_f32_16x16x32_bf16 v[26:29], v[178:181], v[206:209], v[26:29]
	v_mfma_f32_16x16x32_bf16 v[22:25], v[186:189], v[206:209], v[22:25]
	v_mfma_f32_16x16x32_bf16 v[18:21], v[178:181], v[214:217], v[18:21]
	v_mfma_f32_16x16x32_bf16 v[14:17], v[186:189], v[214:217], v[14:17]
	v_mfma_f32_16x16x32_bf16 v[10:13], v[178:181], v[222:225], v[8:11]
	v_mfma_f32_16x16x32_bf16 v[6:9], v[186:189], v[222:225], v[4:7]
	s_setprio 0
	s_barrier
	s_add_i32 s78, s78, 2
	s_add_u32 s52, s52, 0x100
	s_addc_u32 s53, s53, 0
	s_add_u32 s76, s76, 0x100
	s_addc_u32 s77, s77, 0
	s_cmp_gt_u32 s78, 29
	s_cbranch_scc0 .LBB0_1226
	s_and_b64 vcc, exec, s[12:13]
	s_cbranch_vccz .LBB0_1229
	s_barrier

.LBB0_1397:
	ds_read_b128 v[146:149], v154
	ds_read_b128 v[158:161], v154 offset:1024
	ds_read_b128 v[166:169], v154 offset:2048
	ds_read_b128 v[170:173], v154 offset:3072
	ds_read_b128 v[174:177], v155
	ds_read_b128 v[178:181], v155 offset:1024
	ds_read_b128 v[182:185], v155 offset:2048
	ds_read_b128 v[186:189], v155 offset:3072
	s_add_i32 s93, s44, 2
	s_add_u32 s36, s62, 0xfff00080
	s_addc_u32 s37, s63, -1
	s_cmp_eq_u32 s59, s44
	s_cselect_b32 s67, s38, s37
	s_cselect_b32 s66, s39, s36
	s_cselect_b32 s65, s51, s92
	s_cselect_b32 s64, s53, s61
	v_lshl_add_u64 v[150:151], s[62:63], 0, v[140:141]
	s_add_i32 m0, s72, 0xc000
	ds_read_b128 v[190:193], v156
	ds_read_b128 v[194:197], v156 offset:1024
	ds_read_b128 v[202:205], v156 offset:2048
	ds_read_b128 v[206:209], v156 offset:3072
	ds_read_b128 v[210:213], v156 offset:4096
	ds_read_b128 v[214:217], v156 offset:5120
	ds_read_b128 v[218:221], v156 offset:6144
	ds_read_b128 v[222:225], v156 offset:7168
	global_load_lds_dwordx4 v[150:151], off
	v_lshl_add_u64 v[150:151], s[62:63], 0, v[142:143]
	s_add_i32 m0, s72, 0xe000
	s_nop 0
	global_load_lds_dwordx4 v[150:151], off
	s_waitcnt vmcnt(8)
	s_waitcnt lgkmcnt(0)
	s_barrier
	s_setprio 1
	s_waitcnt lgkmcnt(0)
	v_mfma_f32_16x16x32_bf16 v[126:129], v[146:149], v[190:193], v[126:129]
	v_mfma_f32_16x16x32_bf16 v[126:129], v[158:161], v[194:197], v[126:129]
	v_mfma_f32_16x16x32_bf16 v[122:125], v[170:173], v[194:197], v[122:125]
	v_mfma_f32_16x16x32_bf16 v[122:125], v[166:169], v[190:193], v[122:125]
	v_mfma_f32_16x16x32_bf16 v[118:121], v[174:177], v[190:193], v[118:121]
	v_mfma_f32_16x16x32_bf16 v[118:121], v[178:181], v[194:197], v[118:121]
	v_mfma_f32_16x16x32_bf16 v[114:117], v[186:189], v[194:197], v[114:117]
	v_mfma_f32_16x16x32_bf16 v[114:117], v[182:185], v[190:193], v[114:117]
	v_mfma_f32_16x16x32_bf16 v[98:101], v[182:185], v[202:205], v[98:101]
	v_mfma_f32_16x16x32_bf16 v[98:101], v[186:189], v[206:209], v[98:101]
	v_mfma_f32_16x16x32_bf16 v[102:105], v[178:181], v[206:209], v[102:105]
	v_mfma_f32_16x16x32_bf16 v[102:105], v[174:177], v[202:205], v[102:105]
	v_mfma_f32_16x16x32_bf16 v[106:109], v[166:169], v[202:205], v[106:109]
	v_mfma_f32_16x16x32_bf16 v[106:109], v[170:173], v[206:209], v[106:109]
	v_mfma_f32_16x16x32_bf16 v[110:113], v[158:161], v[206:209], v[110:113]
	v_mfma_f32_16x16x32_bf16 v[110:113], v[146:149], v[202:205], v[110:113]
	v_mfma_f32_16x16x32_bf16 v[94:97], v[146:149], v[210:213], v[94:97]
	v_mfma_f32_16x16x32_bf16 v[94:97], v[158:161], v[214:217], v[94:97]
	v_mfma_f32_16x16x32_bf16 v[90:93], v[170:173], v[214:217], v[90:93]
	v_mfma_f32_16x16x32_bf16 v[90:93], v[166:169], v[210:213], v[90:93]
	v_mfma_f32_16x16x32_bf16 v[86:89], v[174:177], v[210:213], v[86:89]
	v_mfma_f32_16x16x32_bf16 v[86:89], v[178:181], v[214:217], v[86:89]
	v_mfma_f32_16x16x32_bf16 v[82:85], v[186:189], v[214:217], v[82:85]
	v_mfma_f32_16x16x32_bf16 v[82:85], v[182:185], v[210:213], v[82:85]
	v_mfma_f32_16x16x32_bf16 v[66:69], v[182:185], v[218:221], v[66:69]
	v_mfma_f32_16x16x32_bf16 v[66:69], v[186:189], v[222:225], v[66:69]
	v_mfma_f32_16x16x32_bf16 v[70:73], v[178:181], v[222:225], v[70:73]
	v_mfma_f32_16x16x32_bf16 v[70:73], v[174:177], v[218:221], v[70:73]
	v_mfma_f32_16x16x32_bf16 v[74:77], v[166:169], v[218:221], v[74:77]
	v_mfma_f32_16x16x32_bf16 v[74:77], v[170:173], v[222:225], v[74:77]
	v_mfma_f32_16x16x32_bf16 v[78:81], v[158:161], v[222:225], v[78:81]
	v_mfma_f32_16x16x32_bf16 v[78:81], v[146:149], v[218:221], v[78:81]
	s_setprio 0
	s_barrier
	s_add_i32 s36, s82, s69
	v_lshl_add_u64 v[150:151], s[64:65], 0, v[132:133]
	s_mov_b32 m0, s36
	ds_read_b128 v[190:193], v156 offset:16384
	ds_read_b128 v[194:197], v156 offset:17408
	ds_read_b128 v[202:205], v156 offset:18432
	ds_read_b128 v[206:209], v156 offset:19456
	ds_read_b128 v[210:213], v156 offset:20480
	ds_read_b128 v[214:217], v156 offset:21504
	ds_read_b128 v[218:221], v156 offset:22528
	ds_read_b128 v[222:225], v156 offset:23552
	global_load_lds_dwordx4 v[150:151], off
	s_add_i32 m0, s36, 0x2000
	s_add_u32 s94, s64, 0x100000
	v_lshl_add_u64 v[198:199], s[64:65], 0, v[136:137]
	s_addc_u32 s95, s65, 0
	s_add_i32 s36, s83, s69
	global_load_lds_dwordx4 v[198:199], off
	v_lshl_add_u64 v[226:227], s[94:95], 0, v[132:133]
	s_mov_b32 m0, s36
	v_lshl_add_u64 v[228:229], s[66:67], 0, v[134:135]
	global_load_lds_dwordx4 v[226:227], off
	v_lshl_add_u64 v[226:227], s[94:95], 0, v[136:137]
	s_add_i32 m0, s36, 0x2000
	s_nop 0
	global_load_lds_dwordx4 v[226:227], off
	v_lshl_add_u64 v[226:227], s[66:67], 0, v[130:131]
	s_mov_b32 m0, s72
	s_nop 0
	global_load_lds_dwordx4 v[226:227], off
	s_mov_b32 m0, s73
	s_nop 0
	global_load_lds_dwordx4 v[228:229], off
	s_waitcnt vmcnt(8)
	s_waitcnt lgkmcnt(0)
	s_barrier
	s_setprio 1
	s_waitcnt lgkmcnt(0)
	v_mfma_f32_16x16x32_bf16 v[62:65], v[146:149], v[190:193], v[62:65]
	v_mfma_f32_16x16x32_bf16 v[62:65], v[158:161], v[194:197], v[62:65]
	v_mfma_f32_16x16x32_bf16 v[58:61], v[170:173], v[194:197], v[58:61]
	v_mfma_f32_16x16x32_bf16 v[58:61], v[166:169], v[190:193], v[58:61]
	v_mfma_f32_16x16x32_bf16 v[54:57], v[174:177], v[190:193], v[54:57]
	v_mfma_f32_16x16x32_bf16 v[54:57], v[178:181], v[194:197], v[54:57]
	v_mfma_f32_16x16x32_bf16 v[50:53], v[186:189], v[194:197], v[50:53]
	v_mfma_f32_16x16x32_bf16 v[50:53], v[182:185], v[190:193], v[50:53]
	v_mfma_f32_16x16x32_bf16 v[34:37], v[182:185], v[202:205], v[34:37]
	v_mfma_f32_16x16x32_bf16 v[34:37], v[186:189], v[206:209], v[34:37]
	v_mfma_f32_16x16x32_bf16 v[38:41], v[178:181], v[206:209], v[38:41]
	v_mfma_f32_16x16x32_bf16 v[38:41], v[174:177], v[202:205], v[38:41]
	v_mfma_f32_16x16x32_bf16 v[42:45], v[166:169], v[202:205], v[42:45]
	v_mfma_f32_16x16x32_bf16 v[42:45], v[170:173], v[206:209], v[42:45]
	v_mfma_f32_16x16x32_bf16 v[46:49], v[158:161], v[206:209], v[46:49]
	v_mfma_f32_16x16x32_bf16 v[46:49], v[146:149], v[202:205], v[46:49]
	v_mfma_f32_16x16x32_bf16 v[30:33], v[146:149], v[210:213], v[30:33]
	v_mfma_f32_16x16x32_bf16 v[30:33], v[158:161], v[214:217], v[30:33]
	v_mfma_f32_16x16x32_bf16 v[26:29], v[170:173], v[214:217], v[26:29]
	v_mfma_f32_16x16x32_bf16 v[26:29], v[166:169], v[210:213], v[26:29]
	v_mfma_f32_16x16x32_bf16 v[22:25], v[174:177], v[210:213], v[22:25]
	v_mfma_f32_16x16x32_bf16 v[22:25], v[178:181], v[214:217], v[22:25]
	v_mfma_f32_16x16x32_bf16 v[18:21], v[186:189], v[214:217], v[18:21]
	v_mfma_f32_16x16x32_bf16 v[18:21], v[182:185], v[210:213], v[18:21]
	v_mfma_f32_16x16x32_bf16 v[2:5], v[182:185], v[218:221], v[2:5]
	v_mfma_f32_16x16x32_bf16 v[2:5], v[186:189], v[222:225], v[2:5]
	v_mfma_f32_16x16x32_bf16 v[6:9], v[178:181], v[222:225], v[6:9]
	v_mfma_f32_16x16x32_bf16 v[6:9], v[174:177], v[218:221], v[6:9]
	v_mfma_f32_16x16x32_bf16 v[10:13], v[166:169], v[218:221], v[10:13]
	v_mfma_f32_16x16x32_bf16 v[10:13], v[170:173], v[222:225], v[10:13]
	v_mfma_f32_16x16x32_bf16 v[14:17], v[158:161], v[222:225], v[14:17]
	v_mfma_f32_16x16x32_bf16 v[14:17], v[146:149], v[218:221], v[14:17]
	s_setprio 0
	s_barrier
	s_add_i32 s36, 0, 0x18000
	v_add_u32_e32 v138, s36, v152
	s_add_i32 s37, 0, 0x1c000
	ds_read_b128 v[146:149], v138
	ds_read_b128 v[158:161], v138 offset:1024
	ds_read_b128 v[166:169], v138 offset:2048
	ds_read_b128 v[170:173], v138 offset:3072
	v_add_u32_e32 v138, s37, v152
	ds_read_b128 v[174:177], v138
	ds_read_b128 v[178:181], v138 offset:1024
	ds_read_b128 v[182:185], v138 offset:2048
	ds_read_b128 v[186:189], v138 offset:3072
	s_add_u32 s66, s66, 0x100000
	s_addc_u32 s67, s67, 0
	s_mov_b32 m0, s74
	v_lshl_add_u64 v[230:231], s[66:67], 0, v[130:131]
	ds_read_b128 v[190:193], v156 offset:32768
	ds_read_b128 v[194:197], v156 offset:33792
	ds_read_b128 v[202:205], v156 offset:34816
	ds_read_b128 v[206:209], v156 offset:35840
	ds_read_b128 v[210:213], v156 offset:36864
	ds_read_b128 v[214:217], v156 offset:37888
	ds_read_b128 v[218:221], v156 offset:38912
	ds_read_b128 v[222:225], v156 offset:39936
	global_load_lds_dwordx4 v[230:231], off
	v_lshl_add_u64 v[230:231], s[66:67], 0, v[134:135]
	s_mov_b32 m0, s75
	s_nop 0
	global_load_lds_dwordx4 v[230:231], off
	s_waitcnt vmcnt(8)
	s_waitcnt lgkmcnt(0)
	s_barrier
	s_setprio 1
	s_waitcnt lgkmcnt(0)
	v_mfma_f32_16x16x32_bf16 v[126:129], v[146:149], v[190:193], v[126:129]
	v_mfma_f32_16x16x32_bf16 v[126:129], v[158:161], v[194:197], v[126:129]
	v_mfma_f32_16x16x32_bf16 v[122:125], v[170:173], v[194:197], v[122:125]
	v_mfma_f32_16x16x32_bf16 v[122:125], v[166:169], v[190:193], v[122:125]
	v_mfma_f32_16x16x32_bf16 v[118:121], v[174:177], v[190:193], v[118:121]
	v_mfma_f32_16x16x32_bf16 v[118:121], v[178:181], v[194:197], v[118:121]
	v_mfma_f32_16x16x32_bf16 v[114:117], v[186:189], v[194:197], v[114:117]
	v_mfma_f32_16x16x32_bf16 v[114:117], v[182:185], v[190:193], v[114:117]
	v_mfma_f32_16x16x32_bf16 v[98:101], v[182:185], v[202:205], v[98:101]
	v_mfma_f32_16x16x32_bf16 v[98:101], v[186:189], v[206:209], v[98:101]
	v_mfma_f32_16x16x32_bf16 v[102:105], v[178:181], v[206:209], v[102:105]
	v_mfma_f32_16x16x32_bf16 v[102:105], v[174:177], v[202:205], v[102:105]
	v_mfma_f32_16x16x32_bf16 v[106:109], v[166:169], v[202:205], v[106:109]
	v_mfma_f32_16x16x32_bf16 v[106:109], v[170:173], v[206:209], v[106:109]
	v_mfma_f32_16x16x32_bf16 v[110:113], v[158:161], v[206:209], v[110:113]
	v_mfma_f32_16x16x32_bf16 v[110:113], v[146:149], v[202:205], v[110:113]
	v_mfma_f32_16x16x32_bf16 v[94:97], v[146:149], v[210:213], v[94:97]
	v_mfma_f32_16x16x32_bf16 v[94:97], v[158:161], v[214:217], v[94:97]
	v_mfma_f32_16x16x32_bf16 v[90:93], v[170:173], v[214:217], v[90:93]
	v_mfma_f32_16x16x32_bf16 v[90:93], v[166:169], v[210:213], v[90:93]
	v_mfma_f32_16x16x32_bf16 v[86:89], v[174:177], v[210:213], v[86:89]
	v_mfma_f32_16x16x32_bf16 v[86:89], v[178:181], v[214:217], v[86:89]
	v_mfma_f32_16x16x32_bf16 v[82:85], v[186:189], v[214:217], v[82:85]
	v_mfma_f32_16x16x32_bf16 v[82:85], v[182:185], v[210:213], v[82:85]
	v_mfma_f32_16x16x32_bf16 v[66:69], v[182:185], v[218:221], v[66:69]
	v_mfma_f32_16x16x32_bf16 v[66:69], v[186:189], v[222:225], v[66:69]
	v_mfma_f32_16x16x32_bf16 v[70:73], v[178:181], v[222:225], v[70:73]
	v_mfma_f32_16x16x32_bf16 v[70:73], v[174:177], v[218:221], v[70:73]
	v_mfma_f32_16x16x32_bf16 v[74:77], v[166:169], v[218:221], v[74:77]
	v_mfma_f32_16x16x32_bf16 v[74:77], v[170:173], v[222:225], v[74:77]
	v_mfma_f32_16x16x32_bf16 v[78:81], v[158:161], v[222:225], v[78:81]
	v_mfma_f32_16x16x32_bf16 v[78:81], v[146:149], v[218:221], v[78:81]
	s_setprio 0
	s_barrier
	s_add_i32 s36, s36, s69
	v_lshl_add_u64 v[150:151], v[150:151], 0, s[16:17]
	s_mov_b32 m0, s36
	ds_read_b128 v[190:193], v156 offset:49152
	ds_read_b128 v[194:197], v156 offset:50176
	ds_read_b128 v[202:205], v156 offset:51200
	ds_read_b128 v[206:209], v156 offset:52224
	ds_read_b128 v[210:213], v156 offset:53248
	ds_read_b128 v[214:217], v156 offset:54272
	ds_read_b128 v[218:221], v156 offset:55296
	ds_read_b128 v[222:225], v156 offset:56320
	global_load_lds_dwordx4 v[150:151], off
	s_add_i32 m0, s36, 0x2000
	s_add_u32 s64, s64, 0x100080
	v_lshl_add_u64 v[150:151], v[198:199], 0, s[16:17]
	s_addc_u32 s65, s65, 0
	s_add_i32 s36, s37, s69
	global_load_lds_dwordx4 v[150:151], off
	v_lshl_add_u64 v[150:151], s[64:65], 0, v[132:133]
	s_mov_b32 m0, s36
	s_nop 0
	global_load_lds_dwordx4 v[150:151], off
	v_lshl_add_u64 v[150:151], s[64:65], 0, v[136:137]
	s_add_i32 m0, s36, 0x2000
	s_nop 0
	global_load_lds_dwordx4 v[150:151], off
	v_lshl_add_u64 v[150:151], v[226:227], 0, s[16:17]
	s_mov_b32 m0, s78
	s_nop 0
	global_load_lds_dwordx4 v[150:151], off
	v_lshl_add_u64 v[150:151], v[228:229], 0, s[16:17]
	s_mov_b32 m0, s79
	s_nop 0
	global_load_lds_dwordx4 v[150:151], off
	s_waitcnt vmcnt(8)
	s_waitcnt lgkmcnt(0)
	s_barrier
	s_setprio 1
	s_waitcnt lgkmcnt(0)
	v_mfma_f32_16x16x32_bf16 v[62:65], v[146:149], v[190:193], v[62:65]
	v_mfma_f32_16x16x32_bf16 v[62:65], v[158:161], v[194:197], v[62:65]
	v_mfma_f32_16x16x32_bf16 v[58:61], v[170:173], v[194:197], v[58:61]
	v_mfma_f32_16x16x32_bf16 v[58:61], v[166:169], v[190:193], v[58:61]
	v_mfma_f32_16x16x32_bf16 v[54:57], v[174:177], v[190:193], v[54:57]
	v_mfma_f32_16x16x32_bf16 v[54:57], v[178:181], v[194:197], v[54:57]
	v_mfma_f32_16x16x32_bf16 v[50:53], v[186:189], v[194:197], v[50:53]
	v_mfma_f32_16x16x32_bf16 v[50:53], v[182:185], v[190:193], v[50:53]
	v_mfma_f32_16x16x32_bf16 v[34:37], v[182:185], v[202:205], v[34:37]
	v_mfma_f32_16x16x32_bf16 v[34:37], v[186:189], v[206:209], v[34:37]
	v_mfma_f32_16x16x32_bf16 v[38:41], v[178:181], v[206:209], v[38:41]
	v_mfma_f32_16x16x32_bf16 v[38:41], v[174:177], v[202:205], v[38:41]
	v_mfma_f32_16x16x32_bf16 v[42:45], v[166:169], v[202:205], v[42:45]
	v_mfma_f32_16x16x32_bf16 v[42:45], v[170:173], v[206:209], v[42:45]
	v_mfma_f32_16x16x32_bf16 v[46:49], v[158:161], v[206:209], v[46:49]
	v_mfma_f32_16x16x32_bf16 v[46:49], v[146:149], v[202:205], v[46:49]
	v_mfma_f32_16x16x32_bf16 v[30:33], v[146:149], v[210:213], v[30:33]
	v_mfma_f32_16x16x32_bf16 v[30:33], v[158:161], v[214:217], v[30:33]
	v_mfma_f32_16x16x32_bf16 v[26:29], v[170:173], v[214:217], v[26:29]
	v_mfma_f32_16x16x32_bf16 v[26:29], v[166:169], v[210:213], v[26:29]
	v_mfma_f32_16x16x32_bf16 v[22:25], v[174:177], v[210:213], v[22:25]
	v_mfma_f32_16x16x32_bf16 v[22:25], v[178:181], v[214:217], v[22:25]
	v_mfma_f32_16x16x32_bf16 v[18:21], v[186:189], v[214:217], v[18:21]
	v_mfma_f32_16x16x32_bf16 v[18:21], v[182:185], v[210:213], v[18:21]
	v_mfma_f32_16x16x32_bf16 v[2:5], v[182:185], v[218:221], v[2:5]
	v_mfma_f32_16x16x32_bf16 v[2:5], v[186:189], v[222:225], v[2:5]
	v_mfma_f32_16x16x32_bf16 v[6:9], v[178:181], v[222:225], v[6:9]
	v_mfma_f32_16x16x32_bf16 v[6:9], v[174:177], v[218:221], v[6:9]
	v_mfma_f32_16x16x32_bf16 v[10:13], v[166:169], v[218:221], v[10:13]
	v_mfma_f32_16x16x32_bf16 v[10:13], v[170:173], v[222:225], v[10:13]
	v_mfma_f32_16x16x32_bf16 v[14:17], v[158:161], v[222:225], v[14:17]
	v_mfma_f32_16x16x32_bf16 v[14:17], v[146:149], v[218:221], v[14:17]
	s_setprio 0
	s_barrier
	s_add_u32 s62, s62, 0x100
	s_addc_u32 s63, s63, 0
	s_add_u32 s61, s61, 0x100
	s_addc_u32 s92, s92, 0
	s_cmp_ge_i32 s93, s11
	s_mov_b32 s44, s93
	s_cbranch_scc0 .LBB0_1397
	s_and_b64 vcc, exec, s[18:19]
	s_cbranch_vccz .LBB0_1400

.LBB0_1631:
	ds_read_b128 v[166:169], v158
	ds_read_b128 v[170:173], v158 offset:1024
	ds_read_b128 v[174:177], v158 offset:2048
	ds_read_b128 v[178:181], v158 offset:3072
	ds_read_b128 v[182:185], v159
	ds_read_b128 v[186:189], v159 offset:1024
	ds_read_b128 v[190:193], v159 offset:2048
	ds_read_b128 v[194:197], v159 offset:3072
	s_add_u32 s36, s54, 0xfff00080
	s_addc_u32 s37, s55, -1
	s_cmp_eq_u32 s78, 60
	s_cselect_b32 s59, s21, s37
	s_cselect_b32 s58, s74, s36
	s_cselect_b32 s57, s19, s77
	s_cselect_b32 s56, s75, s76
	v_lshl_add_u64 v[198:199], s[54:55], 0, v[140:141]
	s_add_i32 m0, s53, 0xc000
	ds_read_b128 v[202:205], v160
	ds_read_b128 v[206:209], v160 offset:1024
	ds_read_b128 v[210:213], v160 offset:2048
	ds_read_b128 v[214:217], v160 offset:3072
	ds_read_b128 v[218:221], v160 offset:4096
	ds_read_b128 v[222:225], v160 offset:5120
	ds_read_b128 v[226:229], v160 offset:6144
	ds_read_b128 v[230:233], v160 offset:7168
	global_load_lds_dwordx4 v[198:199], off
	v_lshl_add_u64 v[198:199], s[54:55], 0, v[142:143]
	s_add_i32 m0, s53, 0xe000
	s_nop 0
	global_load_lds_dwordx4 v[198:199], off
	s_waitcnt vmcnt(8)
	s_waitcnt lgkmcnt(0)
	s_barrier
	s_setprio 1
	s_waitcnt lgkmcnt(0)
	v_mfma_f32_16x16x32_bf16 v[126:129], v[166:169], v[202:205], v[126:129]
	v_mfma_f32_16x16x32_bf16 v[126:129], v[170:173], v[206:209], v[126:129]
	v_mfma_f32_16x16x32_bf16 v[122:125], v[178:181], v[206:209], v[122:125]
	v_mfma_f32_16x16x32_bf16 v[122:125], v[174:177], v[202:205], v[122:125]
	v_mfma_f32_16x16x32_bf16 v[114:117], v[182:185], v[202:205], v[114:117]
	v_mfma_f32_16x16x32_bf16 v[114:117], v[186:189], v[206:209], v[114:117]
	v_mfma_f32_16x16x32_bf16 v[106:109], v[194:197], v[206:209], v[106:109]
	v_mfma_f32_16x16x32_bf16 v[106:109], v[190:193], v[202:205], v[106:109]
	v_mfma_f32_16x16x32_bf16 v[90:93], v[190:193], v[210:213], v[90:93]
	v_mfma_f32_16x16x32_bf16 v[90:93], v[194:197], v[214:217], v[90:93]
	v_mfma_f32_16x16x32_bf16 v[98:101], v[186:189], v[214:217], v[98:101]
	v_mfma_f32_16x16x32_bf16 v[98:101], v[182:185], v[210:213], v[98:101]
	v_mfma_f32_16x16x32_bf16 v[110:113], v[174:177], v[210:213], v[110:113]
	v_mfma_f32_16x16x32_bf16 v[110:113], v[178:181], v[214:217], v[110:113]
	v_mfma_f32_16x16x32_bf16 v[118:121], v[170:173], v[214:217], v[118:121]
	v_mfma_f32_16x16x32_bf16 v[118:121], v[166:169], v[210:213], v[118:121]
	v_mfma_f32_16x16x32_bf16 v[102:105], v[166:169], v[218:221], v[102:105]
	v_mfma_f32_16x16x32_bf16 v[102:105], v[170:173], v[222:225], v[102:105]
	v_mfma_f32_16x16x32_bf16 v[94:97], v[178:181], v[222:225], v[94:97]
	v_mfma_f32_16x16x32_bf16 v[94:97], v[174:177], v[218:221], v[94:97]
	v_mfma_f32_16x16x32_bf16 v[82:85], v[182:185], v[218:221], v[82:85]
	v_mfma_f32_16x16x32_bf16 v[82:85], v[186:189], v[222:225], v[82:85]
	v_mfma_f32_16x16x32_bf16 v[74:77], v[194:197], v[222:225], v[74:77]
	v_mfma_f32_16x16x32_bf16 v[74:77], v[190:193], v[218:221], v[74:77]
	v_mfma_f32_16x16x32_bf16 v[66:69], v[190:193], v[226:229], v[66:69]
	v_mfma_f32_16x16x32_bf16 v[66:69], v[194:197], v[230:233], v[66:69]
	v_mfma_f32_16x16x32_bf16 v[70:73], v[186:189], v[230:233], v[70:73]
	v_mfma_f32_16x16x32_bf16 v[70:73], v[182:185], v[226:229], v[70:73]
	v_mfma_f32_16x16x32_bf16 v[78:81], v[174:177], v[226:229], v[78:81]
	v_mfma_f32_16x16x32_bf16 v[78:81], v[178:181], v[230:233], v[78:81]
	v_mfma_f32_16x16x32_bf16 v[86:89], v[170:173], v[230:233], v[86:89]
	v_mfma_f32_16x16x32_bf16 v[86:89], v[166:169], v[226:229], v[86:89]
	s_setprio 0
	s_barrier
	s_add_i32 s36, s68, s38
	v_lshl_add_u64 v[198:199], s[56:57], 0, v[136:137]
	s_mov_b32 m0, s36
	ds_read_b128 v[202:205], v160 offset:16384
	ds_read_b128 v[206:209], v160 offset:17408
	ds_read_b128 v[210:213], v160 offset:18432
	ds_read_b128 v[214:217], v160 offset:19456
	ds_read_b128 v[218:221], v160 offset:20480
	ds_read_b128 v[222:225], v160 offset:21504
	ds_read_b128 v[226:229], v160 offset:22528
	ds_read_b128 v[230:233], v160 offset:23552
	global_load_lds_dwordx4 v[198:199], off
	s_add_i32 m0, s36, 0x2000
	s_add_u32 s80, s56, 0x100000
	v_lshl_add_u64 v[234:235], s[56:57], 0, v[132:133]
	s_addc_u32 s81, s57, 0
	s_add_i32 s36, s69, s38
	global_load_lds_dwordx4 v[234:235], off
	v_lshl_add_u64 v[236:237], s[80:81], 0, v[136:137]
	s_mov_b32 m0, s36
	v_lshl_add_u64 v[238:239], s[58:59], 0, v[134:135]
	global_load_lds_dwordx4 v[236:237], off
	v_lshl_add_u64 v[236:237], s[80:81], 0, v[132:133]
	s_add_i32 m0, s36, 0x2000
	s_nop 0
	global_load_lds_dwordx4 v[236:237], off
	v_lshl_add_u64 v[236:237], s[58:59], 0, v[138:139]
	s_mov_b32 m0, s53
	s_nop 0
	global_load_lds_dwordx4 v[236:237], off
	s_mov_b32 m0, s61
	s_nop 0
	global_load_lds_dwordx4 v[238:239], off
	s_waitcnt vmcnt(8)
	s_waitcnt lgkmcnt(0)
	s_barrier
	s_setprio 1
	s_waitcnt lgkmcnt(0)
	v_mfma_f32_16x16x32_bf16 v[62:65], v[166:169], v[202:205], v[62:65]
	v_mfma_f32_16x16x32_bf16 v[62:65], v[170:173], v[206:209], v[62:65]
	v_mfma_f32_16x16x32_bf16 v[58:61], v[178:181], v[206:209], v[58:61]
	v_mfma_f32_16x16x32_bf16 v[58:61], v[174:177], v[202:205], v[58:61]
	v_mfma_f32_16x16x32_bf16 v[50:53], v[182:185], v[202:205], v[50:53]
	v_mfma_f32_16x16x32_bf16 v[50:53], v[186:189], v[206:209], v[50:53]
	v_mfma_f32_16x16x32_bf16 v[42:45], v[194:197], v[206:209], v[42:45]
	v_mfma_f32_16x16x32_bf16 v[42:45], v[190:193], v[202:205], v[42:45]
	v_mfma_f32_16x16x32_bf16 v[26:29], v[190:193], v[210:213], v[26:29]
	v_mfma_f32_16x16x32_bf16 v[26:29], v[194:197], v[214:217], v[26:29]
	v_mfma_f32_16x16x32_bf16 v[34:37], v[186:189], v[214:217], v[34:37]
	v_mfma_f32_16x16x32_bf16 v[34:37], v[182:185], v[210:213], v[34:37]
	v_mfma_f32_16x16x32_bf16 v[46:49], v[174:177], v[210:213], v[46:49]
	v_mfma_f32_16x16x32_bf16 v[46:49], v[178:181], v[214:217], v[46:49]
	v_mfma_f32_16x16x32_bf16 v[54:57], v[170:173], v[214:217], v[54:57]
	v_mfma_f32_16x16x32_bf16 v[54:57], v[166:169], v[210:213], v[54:57]
	v_mfma_f32_16x16x32_bf16 v[38:41], v[166:169], v[218:221], v[38:41]
	v_mfma_f32_16x16x32_bf16 v[38:41], v[170:173], v[222:225], v[38:41]
	v_mfma_f32_16x16x32_bf16 v[30:33], v[178:181], v[222:225], v[30:33]
	v_mfma_f32_16x16x32_bf16 v[30:33], v[174:177], v[218:221], v[30:33]
	v_mfma_f32_16x16x32_bf16 v[18:21], v[182:185], v[218:221], v[18:21]
	v_mfma_f32_16x16x32_bf16 v[18:21], v[186:189], v[222:225], v[18:21]
	v_mfma_f32_16x16x32_bf16 v[10:13], v[194:197], v[222:225], v[10:13]
	v_mfma_f32_16x16x32_bf16 v[10:13], v[190:193], v[218:221], v[10:13]
	v_mfma_f32_16x16x32_bf16 v[2:5], v[190:193], v[226:229], v[2:5]
	v_mfma_f32_16x16x32_bf16 v[2:5], v[194:197], v[230:233], v[2:5]
	v_mfma_f32_16x16x32_bf16 v[6:9], v[186:189], v[230:233], v[6:9]
	v_mfma_f32_16x16x32_bf16 v[6:9], v[182:185], v[226:229], v[6:9]
	v_mfma_f32_16x16x32_bf16 v[14:17], v[174:177], v[226:229], v[14:17]
	v_mfma_f32_16x16x32_bf16 v[14:17], v[178:181], v[230:233], v[14:17]
	v_mfma_f32_16x16x32_bf16 v[22:25], v[170:173], v[230:233], v[22:25]
	v_mfma_f32_16x16x32_bf16 v[22:25], v[166:169], v[226:229], v[22:25]
	s_setprio 0
	s_barrier
	s_add_i32 s36, 0, 0x18000
	v_add_u32_e32 v161, s36, v156
	s_add_i32 s37, 0, 0x1c000
	ds_read_b128 v[166:169], v161
	ds_read_b128 v[170:173], v161 offset:1024
	ds_read_b128 v[174:177], v161 offset:2048
	ds_read_b128 v[178:181], v161 offset:3072
	v_add_u32_e32 v161, s37, v156
	ds_read_b128 v[182:185], v161
	ds_read_b128 v[186:189], v161 offset:1024
	ds_read_b128 v[190:193], v161 offset:2048
	ds_read_b128 v[194:197], v161 offset:3072
	s_add_u32 s58, s58, 0x100000
	s_addc_u32 s59, s59, 0
	s_mov_b32 m0, s62
	v_lshl_add_u64 v[240:241], s[58:59], 0, v[138:139]
	ds_read_b128 v[202:205], v160 offset:32768
	ds_read_b128 v[206:209], v160 offset:33792
	ds_read_b128 v[210:213], v160 offset:34816
	ds_read_b128 v[214:217], v160 offset:35840
	ds_read_b128 v[218:221], v160 offset:36864
	ds_read_b128 v[222:225], v160 offset:37888
	ds_read_b128 v[226:229], v160 offset:38912
	ds_read_b128 v[230:233], v160 offset:39936
	global_load_lds_dwordx4 v[240:241], off
	v_lshl_add_u64 v[240:241], s[58:59], 0, v[134:135]
	s_mov_b32 m0, s63
	s_nop 0
	global_load_lds_dwordx4 v[240:241], off
	s_waitcnt vmcnt(8)
	s_waitcnt lgkmcnt(0)
	s_barrier
	s_setprio 1
	s_waitcnt lgkmcnt(0)
	v_mfma_f32_16x16x32_bf16 v[126:129], v[166:169], v[202:205], v[126:129]
	v_mfma_f32_16x16x32_bf16 v[126:129], v[170:173], v[206:209], v[126:129]
	v_mfma_f32_16x16x32_bf16 v[122:125], v[178:181], v[206:209], v[122:125]
	v_mfma_f32_16x16x32_bf16 v[122:125], v[174:177], v[202:205], v[122:125]
	v_mfma_f32_16x16x32_bf16 v[114:117], v[182:185], v[202:205], v[114:117]
	v_mfma_f32_16x16x32_bf16 v[114:117], v[186:189], v[206:209], v[114:117]
	v_mfma_f32_16x16x32_bf16 v[106:109], v[194:197], v[206:209], v[106:109]
	v_mfma_f32_16x16x32_bf16 v[106:109], v[190:193], v[202:205], v[106:109]
	v_mfma_f32_16x16x32_bf16 v[90:93], v[190:193], v[210:213], v[90:93]
	v_mfma_f32_16x16x32_bf16 v[90:93], v[194:197], v[214:217], v[90:93]
	v_mfma_f32_16x16x32_bf16 v[98:101], v[186:189], v[214:217], v[98:101]
	v_mfma_f32_16x16x32_bf16 v[98:101], v[182:185], v[210:213], v[98:101]
	v_mfma_f32_16x16x32_bf16 v[110:113], v[174:177], v[210:213], v[110:113]
	v_mfma_f32_16x16x32_bf16 v[110:113], v[178:181], v[214:217], v[110:113]
	v_mfma_f32_16x16x32_bf16 v[118:121], v[170:173], v[214:217], v[118:121]
	v_mfma_f32_16x16x32_bf16 v[118:121], v[166:169], v[210:213], v[118:121]
	v_mfma_f32_16x16x32_bf16 v[102:105], v[166:169], v[218:221], v[102:105]
	v_mfma_f32_16x16x32_bf16 v[102:105], v[170:173], v[222:225], v[102:105]
	v_mfma_f32_16x16x32_bf16 v[94:97], v[178:181], v[222:225], v[94:97]
	v_mfma_f32_16x16x32_bf16 v[94:97], v[174:177], v[218:221], v[94:97]
	v_mfma_f32_16x16x32_bf16 v[82:85], v[182:185], v[218:221], v[82:85]
	v_mfma_f32_16x16x32_bf16 v[82:85], v[186:189], v[222:225], v[82:85]
	v_mfma_f32_16x16x32_bf16 v[74:77], v[194:197], v[222:225], v[74:77]
	v_mfma_f32_16x16x32_bf16 v[74:77], v[190:193], v[218:221], v[74:77]
	v_mfma_f32_16x16x32_bf16 v[66:69], v[190:193], v[226:229], v[66:69]
	v_mfma_f32_16x16x32_bf16 v[66:69], v[194:197], v[230:233], v[66:69]
	v_mfma_f32_16x16x32_bf16 v[70:73], v[186:189], v[230:233], v[70:73]
	v_mfma_f32_16x16x32_bf16 v[70:73], v[182:185], v[226:229], v[70:73]
	v_mfma_f32_16x16x32_bf16 v[78:81], v[174:177], v[226:229], v[78:81]
	v_mfma_f32_16x16x32_bf16 v[78:81], v[178:181], v[230:233], v[78:81]
	v_mfma_f32_16x16x32_bf16 v[86:89], v[170:173], v[230:233], v[86:89]
	v_mfma_f32_16x16x32_bf16 v[86:89], v[166:169], v[226:229], v[86:89]
	s_setprio 0
	s_barrier
	s_add_i32 s36, s36, s38
	v_lshl_add_u64 v[198:199], v[198:199], 0, s[14:15]
	s_mov_b32 m0, s36
	ds_read_b128 v[202:205], v160 offset:49152
	ds_read_b128 v[206:209], v160 offset:50176
	ds_read_b128 v[210:213], v160 offset:51200
	ds_read_b128 v[214:217], v160 offset:52224
	ds_read_b128 v[218:221], v160 offset:53248
	ds_read_b128 v[222:225], v160 offset:54272
	ds_read_b128 v[226:229], v160 offset:55296
	ds_read_b128 v[230:233], v160 offset:56320
	global_load_lds_dwordx4 v[198:199], off
	s_add_i32 m0, s36, 0x2000
	s_add_u32 s56, s56, 0x100080
	v_lshl_add_u64 v[198:199], v[234:235], 0, s[14:15]
	s_addc_u32 s57, s57, 0
	s_add_i32 s36, s37, s38
	global_load_lds_dwordx4 v[198:199], off
	v_lshl_add_u64 v[198:199], s[56:57], 0, v[136:137]
	s_mov_b32 m0, s36
	s_nop 0
	global_load_lds_dwordx4 v[198:199], off
	v_lshl_add_u64 v[198:199], s[56:57], 0, v[132:133]
	s_add_i32 m0, s36, 0x2000
	s_nop 0
	global_load_lds_dwordx4 v[198:199], off
	v_lshl_add_u64 v[198:199], v[236:237], 0, s[14:15]
	s_mov_b32 m0, s65
	s_nop 0
	global_load_lds_dwordx4 v[198:199], off
	v_lshl_add_u64 v[198:199], v[238:239], 0, s[14:15]
	s_mov_b32 m0, s66
	s_nop 0
	global_load_lds_dwordx4 v[198:199], off
	s_waitcnt vmcnt(8)
	s_waitcnt lgkmcnt(0)
	s_barrier
	s_setprio 1
	s_waitcnt lgkmcnt(0)
	v_mfma_f32_16x16x32_bf16 v[62:65], v[166:169], v[202:205], v[62:65]
	v_mfma_f32_16x16x32_bf16 v[62:65], v[170:173], v[206:209], v[62:65]
	v_mfma_f32_16x16x32_bf16 v[58:61], v[178:181], v[206:209], v[58:61]
	v_mfma_f32_16x16x32_bf16 v[58:61], v[174:177], v[202:205], v[58:61]
	v_mfma_f32_16x16x32_bf16 v[50:53], v[182:185], v[202:205], v[50:53]
	v_mfma_f32_16x16x32_bf16 v[50:53], v[186:189], v[206:209], v[50:53]
	v_mfma_f32_16x16x32_bf16 v[42:45], v[194:197], v[206:209], v[42:45]
	v_mfma_f32_16x16x32_bf16 v[42:45], v[190:193], v[202:205], v[42:45]
	v_mfma_f32_16x16x32_bf16 v[26:29], v[190:193], v[210:213], v[26:29]
	v_mfma_f32_16x16x32_bf16 v[26:29], v[194:197], v[214:217], v[26:29]
	v_mfma_f32_16x16x32_bf16 v[34:37], v[186:189], v[214:217], v[34:37]
	v_mfma_f32_16x16x32_bf16 v[34:37], v[182:185], v[210:213], v[34:37]
	v_mfma_f32_16x16x32_bf16 v[46:49], v[174:177], v[210:213], v[46:49]
	v_mfma_f32_16x16x32_bf16 v[46:49], v[178:181], v[214:217], v[46:49]
	v_mfma_f32_16x16x32_bf16 v[54:57], v[170:173], v[214:217], v[54:57]
	v_mfma_f32_16x16x32_bf16 v[54:57], v[166:169], v[210:213], v[54:57]
	v_mfma_f32_16x16x32_bf16 v[38:41], v[166:169], v[218:221], v[38:41]
	v_mfma_f32_16x16x32_bf16 v[38:41], v[170:173], v[222:225], v[38:41]
	v_mfma_f32_16x16x32_bf16 v[30:33], v[178:181], v[222:225], v[30:33]
	v_mfma_f32_16x16x32_bf16 v[30:33], v[174:177], v[218:221], v[30:33]
	v_mfma_f32_16x16x32_bf16 v[18:21], v[182:185], v[218:221], v[18:21]
	v_mfma_f32_16x16x32_bf16 v[18:21], v[186:189], v[222:225], v[18:21]
	v_mfma_f32_16x16x32_bf16 v[10:13], v[194:197], v[222:225], v[10:13]
	v_mfma_f32_16x16x32_bf16 v[10:13], v[190:193], v[218:221], v[10:13]
	v_mfma_f32_16x16x32_bf16 v[2:5], v[190:193], v[226:229], v[2:5]
	v_mfma_f32_16x16x32_bf16 v[2:5], v[194:197], v[230:233], v[2:5]
	v_mfma_f32_16x16x32_bf16 v[6:9], v[186:189], v[230:233], v[6:9]
	v_mfma_f32_16x16x32_bf16 v[6:9], v[182:185], v[226:229], v[6:9]
	v_mfma_f32_16x16x32_bf16 v[14:17], v[174:177], v[226:229], v[14:17]
	v_mfma_f32_16x16x32_bf16 v[14:17], v[178:181], v[230:233], v[14:17]
	v_mfma_f32_16x16x32_bf16 v[22:25], v[170:173], v[230:233], v[22:25]
	v_mfma_f32_16x16x32_bf16 v[22:25], v[166:169], v[226:229], v[22:25]
	s_setprio 0
	s_barrier
	s_add_i32 s78, s78, 2
	s_add_u32 s54, s54, 0x100
	s_addc_u32 s55, s55, 0
	s_add_u32 s76, s76, 0x100
	s_addc_u32 s77, s77, 0
	s_cmp_gt_u32 s78, 61
	s_cbranch_scc0 .LBB0_1631
	s_and_b64 vcc, exec, s[16:17]
	s_cbranch_vccz .LBB0_1634
	s_barrier

.LBB0_1649:
	s_add_u32 s36, s56, s44
	s_addc_u32 s37, s57, 0
	s_add_u32 s64, s36, 0x100
	s_addc_u32 s65, s37, 0
	s_and_b64 s[62:63], s[60:61], exec
	s_cselect_b32 s65, s21, s65
	s_cselect_b32 s64, s87, s64
	s_add_u32 s44, s54, s44
	s_addc_u32 s62, s55, 0
	s_add_u32 s44, s44, 0x100
	s_addc_u32 s62, s62, 0
	s_and_b64 s[60:61], s[60:61], exec
	s_cselect_b32 s67, s19, s62
	s_cselect_b32 s66, s89, s44
	s_add_u32 s70, s36, 0x10080
	s_addc_u32 s71, s37, 0
	s_add_i32 vcc_lo, s84, s39
	ds_read_b128 v[158:161], v147
	ds_read_b128 v[166:169], v147 offset:1024
	ds_read_b128 v[170:173], v147 offset:2048
	ds_read_b128 v[174:177], v147 offset:3072
	ds_read_b128 v[178:181], v155
	ds_read_b128 v[182:185], v155 offset:1024
	ds_read_b128 v[186:189], v155 offset:2048
	ds_read_b128 v[190:193], v155 offset:3072
	s_add_i32 m0, s53, 0xc000
	s_add_i32 vcc_hi, s53, 0xe000
	s_add_i32 s95, vcc_lo, 0x2000
	s_add_u32 s68, s66, 0x10000
	s_addc_u32 s69, s67, 0
	s_add_i32 s97, s85, s39
	s_add_i32 s96, s97, 0x2000
	s_add_i32 s94, 0, 0x18000
	s_add_i32 s93, 0, 0x1c000
	s_add_u32 s62, s64, 0x10000
	s_addc_u32 s63, s65, 0
	s_add_i32 s92, s94, s39
	s_add_i32 s90, s92, 0x2000
	s_add_u32 s60, s66, 0x10080
	s_addc_u32 s61, s67, 0
	s_add_i32 s91, s93, s39
	s_add_i32 s44, s91, 0x2000
	v_lshl_add_u64 v[198:199], s[70:71], 0, v[138:139]
	ds_read_b128 v[194:197], v156
	ds_read_b128 v[202:205], v156 offset:1024
	ds_read_b128 v[206:209], v156 offset:2048
	ds_read_b128 v[210:213], v156 offset:3072
	ds_read_b128 v[214:217], v156 offset:4096
	ds_read_b128 v[218:221], v156 offset:5120
	ds_read_b128 v[222:225], v156 offset:6144
	ds_read_b128 v[226:229], v156 offset:7168
	global_load_lds_dwordx4 v[198:199], off
	v_lshl_add_u64 v[198:199], s[70:71], 0, v[134:135]
	s_mov_b32 m0, vcc_hi
	s_nop 0
	global_load_lds_dwordx4 v[198:199], off
	s_waitcnt vmcnt(8)
	s_waitcnt lgkmcnt(0)
	s_barrier
	s_setprio 1
	s_waitcnt lgkmcnt(0)
	v_mfma_f32_16x16x32_bf16 v[126:129], v[158:161], v[194:197], v[126:129]
	v_mfma_f32_16x16x32_bf16 v[126:129], v[166:169], v[202:205], v[126:129]
	v_mfma_f32_16x16x32_bf16 v[122:125], v[174:177], v[202:205], v[122:125]
	v_mfma_f32_16x16x32_bf16 v[122:125], v[170:173], v[194:197], v[122:125]
	v_mfma_f32_16x16x32_bf16 v[114:117], v[178:181], v[194:197], v[114:117]
	v_mfma_f32_16x16x32_bf16 v[114:117], v[182:185], v[202:205], v[114:117]
	v_mfma_f32_16x16x32_bf16 v[106:109], v[190:193], v[202:205], v[106:109]
	v_mfma_f32_16x16x32_bf16 v[106:109], v[186:189], v[194:197], v[106:109]
	v_mfma_f32_16x16x32_bf16 v[90:93], v[186:189], v[206:209], v[90:93]
	v_mfma_f32_16x16x32_bf16 v[90:93], v[190:193], v[210:213], v[90:93]
	v_mfma_f32_16x16x32_bf16 v[98:101], v[182:185], v[210:213], v[98:101]
	v_mfma_f32_16x16x32_bf16 v[98:101], v[178:181], v[206:209], v[98:101]
	v_mfma_f32_16x16x32_bf16 v[110:113], v[170:173], v[206:209], v[110:113]
	v_mfma_f32_16x16x32_bf16 v[110:113], v[174:177], v[210:213], v[110:113]
	v_mfma_f32_16x16x32_bf16 v[118:121], v[166:169], v[210:213], v[118:121]
	v_mfma_f32_16x16x32_bf16 v[118:121], v[158:161], v[206:209], v[118:121]
	v_mfma_f32_16x16x32_bf16 v[102:105], v[158:161], v[214:217], v[102:105]
	v_mfma_f32_16x16x32_bf16 v[102:105], v[166:169], v[218:221], v[102:105]
	v_mfma_f32_16x16x32_bf16 v[94:97], v[174:177], v[218:221], v[94:97]
	v_mfma_f32_16x16x32_bf16 v[94:97], v[170:173], v[214:217], v[94:97]
	v_mfma_f32_16x16x32_bf16 v[82:85], v[178:181], v[214:217], v[82:85]
	v_mfma_f32_16x16x32_bf16 v[82:85], v[182:185], v[218:221], v[82:85]
	v_mfma_f32_16x16x32_bf16 v[74:77], v[190:193], v[218:221], v[74:77]
	v_mfma_f32_16x16x32_bf16 v[74:77], v[186:189], v[214:217], v[74:77]
	v_mfma_f32_16x16x32_bf16 v[66:69], v[186:189], v[222:225], v[66:69]
	v_mfma_f32_16x16x32_bf16 v[66:69], v[190:193], v[226:229], v[66:69]
	v_mfma_f32_16x16x32_bf16 v[70:73], v[182:185], v[226:229], v[70:73]
	v_mfma_f32_16x16x32_bf16 v[70:73], v[178:181], v[222:225], v[70:73]
	v_mfma_f32_16x16x32_bf16 v[78:81], v[170:173], v[222:225], v[78:81]
	v_mfma_f32_16x16x32_bf16 v[78:81], v[174:177], v[226:229], v[78:81]
	v_mfma_f32_16x16x32_bf16 v[86:89], v[166:169], v[226:229], v[86:89]
	v_mfma_f32_16x16x32_bf16 v[86:89], v[158:161], v[222:225], v[86:89]
	s_setprio 0
	s_barrier
	s_mov_b32 m0, vcc_lo
	v_lshl_add_u64 v[198:199], s[66:67], 0, v[136:137]
	ds_read_b128 v[194:197], v156 offset:16384
	ds_read_b128 v[202:205], v156 offset:17408
	ds_read_b128 v[206:209], v156 offset:18432
	ds_read_b128 v[210:213], v156 offset:19456
	ds_read_b128 v[214:217], v156 offset:20480
	ds_read_b128 v[218:221], v156 offset:21504
	ds_read_b128 v[222:225], v156 offset:22528
	ds_read_b128 v[226:229], v156 offset:23552
	global_load_lds_dwordx4 v[198:199], off
	v_lshl_add_u64 v[230:231], s[66:67], 0, v[132:133]
	s_mov_b32 m0, s95
	v_lshl_add_u64 v[232:233], s[68:69], 0, v[136:137]
	global_load_lds_dwordx4 v[230:231], off
	s_mov_b32 m0, s97
	v_lshl_add_u64 v[234:235], s[64:65], 0, v[134:135]
	global_load_lds_dwordx4 v[232:233], off
	v_lshl_add_u64 v[232:233], s[68:69], 0, v[132:133]
	s_mov_b32 m0, s96
	s_nop 0
	global_load_lds_dwordx4 v[232:233], off
	v_lshl_add_u64 v[232:233], s[64:65], 0, v[138:139]
	s_mov_b32 m0, s53
	s_nop 0
	global_load_lds_dwordx4 v[232:233], off
	s_mov_b32 m0, s75
	s_nop 0
	global_load_lds_dwordx4 v[234:235], off
	s_waitcnt vmcnt(8)
	s_waitcnt lgkmcnt(0)
	s_barrier
	s_setprio 1
	s_waitcnt lgkmcnt(0)
	v_mfma_f32_16x16x32_bf16 v[62:65], v[158:161], v[194:197], v[62:65]
	v_mfma_f32_16x16x32_bf16 v[62:65], v[166:169], v[202:205], v[62:65]
	v_mfma_f32_16x16x32_bf16 v[58:61], v[174:177], v[202:205], v[58:61]
	v_mfma_f32_16x16x32_bf16 v[58:61], v[170:173], v[194:197], v[58:61]
	v_mfma_f32_16x16x32_bf16 v[50:53], v[178:181], v[194:197], v[50:53]
	v_mfma_f32_16x16x32_bf16 v[50:53], v[182:185], v[202:205], v[50:53]
	v_mfma_f32_16x16x32_bf16 v[42:45], v[190:193], v[202:205], v[42:45]
	v_mfma_f32_16x16x32_bf16 v[42:45], v[186:189], v[194:197], v[42:45]
	v_mfma_f32_16x16x32_bf16 v[26:29], v[186:189], v[206:209], v[26:29]
	v_mfma_f32_16x16x32_bf16 v[26:29], v[190:193], v[210:213], v[26:29]
	v_mfma_f32_16x16x32_bf16 v[34:37], v[182:185], v[210:213], v[34:37]
	v_mfma_f32_16x16x32_bf16 v[34:37], v[178:181], v[206:209], v[34:37]
	v_mfma_f32_16x16x32_bf16 v[46:49], v[170:173], v[206:209], v[46:49]
	v_mfma_f32_16x16x32_bf16 v[46:49], v[174:177], v[210:213], v[46:49]
	v_mfma_f32_16x16x32_bf16 v[54:57], v[166:169], v[210:213], v[54:57]
	v_mfma_f32_16x16x32_bf16 v[54:57], v[158:161], v[206:209], v[54:57]
	v_mfma_f32_16x16x32_bf16 v[38:41], v[158:161], v[214:217], v[38:41]
	v_mfma_f32_16x16x32_bf16 v[38:41], v[166:169], v[218:221], v[38:41]
	v_mfma_f32_16x16x32_bf16 v[30:33], v[174:177], v[218:221], v[30:33]
	v_mfma_f32_16x16x32_bf16 v[30:33], v[170:173], v[214:217], v[30:33]
	v_mfma_f32_16x16x32_bf16 v[18:21], v[178:181], v[214:217], v[18:21]
	v_mfma_f32_16x16x32_bf16 v[18:21], v[182:185], v[218:221], v[18:21]
	v_mfma_f32_16x16x32_bf16 v[10:13], v[190:193], v[218:221], v[10:13]
	v_mfma_f32_16x16x32_bf16 v[10:13], v[186:189], v[214:217], v[10:13]
	v_mfma_f32_16x16x32_bf16 v[2:5], v[186:189], v[222:225], v[2:5]
	v_mfma_f32_16x16x32_bf16 v[2:5], v[190:193], v[226:229], v[2:5]
	v_mfma_f32_16x16x32_bf16 v[6:9], v[182:185], v[226:229], v[6:9]
	v_mfma_f32_16x16x32_bf16 v[6:9], v[178:181], v[222:225], v[6:9]
	v_mfma_f32_16x16x32_bf16 v[14:17], v[170:173], v[222:225], v[14:17]
	v_mfma_f32_16x16x32_bf16 v[14:17], v[174:177], v[226:229], v[14:17]
	v_mfma_f32_16x16x32_bf16 v[22:25], v[166:169], v[226:229], v[22:25]
	v_mfma_f32_16x16x32_bf16 v[22:25], v[158:161], v[222:225], v[22:25]
	s_setprio 0
	s_barrier
	v_add_u32_e32 v157, s94, v145
	ds_read_b128 v[158:161], v157
	ds_read_b128 v[166:169], v157 offset:1024
	ds_read_b128 v[170:173], v157 offset:2048
	ds_read_b128 v[174:177], v157 offset:3072
	v_add_u32_e32 v157, s93, v145
	ds_read_b128 v[178:181], v157
	ds_read_b128 v[182:185], v157 offset:1024
	ds_read_b128 v[186:189], v157 offset:2048
	ds_read_b128 v[190:193], v157 offset:3072
	s_mov_b32 m0, s76
	v_lshl_add_u64 v[236:237], s[62:63], 0, v[138:139]
	ds_read_b128 v[194:197], v156 offset:32768
	ds_read_b128 v[202:205], v156 offset:33792
	ds_read_b128 v[206:209], v156 offset:34816
	ds_read_b128 v[210:213], v156 offset:35840
	ds_read_b128 v[214:217], v156 offset:36864
	ds_read_b128 v[218:221], v156 offset:37888
	ds_read_b128 v[222:225], v156 offset:38912
	ds_read_b128 v[226:229], v156 offset:39936
	global_load_lds_dwordx4 v[236:237], off
	v_lshl_add_u64 v[236:237], s[62:63], 0, v[134:135]
	s_mov_b32 m0, s77
	s_nop 0
	global_load_lds_dwordx4 v[236:237], off
	s_waitcnt vmcnt(8)
	s_waitcnt lgkmcnt(0)
	s_barrier
	s_setprio 1
	s_waitcnt lgkmcnt(0)
	v_mfma_f32_16x16x32_bf16 v[126:129], v[158:161], v[194:197], v[126:129]
	v_mfma_f32_16x16x32_bf16 v[126:129], v[166:169], v[202:205], v[126:129]
	v_mfma_f32_16x16x32_bf16 v[122:125], v[174:177], v[202:205], v[122:125]
	v_mfma_f32_16x16x32_bf16 v[122:125], v[170:173], v[194:197], v[122:125]
	v_mfma_f32_16x16x32_bf16 v[114:117], v[178:181], v[194:197], v[114:117]
	v_mfma_f32_16x16x32_bf16 v[114:117], v[182:185], v[202:205], v[114:117]
	v_mfma_f32_16x16x32_bf16 v[106:109], v[190:193], v[202:205], v[106:109]
	v_mfma_f32_16x16x32_bf16 v[106:109], v[186:189], v[194:197], v[106:109]
	v_mfma_f32_16x16x32_bf16 v[90:93], v[186:189], v[206:209], v[90:93]
	v_mfma_f32_16x16x32_bf16 v[90:93], v[190:193], v[210:213], v[90:93]
	v_mfma_f32_16x16x32_bf16 v[98:101], v[182:185], v[210:213], v[98:101]
	v_mfma_f32_16x16x32_bf16 v[98:101], v[178:181], v[206:209], v[98:101]
	v_mfma_f32_16x16x32_bf16 v[110:113], v[170:173], v[206:209], v[110:113]
	v_mfma_f32_16x16x32_bf16 v[110:113], v[174:177], v[210:213], v[110:113]
	v_mfma_f32_16x16x32_bf16 v[118:121], v[166:169], v[210:213], v[118:121]
	v_mfma_f32_16x16x32_bf16 v[118:121], v[158:161], v[206:209], v[118:121]
	v_mfma_f32_16x16x32_bf16 v[102:105], v[158:161], v[214:217], v[102:105]
	v_mfma_f32_16x16x32_bf16 v[102:105], v[166:169], v[218:221], v[102:105]
	v_mfma_f32_16x16x32_bf16 v[94:97], v[174:177], v[218:221], v[94:97]
	v_mfma_f32_16x16x32_bf16 v[94:97], v[170:173], v[214:217], v[94:97]
	v_mfma_f32_16x16x32_bf16 v[82:85], v[178:181], v[214:217], v[82:85]
	v_mfma_f32_16x16x32_bf16 v[82:85], v[182:185], v[218:221], v[82:85]
	v_mfma_f32_16x16x32_bf16 v[74:77], v[190:193], v[218:221], v[74:77]
	v_mfma_f32_16x16x32_bf16 v[74:77], v[186:189], v[214:217], v[74:77]
	v_mfma_f32_16x16x32_bf16 v[66:69], v[186:189], v[222:225], v[66:69]
	v_mfma_f32_16x16x32_bf16 v[66:69], v[190:193], v[226:229], v[66:69]
	v_mfma_f32_16x16x32_bf16 v[70:73], v[182:185], v[226:229], v[70:73]
	v_mfma_f32_16x16x32_bf16 v[70:73], v[178:181], v[222:225], v[70:73]
	v_mfma_f32_16x16x32_bf16 v[78:81], v[170:173], v[222:225], v[78:81]
	v_mfma_f32_16x16x32_bf16 v[78:81], v[174:177], v[226:229], v[78:81]
	v_mfma_f32_16x16x32_bf16 v[86:89], v[166:169], v[226:229], v[86:89]
	v_mfma_f32_16x16x32_bf16 v[86:89], v[158:161], v[222:225], v[86:89]
	s_setprio 0
	s_barrier
	s_mov_b32 m0, s92
	v_lshl_add_u64 v[198:199], v[198:199], 0, s[14:15]
	ds_read_b128 v[194:197], v156 offset:49152
	ds_read_b128 v[202:205], v156 offset:50176
	ds_read_b128 v[206:209], v156 offset:51200
	ds_read_b128 v[210:213], v156 offset:52224
	ds_read_b128 v[214:217], v156 offset:53248
	ds_read_b128 v[218:221], v156 offset:54272
	ds_read_b128 v[222:225], v156 offset:55296
	ds_read_b128 v[226:229], v156 offset:56320
	global_load_lds_dwordx4 v[198:199], off
	v_lshl_add_u64 v[198:199], v[230:231], 0, s[14:15]
	s_mov_b32 m0, s90
	s_nop 0
	global_load_lds_dwordx4 v[198:199], off
	v_lshl_add_u64 v[198:199], s[60:61], 0, v[136:137]
	s_mov_b32 m0, s91
	s_nop 0
	global_load_lds_dwordx4 v[198:199], off
	v_lshl_add_u64 v[198:199], s[60:61], 0, v[132:133]
	s_mov_b32 m0, s44
	s_nop 0
	global_load_lds_dwordx4 v[198:199], off
	v_lshl_add_u64 v[198:199], v[232:233], 0, s[14:15]
	s_mov_b32 m0, s80
	s_nop 0
	global_load_lds_dwordx4 v[198:199], off
	v_lshl_add_u64 v[198:199], v[234:235], 0, s[14:15]
	s_mov_b32 m0, s81
	s_nop 0
	global_load_lds_dwordx4 v[198:199], off
	s_waitcnt vmcnt(8)
	s_waitcnt lgkmcnt(0)
	s_barrier
	s_setprio 1
	s_waitcnt lgkmcnt(0)
	v_mfma_f32_16x16x32_bf16 v[62:65], v[158:161], v[194:197], v[62:65]
	v_mfma_f32_16x16x32_bf16 v[62:65], v[166:169], v[202:205], v[62:65]
	v_mfma_f32_16x16x32_bf16 v[58:61], v[174:177], v[202:205], v[58:61]
	v_mfma_f32_16x16x32_bf16 v[58:61], v[170:173], v[194:197], v[58:61]
	v_mfma_f32_16x16x32_bf16 v[50:53], v[178:181], v[194:197], v[50:53]
	v_mfma_f32_16x16x32_bf16 v[50:53], v[182:185], v[202:205], v[50:53]
	v_mfma_f32_16x16x32_bf16 v[42:45], v[190:193], v[202:205], v[42:45]
	v_mfma_f32_16x16x32_bf16 v[42:45], v[186:189], v[194:197], v[42:45]
	v_mfma_f32_16x16x32_bf16 v[26:29], v[186:189], v[206:209], v[26:29]
	v_mfma_f32_16x16x32_bf16 v[26:29], v[190:193], v[210:213], v[26:29]
	v_mfma_f32_16x16x32_bf16 v[34:37], v[182:185], v[210:213], v[34:37]
	v_mfma_f32_16x16x32_bf16 v[34:37], v[178:181], v[206:209], v[34:37]
	v_mfma_f32_16x16x32_bf16 v[46:49], v[170:173], v[206:209], v[46:49]
	v_mfma_f32_16x16x32_bf16 v[46:49], v[174:177], v[210:213], v[46:49]
	v_mfma_f32_16x16x32_bf16 v[54:57], v[166:169], v[210:213], v[54:57]
	v_mfma_f32_16x16x32_bf16 v[54:57], v[158:161], v[206:209], v[54:57]
	v_mfma_f32_16x16x32_bf16 v[38:41], v[158:161], v[214:217], v[38:41]
	v_mfma_f32_16x16x32_bf16 v[38:41], v[166:169], v[218:221], v[38:41]
	v_mfma_f32_16x16x32_bf16 v[30:33], v[174:177], v[218:221], v[30:33]
	v_mfma_f32_16x16x32_bf16 v[30:33], v[170:173], v[214:217], v[30:33]
	v_mfma_f32_16x16x32_bf16 v[18:21], v[178:181], v[214:217], v[18:21]
	v_mfma_f32_16x16x32_bf16 v[18:21], v[182:185], v[218:221], v[18:21]
	v_mfma_f32_16x16x32_bf16 v[10:13], v[190:193], v[218:221], v[10:13]
	v_mfma_f32_16x16x32_bf16 v[10:13], v[186:189], v[214:217], v[10:13]
	v_mfma_f32_16x16x32_bf16 v[2:5], v[186:189], v[222:225], v[2:5]
	v_mfma_f32_16x16x32_bf16 v[2:5], v[190:193], v[226:229], v[2:5]
	v_mfma_f32_16x16x32_bf16 v[6:9], v[182:185], v[226:229], v[6:9]
	v_mfma_f32_16x16x32_bf16 v[6:9], v[178:181], v[222:225], v[6:9]
	v_mfma_f32_16x16x32_bf16 v[14:17], v[170:173], v[222:225], v[14:17]
	v_mfma_f32_16x16x32_bf16 v[14:17], v[174:177], v[226:229], v[14:17]
	v_mfma_f32_16x16x32_bf16 v[22:25], v[166:169], v[226:229], v[22:25]
	v_mfma_f32_16x16x32_bf16 v[22:25], v[158:161], v[222:225], v[22:25]
	s_setprio 0
	s_barrier
	s_movk_i32 s44, 0x100
	s_andn2_b64 vcc, exec, s[58:59]
	s_mov_b64 s[60:61], -1
	s_mov_b64 s[58:59], 0
	s_cbranch_vccz .LBB0_1649
	s_and_b64 vcc, exec, s[16:17]
	s_cbranch_vccz .LBB0_1652
	s_barrier

.LBB0_1667:
	s_add_u32 s36, s56, s44
	s_addc_u32 s37, s57, 0
	s_add_u32 s64, s36, 0x100
	s_addc_u32 s65, s37, 0
	s_and_b64 s[62:63], s[60:61], exec
	s_cselect_b32 s65, s21, s65
	s_cselect_b32 s64, s86, s64
	s_add_u32 s44, s54, s44
	s_addc_u32 s62, s55, 0
	s_add_u32 s44, s44, 0x100
	s_addc_u32 s62, s62, 0
	s_and_b64 s[60:61], s[60:61], exec
	s_cselect_b32 s67, s19, s62
	s_cselect_b32 s66, s87, s44
	s_add_u32 s70, s36, 0x10080
	s_addc_u32 s71, s37, 0
	s_add_i32 s97, s82, s38
	ds_read_b128 v[150:153], v146
	ds_read_b128 v[154:157], v146 offset:1024
	ds_read_b128 v[158:161], v146 offset:2048
	ds_read_b128 v[166:169], v146 offset:3072
	ds_read_b128 v[170:173], v147
	ds_read_b128 v[174:177], v147 offset:1024
	ds_read_b128 v[178:181], v147 offset:2048
	ds_read_b128 v[182:185], v147 offset:3072
	s_add_i32 m0, s53, 0xc000
	s_add_i32 vcc_lo, s53, 0xe000
	s_add_i32 s94, s97, 0x2000
	s_add_u32 s68, s66, 0x10000
	s_addc_u32 s69, s67, 0
	s_add_i32 s96, s83, s38
	s_add_i32 s95, s96, 0x2000
	s_add_i32 s93, 0, 0x18000
	s_add_i32 s92, 0, 0x1c000
	s_add_u32 s62, s64, 0x10000
	s_addc_u32 s63, s65, 0
	s_add_i32 s91, s93, s38
	s_add_i32 s89, s91, 0x2000
	s_add_u32 s60, s66, 0x10080
	s_addc_u32 s61, s67, 0
	s_add_i32 s90, s92, s38
	s_add_i32 s44, s90, 0x2000
	v_lshl_add_u64 v[198:199], s[70:71], 0, v[138:139]
	ds_read_b128 v[186:189], v148
	ds_read_b128 v[190:193], v148 offset:1024
	ds_read_b128 v[194:197], v148 offset:2048
	ds_read_b128 v[202:205], v148 offset:3072
	ds_read_b128 v[206:209], v148 offset:4096
	ds_read_b128 v[210:213], v148 offset:5120
	ds_read_b128 v[214:217], v148 offset:6144
	ds_read_b128 v[218:221], v148 offset:7168
	global_load_lds_dwordx4 v[198:199], off
	v_lshl_add_u64 v[198:199], s[70:71], 0, v[134:135]
	s_mov_b32 m0, vcc_lo
	s_nop 0
	global_load_lds_dwordx4 v[198:199], off
	s_waitcnt vmcnt(8)
	s_waitcnt lgkmcnt(0)
	s_barrier
	s_setprio 1
	s_waitcnt lgkmcnt(0)
	v_mfma_f32_16x16x32_bf16 v[126:129], v[150:153], v[186:189], v[126:129]
	v_mfma_f32_16x16x32_bf16 v[126:129], v[154:157], v[190:193], v[126:129]
	v_mfma_f32_16x16x32_bf16 v[122:125], v[166:169], v[190:193], v[122:125]
	v_mfma_f32_16x16x32_bf16 v[122:125], v[158:161], v[186:189], v[122:125]
	v_mfma_f32_16x16x32_bf16 v[114:117], v[170:173], v[186:189], v[114:117]
	v_mfma_f32_16x16x32_bf16 v[114:117], v[174:177], v[190:193], v[114:117]
	v_mfma_f32_16x16x32_bf16 v[106:109], v[182:185], v[190:193], v[106:109]
	v_mfma_f32_16x16x32_bf16 v[106:109], v[178:181], v[186:189], v[106:109]
	v_mfma_f32_16x16x32_bf16 v[90:93], v[178:181], v[194:197], v[90:93]
	v_mfma_f32_16x16x32_bf16 v[90:93], v[182:185], v[202:205], v[90:93]
	v_mfma_f32_16x16x32_bf16 v[98:101], v[174:177], v[202:205], v[98:101]
	v_mfma_f32_16x16x32_bf16 v[98:101], v[170:173], v[194:197], v[98:101]
	v_mfma_f32_16x16x32_bf16 v[110:113], v[158:161], v[194:197], v[110:113]
	v_mfma_f32_16x16x32_bf16 v[110:113], v[166:169], v[202:205], v[110:113]
	v_mfma_f32_16x16x32_bf16 v[118:121], v[154:157], v[202:205], v[118:121]
	v_mfma_f32_16x16x32_bf16 v[118:121], v[150:153], v[194:197], v[118:121]
	v_mfma_f32_16x16x32_bf16 v[102:105], v[150:153], v[206:209], v[102:105]
	v_mfma_f32_16x16x32_bf16 v[102:105], v[154:157], v[210:213], v[102:105]
	v_mfma_f32_16x16x32_bf16 v[94:97], v[166:169], v[210:213], v[94:97]
	v_mfma_f32_16x16x32_bf16 v[94:97], v[158:161], v[206:209], v[94:97]
	v_mfma_f32_16x16x32_bf16 v[82:85], v[170:173], v[206:209], v[82:85]
	v_mfma_f32_16x16x32_bf16 v[82:85], v[174:177], v[210:213], v[82:85]
	v_mfma_f32_16x16x32_bf16 v[74:77], v[182:185], v[210:213], v[74:77]
	v_mfma_f32_16x16x32_bf16 v[74:77], v[178:181], v[206:209], v[74:77]
	v_mfma_f32_16x16x32_bf16 v[66:69], v[178:181], v[214:217], v[66:69]
	v_mfma_f32_16x16x32_bf16 v[66:69], v[182:185], v[218:221], v[66:69]
	v_mfma_f32_16x16x32_bf16 v[70:73], v[174:177], v[218:221], v[70:73]
	v_mfma_f32_16x16x32_bf16 v[70:73], v[170:173], v[214:217], v[70:73]
	v_mfma_f32_16x16x32_bf16 v[78:81], v[158:161], v[214:217], v[78:81]
	v_mfma_f32_16x16x32_bf16 v[78:81], v[166:169], v[218:221], v[78:81]
	v_mfma_f32_16x16x32_bf16 v[86:89], v[154:157], v[218:221], v[86:89]
	v_mfma_f32_16x16x32_bf16 v[86:89], v[150:153], v[214:217], v[86:89]
	s_setprio 0
	s_barrier
	s_mov_b32 m0, s97
	v_lshl_add_u64 v[198:199], s[66:67], 0, v[136:137]
	ds_read_b128 v[186:189], v148 offset:16384
	ds_read_b128 v[190:193], v148 offset:17408
	ds_read_b128 v[194:197], v148 offset:18432
	ds_read_b128 v[202:205], v148 offset:19456
	ds_read_b128 v[206:209], v148 offset:20480
	ds_read_b128 v[210:213], v148 offset:21504
	ds_read_b128 v[214:217], v148 offset:22528
	ds_read_b128 v[218:221], v148 offset:23552
	global_load_lds_dwordx4 v[198:199], off
	v_lshl_add_u64 v[222:223], s[66:67], 0, v[132:133]
	s_mov_b32 m0, s94
	v_lshl_add_u64 v[224:225], s[68:69], 0, v[136:137]
	global_load_lds_dwordx4 v[222:223], off
	s_mov_b32 m0, s96
	v_lshl_add_u64 v[226:227], s[64:65], 0, v[134:135]
	global_load_lds_dwordx4 v[224:225], off
	v_lshl_add_u64 v[224:225], s[68:69], 0, v[132:133]
	s_mov_b32 m0, s95
	s_nop 0
	global_load_lds_dwordx4 v[224:225], off
	v_lshl_add_u64 v[224:225], s[64:65], 0, v[138:139]
	s_mov_b32 m0, s53
	s_nop 0
	global_load_lds_dwordx4 v[224:225], off
	s_mov_b32 m0, s75
	s_nop 0
	global_load_lds_dwordx4 v[226:227], off
	s_waitcnt vmcnt(8)
	s_waitcnt lgkmcnt(0)
	s_barrier
	s_setprio 1
	s_waitcnt lgkmcnt(0)
	v_mfma_f32_16x16x32_bf16 v[62:65], v[150:153], v[186:189], v[62:65]
	v_mfma_f32_16x16x32_bf16 v[62:65], v[154:157], v[190:193], v[62:65]
	v_mfma_f32_16x16x32_bf16 v[58:61], v[166:169], v[190:193], v[58:61]
	v_mfma_f32_16x16x32_bf16 v[58:61], v[158:161], v[186:189], v[58:61]
	v_mfma_f32_16x16x32_bf16 v[50:53], v[170:173], v[186:189], v[50:53]
	v_mfma_f32_16x16x32_bf16 v[50:53], v[174:177], v[190:193], v[50:53]
	v_mfma_f32_16x16x32_bf16 v[42:45], v[182:185], v[190:193], v[42:45]
	v_mfma_f32_16x16x32_bf16 v[42:45], v[178:181], v[186:189], v[42:45]
	v_mfma_f32_16x16x32_bf16 v[26:29], v[178:181], v[194:197], v[26:29]
	v_mfma_f32_16x16x32_bf16 v[26:29], v[182:185], v[202:205], v[26:29]
	v_mfma_f32_16x16x32_bf16 v[34:37], v[174:177], v[202:205], v[34:37]
	v_mfma_f32_16x16x32_bf16 v[34:37], v[170:173], v[194:197], v[34:37]
	v_mfma_f32_16x16x32_bf16 v[46:49], v[158:161], v[194:197], v[46:49]
	v_mfma_f32_16x16x32_bf16 v[46:49], v[166:169], v[202:205], v[46:49]
	v_mfma_f32_16x16x32_bf16 v[54:57], v[154:157], v[202:205], v[54:57]
	v_mfma_f32_16x16x32_bf16 v[54:57], v[150:153], v[194:197], v[54:57]
	v_mfma_f32_16x16x32_bf16 v[38:41], v[150:153], v[206:209], v[38:41]
	v_mfma_f32_16x16x32_bf16 v[38:41], v[154:157], v[210:213], v[38:41]
	v_mfma_f32_16x16x32_bf16 v[30:33], v[166:169], v[210:213], v[30:33]
	v_mfma_f32_16x16x32_bf16 v[30:33], v[158:161], v[206:209], v[30:33]
	v_mfma_f32_16x16x32_bf16 v[18:21], v[170:173], v[206:209], v[18:21]
	v_mfma_f32_16x16x32_bf16 v[18:21], v[174:177], v[210:213], v[18:21]
	v_mfma_f32_16x16x32_bf16 v[10:13], v[182:185], v[210:213], v[10:13]
	v_mfma_f32_16x16x32_bf16 v[10:13], v[178:181], v[206:209], v[10:13]
	v_mfma_f32_16x16x32_bf16 v[2:5], v[178:181], v[214:217], v[2:5]
	v_mfma_f32_16x16x32_bf16 v[2:5], v[182:185], v[218:221], v[2:5]
	v_mfma_f32_16x16x32_bf16 v[6:9], v[174:177], v[218:221], v[6:9]
	v_mfma_f32_16x16x32_bf16 v[6:9], v[170:173], v[214:217], v[6:9]
	v_mfma_f32_16x16x32_bf16 v[14:17], v[158:161], v[214:217], v[14:17]
	v_mfma_f32_16x16x32_bf16 v[14:17], v[166:169], v[218:221], v[14:17]
	v_mfma_f32_16x16x32_bf16 v[22:25], v[154:157], v[218:221], v[22:25]
	v_mfma_f32_16x16x32_bf16 v[22:25], v[150:153], v[214:217], v[22:25]
	s_setprio 0
	s_barrier
	v_add_u32_e32 v149, s93, v145
	ds_read_b128 v[150:153], v149
	ds_read_b128 v[154:157], v149 offset:1024
	ds_read_b128 v[158:161], v149 offset:2048
	ds_read_b128 v[166:169], v149 offset:3072
	v_add_u32_e32 v149, s92, v145
	ds_read_b128 v[170:173], v149
	ds_read_b128 v[174:177], v149 offset:1024
	ds_read_b128 v[178:181], v149 offset:2048
	ds_read_b128 v[182:185], v149 offset:3072
	s_mov_b32 m0, s76
	v_lshl_add_u64 v[228:229], s[62:63], 0, v[138:139]
	ds_read_b128 v[186:189], v148 offset:32768
	ds_read_b128 v[190:193], v148 offset:33792
	ds_read_b128 v[194:197], v148 offset:34816
	ds_read_b128 v[202:205], v148 offset:35840
	ds_read_b128 v[206:209], v148 offset:36864
	ds_read_b128 v[210:213], v148 offset:37888
	ds_read_b128 v[214:217], v148 offset:38912
	ds_read_b128 v[218:221], v148 offset:39936
	global_load_lds_dwordx4 v[228:229], off
	v_lshl_add_u64 v[228:229], s[62:63], 0, v[134:135]
	s_mov_b32 m0, s77
	s_nop 0
	global_load_lds_dwordx4 v[228:229], off
	s_waitcnt vmcnt(8)
	s_waitcnt lgkmcnt(0)
	s_barrier
	s_setprio 1
	s_waitcnt lgkmcnt(0)
	v_mfma_f32_16x16x32_bf16 v[126:129], v[150:153], v[186:189], v[126:129]
	v_mfma_f32_16x16x32_bf16 v[126:129], v[154:157], v[190:193], v[126:129]
	v_mfma_f32_16x16x32_bf16 v[122:125], v[166:169], v[190:193], v[122:125]
	v_mfma_f32_16x16x32_bf16 v[122:125], v[158:161], v[186:189], v[122:125]
	v_mfma_f32_16x16x32_bf16 v[114:117], v[170:173], v[186:189], v[114:117]
	v_mfma_f32_16x16x32_bf16 v[114:117], v[174:177], v[190:193], v[114:117]
	v_mfma_f32_16x16x32_bf16 v[106:109], v[182:185], v[190:193], v[106:109]
	v_mfma_f32_16x16x32_bf16 v[106:109], v[178:181], v[186:189], v[106:109]
	v_mfma_f32_16x16x32_bf16 v[90:93], v[178:181], v[194:197], v[90:93]
	v_mfma_f32_16x16x32_bf16 v[90:93], v[182:185], v[202:205], v[90:93]
	v_mfma_f32_16x16x32_bf16 v[98:101], v[174:177], v[202:205], v[98:101]
	v_mfma_f32_16x16x32_bf16 v[98:101], v[170:173], v[194:197], v[98:101]
	v_mfma_f32_16x16x32_bf16 v[110:113], v[158:161], v[194:197], v[110:113]
	v_mfma_f32_16x16x32_bf16 v[110:113], v[166:169], v[202:205], v[110:113]
	v_mfma_f32_16x16x32_bf16 v[118:121], v[154:157], v[202:205], v[118:121]
	v_mfma_f32_16x16x32_bf16 v[118:121], v[150:153], v[194:197], v[118:121]
	v_mfma_f32_16x16x32_bf16 v[102:105], v[150:153], v[206:209], v[102:105]
	v_mfma_f32_16x16x32_bf16 v[102:105], v[154:157], v[210:213], v[102:105]
	v_mfma_f32_16x16x32_bf16 v[94:97], v[166:169], v[210:213], v[94:97]
	v_mfma_f32_16x16x32_bf16 v[94:97], v[158:161], v[206:209], v[94:97]
	v_mfma_f32_16x16x32_bf16 v[82:85], v[170:173], v[206:209], v[82:85]
	v_mfma_f32_16x16x32_bf16 v[82:85], v[174:177], v[210:213], v[82:85]
	v_mfma_f32_16x16x32_bf16 v[74:77], v[182:185], v[210:213], v[74:77]
	v_mfma_f32_16x16x32_bf16 v[74:77], v[178:181], v[206:209], v[74:77]
	v_mfma_f32_16x16x32_bf16 v[66:69], v[178:181], v[214:217], v[66:69]
	v_mfma_f32_16x16x32_bf16 v[66:69], v[182:185], v[218:221], v[66:69]
	v_mfma_f32_16x16x32_bf16 v[70:73], v[174:177], v[218:221], v[70:73]
	v_mfma_f32_16x16x32_bf16 v[70:73], v[170:173], v[214:217], v[70:73]
	v_mfma_f32_16x16x32_bf16 v[78:81], v[158:161], v[214:217], v[78:81]
	v_mfma_f32_16x16x32_bf16 v[78:81], v[166:169], v[218:221], v[78:81]
	v_mfma_f32_16x16x32_bf16 v[86:89], v[154:157], v[218:221], v[86:89]
	v_mfma_f32_16x16x32_bf16 v[86:89], v[150:153], v[214:217], v[86:89]
	s_setprio 0
	s_barrier
	s_mov_b32 m0, s91
	v_lshl_add_u64 v[198:199], v[198:199], 0, s[14:15]
	ds_read_b128 v[186:189], v148 offset:49152
	ds_read_b128 v[190:193], v148 offset:50176
	ds_read_b128 v[194:197], v148 offset:51200
	ds_read_b128 v[202:205], v148 offset:52224
	ds_read_b128 v[206:209], v148 offset:53248
	ds_read_b128 v[210:213], v148 offset:54272
	ds_read_b128 v[214:217], v148 offset:55296
	ds_read_b128 v[218:221], v148 offset:56320
	global_load_lds_dwordx4 v[198:199], off
	v_lshl_add_u64 v[198:199], v[222:223], 0, s[14:15]
	s_mov_b32 m0, s89
	s_nop 0
	global_load_lds_dwordx4 v[198:199], off
	v_lshl_add_u64 v[198:199], s[60:61], 0, v[136:137]
	s_mov_b32 m0, s90
	s_nop 0
	global_load_lds_dwordx4 v[198:199], off
	v_lshl_add_u64 v[198:199], s[60:61], 0, v[132:133]
	s_mov_b32 m0, s44
	s_nop 0
	global_load_lds_dwordx4 v[198:199], off
	v_lshl_add_u64 v[198:199], v[224:225], 0, s[14:15]
	s_mov_b32 m0, s79
	s_nop 0
	global_load_lds_dwordx4 v[198:199], off
	v_lshl_add_u64 v[198:199], v[226:227], 0, s[14:15]
	s_mov_b32 m0, s80
	s_nop 0
	global_load_lds_dwordx4 v[198:199], off
	s_waitcnt vmcnt(8)
	s_waitcnt lgkmcnt(0)
	s_barrier
	s_setprio 1
	s_waitcnt lgkmcnt(0)
	v_mfma_f32_16x16x32_bf16 v[62:65], v[150:153], v[186:189], v[62:65]
	v_mfma_f32_16x16x32_bf16 v[62:65], v[154:157], v[190:193], v[62:65]
	v_mfma_f32_16x16x32_bf16 v[58:61], v[166:169], v[190:193], v[58:61]
	v_mfma_f32_16x16x32_bf16 v[58:61], v[158:161], v[186:189], v[58:61]
	v_mfma_f32_16x16x32_bf16 v[50:53], v[170:173], v[186:189], v[50:53]
	v_mfma_f32_16x16x32_bf16 v[50:53], v[174:177], v[190:193], v[50:53]
	v_mfma_f32_16x16x32_bf16 v[42:45], v[182:185], v[190:193], v[42:45]
	v_mfma_f32_16x16x32_bf16 v[42:45], v[178:181], v[186:189], v[42:45]
	v_mfma_f32_16x16x32_bf16 v[26:29], v[178:181], v[194:197], v[26:29]
	v_mfma_f32_16x16x32_bf16 v[26:29], v[182:185], v[202:205], v[26:29]
	v_mfma_f32_16x16x32_bf16 v[34:37], v[174:177], v[202:205], v[34:37]
	v_mfma_f32_16x16x32_bf16 v[34:37], v[170:173], v[194:197], v[34:37]
	v_mfma_f32_16x16x32_bf16 v[46:49], v[158:161], v[194:197], v[46:49]
	v_mfma_f32_16x16x32_bf16 v[46:49], v[166:169], v[202:205], v[46:49]
	v_mfma_f32_16x16x32_bf16 v[54:57], v[154:157], v[202:205], v[54:57]
	v_mfma_f32_16x16x32_bf16 v[54:57], v[150:153], v[194:197], v[54:57]
	v_mfma_f32_16x16x32_bf16 v[38:41], v[150:153], v[206:209], v[38:41]
	v_mfma_f32_16x16x32_bf16 v[38:41], v[154:157], v[210:213], v[38:41]
	v_mfma_f32_16x16x32_bf16 v[30:33], v[166:169], v[210:213], v[30:33]
	v_mfma_f32_16x16x32_bf16 v[30:33], v[158:161], v[206:209], v[30:33]
	v_mfma_f32_16x16x32_bf16 v[18:21], v[170:173], v[206:209], v[18:21]
	v_mfma_f32_16x16x32_bf16 v[18:21], v[174:177], v[210:213], v[18:21]
	v_mfma_f32_16x16x32_bf16 v[10:13], v[182:185], v[210:213], v[10:13]
	v_mfma_f32_16x16x32_bf16 v[10:13], v[178:181], v[206:209], v[10:13]
	v_mfma_f32_16x16x32_bf16 v[2:5], v[178:181], v[214:217], v[2:5]
	v_mfma_f32_16x16x32_bf16 v[2:5], v[182:185], v[218:221], v[2:5]
	v_mfma_f32_16x16x32_bf16 v[6:9], v[174:177], v[218:221], v[6:9]
	v_mfma_f32_16x16x32_bf16 v[6:9], v[170:173], v[214:217], v[6:9]
	v_mfma_f32_16x16x32_bf16 v[14:17], v[158:161], v[214:217], v[14:17]
	v_mfma_f32_16x16x32_bf16 v[14:17], v[166:169], v[218:221], v[14:17]
	v_mfma_f32_16x16x32_bf16 v[22:25], v[154:157], v[218:221], v[22:25]
	v_mfma_f32_16x16x32_bf16 v[22:25], v[150:153], v[214:217], v[22:25]
	s_setprio 0
	s_barrier
	s_movk_i32 s44, 0x100
	s_andn2_b64 vcc, exec, s[58:59]
	s_mov_b64 s[60:61], -1
	s_mov_b64 s[58:59], 0
	s_cbranch_vccz .LBB0_1667
	s_and_b64 vcc, exec, s[16:17]
	s_cbranch_vccz .LBB0_1670
	s_barrier

.LBB0_1685:
	ds_read_b128 v[156:159], v153
	ds_read_b128 v[166:169], v153 offset:1024
	ds_read_b128 v[170:173], v153 offset:2048
	ds_read_b128 v[174:177], v153 offset:3072
	ds_read_b128 v[178:181], v154
	ds_read_b128 v[182:185], v154 offset:1024
	ds_read_b128 v[186:189], v154 offset:2048
	ds_read_b128 v[190:193], v154 offset:3072
	s_add_u32 s36, s56, 0xfff00080
	s_addc_u32 s37, s57, -1
	s_cmp_eq_u32 s78, 60
	s_cselect_b32 s61, s25, s37
	s_cselect_b32 s60, s74, s36
	s_cselect_b32 s59, s21, s77
	s_cselect_b32 s58, s75, s76
	v_lshl_add_u64 v[160:161], s[56:57], 0, v[140:141]
	s_add_i32 m0, s55, 0xc000
	ds_read_b128 v[194:197], v155
	ds_read_b128 v[202:205], v155 offset:1024
	ds_read_b128 v[206:209], v155 offset:2048
	ds_read_b128 v[210:213], v155 offset:3072
	ds_read_b128 v[214:217], v155 offset:4096
	ds_read_b128 v[218:221], v155 offset:5120
	ds_read_b128 v[222:225], v155 offset:6144
	ds_read_b128 v[226:229], v155 offset:7168
	global_load_lds_dwordx4 v[160:161], off
	v_lshl_add_u64 v[160:161], s[56:57], 0, v[142:143]
	s_add_i32 m0, s55, 0xe000
	s_nop 0
	global_load_lds_dwordx4 v[160:161], off
	s_waitcnt vmcnt(8)
	s_waitcnt lgkmcnt(0)
	s_barrier
	s_setprio 1
	s_waitcnt lgkmcnt(0)
	v_mfma_f32_16x16x32_bf16 v[126:129], v[156:159], v[194:197], v[126:129]
	v_mfma_f32_16x16x32_bf16 v[126:129], v[166:169], v[202:205], v[126:129]
	v_mfma_f32_16x16x32_bf16 v[122:125], v[174:177], v[202:205], v[122:125]
	v_mfma_f32_16x16x32_bf16 v[122:125], v[170:173], v[194:197], v[122:125]
	v_mfma_f32_16x16x32_bf16 v[114:117], v[178:181], v[194:197], v[114:117]
	v_mfma_f32_16x16x32_bf16 v[114:117], v[182:185], v[202:205], v[114:117]
	v_mfma_f32_16x16x32_bf16 v[106:109], v[190:193], v[202:205], v[106:109]
	v_mfma_f32_16x16x32_bf16 v[106:109], v[186:189], v[194:197], v[106:109]
	v_mfma_f32_16x16x32_bf16 v[90:93], v[186:189], v[206:209], v[90:93]
	v_mfma_f32_16x16x32_bf16 v[90:93], v[190:193], v[210:213], v[90:93]
	v_mfma_f32_16x16x32_bf16 v[98:101], v[182:185], v[210:213], v[98:101]
	v_mfma_f32_16x16x32_bf16 v[98:101], v[178:181], v[206:209], v[98:101]
	v_mfma_f32_16x16x32_bf16 v[110:113], v[170:173], v[206:209], v[110:113]
	v_mfma_f32_16x16x32_bf16 v[110:113], v[174:177], v[210:213], v[110:113]
	v_mfma_f32_16x16x32_bf16 v[118:121], v[166:169], v[210:213], v[118:121]
	v_mfma_f32_16x16x32_bf16 v[118:121], v[156:159], v[206:209], v[118:121]
	v_mfma_f32_16x16x32_bf16 v[102:105], v[156:159], v[214:217], v[102:105]
	v_mfma_f32_16x16x32_bf16 v[102:105], v[166:169], v[218:221], v[102:105]
	v_mfma_f32_16x16x32_bf16 v[94:97], v[174:177], v[218:221], v[94:97]
	v_mfma_f32_16x16x32_bf16 v[94:97], v[170:173], v[214:217], v[94:97]
	v_mfma_f32_16x16x32_bf16 v[82:85], v[178:181], v[214:217], v[82:85]
	v_mfma_f32_16x16x32_bf16 v[82:85], v[182:185], v[218:221], v[82:85]
	v_mfma_f32_16x16x32_bf16 v[74:77], v[190:193], v[218:221], v[74:77]
	v_mfma_f32_16x16x32_bf16 v[74:77], v[186:189], v[214:217], v[74:77]
	v_mfma_f32_16x16x32_bf16 v[66:69], v[186:189], v[222:225], v[66:69]
	v_mfma_f32_16x16x32_bf16 v[66:69], v[190:193], v[226:229], v[66:69]
	v_mfma_f32_16x16x32_bf16 v[70:73], v[182:185], v[226:229], v[70:73]
	v_mfma_f32_16x16x32_bf16 v[70:73], v[178:181], v[222:225], v[70:73]
	v_mfma_f32_16x16x32_bf16 v[78:81], v[170:173], v[222:225], v[78:81]
	v_mfma_f32_16x16x32_bf16 v[78:81], v[174:177], v[226:229], v[78:81]
	v_mfma_f32_16x16x32_bf16 v[86:89], v[166:169], v[226:229], v[86:89]
	v_mfma_f32_16x16x32_bf16 v[86:89], v[156:159], v[222:225], v[86:89]
	s_setprio 0
	s_barrier
	s_add_i32 s36, s68, s38
	v_lshl_add_u64 v[160:161], s[58:59], 0, v[136:137]
	s_mov_b32 m0, s36
	ds_read_b128 v[194:197], v155 offset:16384
	ds_read_b128 v[202:205], v155 offset:17408
	ds_read_b128 v[206:209], v155 offset:18432
	ds_read_b128 v[210:213], v155 offset:19456
	ds_read_b128 v[214:217], v155 offset:20480
	ds_read_b128 v[218:221], v155 offset:21504
	ds_read_b128 v[222:225], v155 offset:22528
	ds_read_b128 v[226:229], v155 offset:23552
	global_load_lds_dwordx4 v[160:161], off
	s_add_i32 m0, s36, 0x2000
	s_add_u32 s80, s58, 0x100000
	v_lshl_add_u64 v[198:199], s[58:59], 0, v[132:133]
	s_addc_u32 s81, s59, 0
	s_add_i32 s36, s69, s38
	global_load_lds_dwordx4 v[198:199], off
	v_lshl_add_u64 v[230:231], s[80:81], 0, v[136:137]
	s_mov_b32 m0, s36
	v_lshl_add_u64 v[232:233], s[60:61], 0, v[134:135]
	global_load_lds_dwordx4 v[230:231], off
	v_lshl_add_u64 v[230:231], s[80:81], 0, v[132:133]
	s_add_i32 m0, s36, 0x2000
	s_nop 0
	global_load_lds_dwordx4 v[230:231], off
	v_lshl_add_u64 v[230:231], s[60:61], 0, v[138:139]
	s_mov_b32 m0, s55
	s_nop 0
	global_load_lds_dwordx4 v[230:231], off
	s_mov_b32 m0, s63
	s_nop 0
	global_load_lds_dwordx4 v[232:233], off
	s_waitcnt vmcnt(8)
	s_waitcnt lgkmcnt(0)
	s_barrier
	s_setprio 1
	s_waitcnt lgkmcnt(0)
	v_mfma_f32_16x16x32_bf16 v[62:65], v[156:159], v[194:197], v[62:65]
	v_mfma_f32_16x16x32_bf16 v[62:65], v[166:169], v[202:205], v[62:65]
	v_mfma_f32_16x16x32_bf16 v[58:61], v[174:177], v[202:205], v[58:61]
	v_mfma_f32_16x16x32_bf16 v[58:61], v[170:173], v[194:197], v[58:61]
	v_mfma_f32_16x16x32_bf16 v[50:53], v[178:181], v[194:197], v[50:53]
	v_mfma_f32_16x16x32_bf16 v[50:53], v[182:185], v[202:205], v[50:53]
	v_mfma_f32_16x16x32_bf16 v[42:45], v[190:193], v[202:205], v[42:45]
	v_mfma_f32_16x16x32_bf16 v[42:45], v[186:189], v[194:197], v[42:45]
	v_mfma_f32_16x16x32_bf16 v[26:29], v[186:189], v[206:209], v[26:29]
	v_mfma_f32_16x16x32_bf16 v[26:29], v[190:193], v[210:213], v[26:29]
	v_mfma_f32_16x16x32_bf16 v[34:37], v[182:185], v[210:213], v[34:37]
	v_mfma_f32_16x16x32_bf16 v[34:37], v[178:181], v[206:209], v[34:37]
	v_mfma_f32_16x16x32_bf16 v[46:49], v[170:173], v[206:209], v[46:49]
	v_mfma_f32_16x16x32_bf16 v[46:49], v[174:177], v[210:213], v[46:49]
	v_mfma_f32_16x16x32_bf16 v[54:57], v[166:169], v[210:213], v[54:57]
	v_mfma_f32_16x16x32_bf16 v[54:57], v[156:159], v[206:209], v[54:57]
	v_mfma_f32_16x16x32_bf16 v[38:41], v[156:159], v[214:217], v[38:41]
	v_mfma_f32_16x16x32_bf16 v[38:41], v[166:169], v[218:221], v[38:41]
	v_mfma_f32_16x16x32_bf16 v[30:33], v[174:177], v[218:221], v[30:33]
	v_mfma_f32_16x16x32_bf16 v[30:33], v[170:173], v[214:217], v[30:33]
	v_mfma_f32_16x16x32_bf16 v[18:21], v[178:181], v[214:217], v[18:21]
	v_mfma_f32_16x16x32_bf16 v[18:21], v[182:185], v[218:221], v[18:21]
	v_mfma_f32_16x16x32_bf16 v[10:13], v[190:193], v[218:221], v[10:13]
	v_mfma_f32_16x16x32_bf16 v[10:13], v[186:189], v[214:217], v[10:13]
	v_mfma_f32_16x16x32_bf16 v[2:5], v[186:189], v[222:225], v[2:5]
	v_mfma_f32_16x16x32_bf16 v[2:5], v[190:193], v[226:229], v[2:5]
	v_mfma_f32_16x16x32_bf16 v[6:9], v[182:185], v[226:229], v[6:9]
	v_mfma_f32_16x16x32_bf16 v[6:9], v[178:181], v[222:225], v[6:9]
	v_mfma_f32_16x16x32_bf16 v[14:17], v[170:173], v[222:225], v[14:17]
	v_mfma_f32_16x16x32_bf16 v[14:17], v[174:177], v[226:229], v[14:17]
	v_mfma_f32_16x16x32_bf16 v[22:25], v[166:169], v[226:229], v[22:25]
	v_mfma_f32_16x16x32_bf16 v[22:25], v[156:159], v[222:225], v[22:25]
	s_setprio 0
	s_barrier
	s_add_i32 s36, 0, 0x18000
	v_add_u32_e32 v165, s36, v151
	s_add_i32 s37, 0, 0x1c000
	ds_read_b128 v[156:159], v165
	ds_read_b128 v[166:169], v165 offset:1024
	ds_read_b128 v[170:173], v165 offset:2048
	ds_read_b128 v[174:177], v165 offset:3072
	v_add_u32_e32 v165, s37, v151
	ds_read_b128 v[178:181], v165
	ds_read_b128 v[182:185], v165 offset:1024
	ds_read_b128 v[186:189], v165 offset:2048
	ds_read_b128 v[190:193], v165 offset:3072
	s_add_u32 s60, s60, 0x100000
	s_addc_u32 s61, s61, 0
	s_mov_b32 m0, s64
	v_lshl_add_u64 v[234:235], s[60:61], 0, v[138:139]
	ds_read_b128 v[194:197], v155 offset:32768
	ds_read_b128 v[202:205], v155 offset:33792
	ds_read_b128 v[206:209], v155 offset:34816
	ds_read_b128 v[210:213], v155 offset:35840
	ds_read_b128 v[214:217], v155 offset:36864
	ds_read_b128 v[218:221], v155 offset:37888
	ds_read_b128 v[222:225], v155 offset:38912
	ds_read_b128 v[226:229], v155 offset:39936
	global_load_lds_dwordx4 v[234:235], off
	v_lshl_add_u64 v[234:235], s[60:61], 0, v[134:135]
	s_mov_b32 m0, s65
	s_nop 0
	global_load_lds_dwordx4 v[234:235], off
	s_waitcnt vmcnt(8)
	s_waitcnt lgkmcnt(0)
	s_barrier
	s_setprio 1
	s_waitcnt lgkmcnt(0)
	v_mfma_f32_16x16x32_bf16 v[126:129], v[156:159], v[194:197], v[126:129]
	v_mfma_f32_16x16x32_bf16 v[126:129], v[166:169], v[202:205], v[126:129]
	v_mfma_f32_16x16x32_bf16 v[122:125], v[174:177], v[202:205], v[122:125]
	v_mfma_f32_16x16x32_bf16 v[122:125], v[170:173], v[194:197], v[122:125]
	v_mfma_f32_16x16x32_bf16 v[114:117], v[178:181], v[194:197], v[114:117]
	v_mfma_f32_16x16x32_bf16 v[114:117], v[182:185], v[202:205], v[114:117]
	v_mfma_f32_16x16x32_bf16 v[106:109], v[190:193], v[202:205], v[106:109]
	v_mfma_f32_16x16x32_bf16 v[106:109], v[186:189], v[194:197], v[106:109]
	v_mfma_f32_16x16x32_bf16 v[90:93], v[186:189], v[206:209], v[90:93]
	v_mfma_f32_16x16x32_bf16 v[90:93], v[190:193], v[210:213], v[90:93]
	v_mfma_f32_16x16x32_bf16 v[98:101], v[182:185], v[210:213], v[98:101]
	v_mfma_f32_16x16x32_bf16 v[98:101], v[178:181], v[206:209], v[98:101]
	v_mfma_f32_16x16x32_bf16 v[110:113], v[170:173], v[206:209], v[110:113]
	v_mfma_f32_16x16x32_bf16 v[110:113], v[174:177], v[210:213], v[110:113]
	v_mfma_f32_16x16x32_bf16 v[118:121], v[166:169], v[210:213], v[118:121]
	v_mfma_f32_16x16x32_bf16 v[118:121], v[156:159], v[206:209], v[118:121]
	v_mfma_f32_16x16x32_bf16 v[102:105], v[156:159], v[214:217], v[102:105]
	v_mfma_f32_16x16x32_bf16 v[102:105], v[166:169], v[218:221], v[102:105]
	v_mfma_f32_16x16x32_bf16 v[94:97], v[174:177], v[218:221], v[94:97]
	v_mfma_f32_16x16x32_bf16 v[94:97], v[170:173], v[214:217], v[94:97]
	v_mfma_f32_16x16x32_bf16 v[82:85], v[178:181], v[214:217], v[82:85]
	v_mfma_f32_16x16x32_bf16 v[82:85], v[182:185], v[218:221], v[82:85]
	v_mfma_f32_16x16x32_bf16 v[74:77], v[190:193], v[218:221], v[74:77]
	v_mfma_f32_16x16x32_bf16 v[74:77], v[186:189], v[214:217], v[74:77]
	v_mfma_f32_16x16x32_bf16 v[66:69], v[186:189], v[222:225], v[66:69]
	v_mfma_f32_16x16x32_bf16 v[66:69], v[190:193], v[226:229], v[66:69]
	v_mfma_f32_16x16x32_bf16 v[70:73], v[182:185], v[226:229], v[70:73]
	v_mfma_f32_16x16x32_bf16 v[70:73], v[178:181], v[222:225], v[70:73]
	v_mfma_f32_16x16x32_bf16 v[78:81], v[170:173], v[222:225], v[78:81]
	v_mfma_f32_16x16x32_bf16 v[78:81], v[174:177], v[226:229], v[78:81]
	v_mfma_f32_16x16x32_bf16 v[86:89], v[166:169], v[226:229], v[86:89]
	v_mfma_f32_16x16x32_bf16 v[86:89], v[156:159], v[222:225], v[86:89]
	s_setprio 0
	s_barrier
	s_add_i32 s36, s36, s38
	v_lshl_add_u64 v[160:161], v[160:161], 0, s[16:17]
	s_mov_b32 m0, s36
	ds_read_b128 v[194:197], v155 offset:49152
	ds_read_b128 v[202:205], v155 offset:50176
	ds_read_b128 v[206:209], v155 offset:51200
	ds_read_b128 v[210:213], v155 offset:52224
	ds_read_b128 v[214:217], v155 offset:53248
	ds_read_b128 v[218:221], v155 offset:54272
	ds_read_b128 v[222:225], v155 offset:55296
	ds_read_b128 v[226:229], v155 offset:56320
	global_load_lds_dwordx4 v[160:161], off
	s_add_i32 m0, s36, 0x2000
	s_add_u32 s58, s58, 0x100080
	v_lshl_add_u64 v[160:161], v[198:199], 0, s[16:17]
	s_addc_u32 s59, s59, 0
	s_add_i32 s36, s37, s38
	global_load_lds_dwordx4 v[160:161], off
	v_lshl_add_u64 v[160:161], s[58:59], 0, v[136:137]
	s_mov_b32 m0, s36
	s_nop 0
	global_load_lds_dwordx4 v[160:161], off
	v_lshl_add_u64 v[160:161], s[58:59], 0, v[132:133]
	s_add_i32 m0, s36, 0x2000
	s_nop 0
	global_load_lds_dwordx4 v[160:161], off
	v_lshl_add_u64 v[160:161], v[230:231], 0, s[16:17]
	s_mov_b32 m0, s66
	s_nop 0
	global_load_lds_dwordx4 v[160:161], off
	v_lshl_add_u64 v[160:161], v[232:233], 0, s[16:17]
	s_mov_b32 m0, s67
	s_nop 0
	global_load_lds_dwordx4 v[160:161], off
	s_waitcnt vmcnt(8)
	s_waitcnt lgkmcnt(0)
	s_barrier
	s_setprio 1
	s_waitcnt lgkmcnt(0)
	v_mfma_f32_16x16x32_bf16 v[62:65], v[156:159], v[194:197], v[62:65]
	v_mfma_f32_16x16x32_bf16 v[62:65], v[166:169], v[202:205], v[62:65]
	v_mfma_f32_16x16x32_bf16 v[58:61], v[174:177], v[202:205], v[58:61]
	v_mfma_f32_16x16x32_bf16 v[58:61], v[170:173], v[194:197], v[58:61]
	v_mfma_f32_16x16x32_bf16 v[50:53], v[178:181], v[194:197], v[50:53]
	v_mfma_f32_16x16x32_bf16 v[50:53], v[182:185], v[202:205], v[50:53]
	v_mfma_f32_16x16x32_bf16 v[42:45], v[190:193], v[202:205], v[42:45]
	v_mfma_f32_16x16x32_bf16 v[42:45], v[186:189], v[194:197], v[42:45]
	v_mfma_f32_16x16x32_bf16 v[26:29], v[186:189], v[206:209], v[26:29]
	v_mfma_f32_16x16x32_bf16 v[26:29], v[190:193], v[210:213], v[26:29]
	v_mfma_f32_16x16x32_bf16 v[34:37], v[182:185], v[210:213], v[34:37]
	v_mfma_f32_16x16x32_bf16 v[34:37], v[178:181], v[206:209], v[34:37]
	v_mfma_f32_16x16x32_bf16 v[46:49], v[170:173], v[206:209], v[46:49]
	v_mfma_f32_16x16x32_bf16 v[46:49], v[174:177], v[210:213], v[46:49]
	v_mfma_f32_16x16x32_bf16 v[54:57], v[166:169], v[210:213], v[54:57]
	v_mfma_f32_16x16x32_bf16 v[54:57], v[156:159], v[206:209], v[54:57]
	v_mfma_f32_16x16x32_bf16 v[38:41], v[156:159], v[214:217], v[38:41]
	v_mfma_f32_16x16x32_bf16 v[38:41], v[166:169], v[218:221], v[38:41]
	v_mfma_f32_16x16x32_bf16 v[30:33], v[174:177], v[218:221], v[30:33]
	v_mfma_f32_16x16x32_bf16 v[30:33], v[170:173], v[214:217], v[30:33]
	v_mfma_f32_16x16x32_bf16 v[18:21], v[178:181], v[214:217], v[18:21]
	v_mfma_f32_16x16x32_bf16 v[18:21], v[182:185], v[218:221], v[18:21]
	v_mfma_f32_16x16x32_bf16 v[10:13], v[190:193], v[218:221], v[10:13]
	v_mfma_f32_16x16x32_bf16 v[10:13], v[186:189], v[214:217], v[10:13]
	v_mfma_f32_16x16x32_bf16 v[2:5], v[186:189], v[222:225], v[2:5]
	v_mfma_f32_16x16x32_bf16 v[2:5], v[190:193], v[226:229], v[2:5]
	v_mfma_f32_16x16x32_bf16 v[6:9], v[182:185], v[226:229], v[6:9]
	v_mfma_f32_16x16x32_bf16 v[6:9], v[178:181], v[222:225], v[6:9]
	v_mfma_f32_16x16x32_bf16 v[14:17], v[170:173], v[222:225], v[14:17]
	v_mfma_f32_16x16x32_bf16 v[14:17], v[174:177], v[226:229], v[14:17]
	v_mfma_f32_16x16x32_bf16 v[22:25], v[166:169], v[226:229], v[22:25]
	v_mfma_f32_16x16x32_bf16 v[22:25], v[156:159], v[222:225], v[22:25]
	s_setprio 0
	s_barrier
	s_add_i32 s78, s78, 2
	s_add_u32 s56, s56, 0x100
	s_addc_u32 s57, s57, 0
	s_add_u32 s76, s76, 0x100
	s_addc_u32 s77, s77, 0
	s_cmp_gt_u32 s78, 61
	s_cbranch_scc0 .LBB0_1685
	s_and_b64 vcc, exec, s[18:19]
	s_cbranch_vccz .LBB0_1688
	s_barrier

.LBB0_1701:
	s_add_u32 s36, s56, s44
	s_addc_u32 s37, s57, 0
	s_add_u32 s64, s36, 0x100
	s_addc_u32 s65, s37, 0
	s_and_b64 s[62:63], s[60:61], exec
	s_cselect_b32 s65, s21, s65
	s_cselect_b32 s64, s86, s64
	s_add_u32 s44, s54, s44
	s_addc_u32 s62, s55, 0
	s_add_u32 s44, s44, 0x100
	s_addc_u32 s62, s62, 0
	s_and_b64 s[60:61], s[60:61], exec
	s_cselect_b32 s67, s25, s62
	s_cselect_b32 s66, s87, s44
	s_add_u32 s70, s36, 0x10080
	s_addc_u32 s71, s37, 0
	s_add_i32 s97, s81, s39
	ds_read_b128 v[152:155], v147
	ds_read_b128 v[156:159], v147 offset:1024
	ds_read_b128 v[166:169], v147 offset:2048
	ds_read_b128 v[170:173], v147 offset:3072
	ds_read_b128 v[174:177], v150
	ds_read_b128 v[178:181], v150 offset:1024
	ds_read_b128 v[182:185], v150 offset:2048
	ds_read_b128 v[186:189], v150 offset:3072
	s_add_i32 m0, s74, 0xc000
	s_add_i32 vcc_lo, s74, 0xe000
	s_add_i32 s94, s97, 0x2000
	s_add_u32 s68, s66, 0x10000
	s_addc_u32 s69, s67, 0
	s_add_i32 s96, s82, s39
	s_add_i32 s95, s96, 0x2000
	s_add_i32 s93, 0, 0x18000
	s_add_i32 s92, 0, 0x1c000
	s_add_u32 s62, s64, 0x10000
	s_addc_u32 s63, s65, 0
	s_add_i32 s91, s93, s39
	s_add_i32 s89, s91, 0x2000
	s_add_u32 s60, s66, 0x10080
	s_addc_u32 s61, s67, 0
	s_add_i32 s90, s92, s39
	s_add_i32 s44, s90, 0x2000
	v_lshl_add_u64 v[160:161], s[70:71], 0, v[138:139]
	ds_read_b128 v[190:193], v151
	ds_read_b128 v[194:197], v151 offset:1024
	ds_read_b128 v[202:205], v151 offset:2048
	ds_read_b128 v[206:209], v151 offset:3072
	ds_read_b128 v[210:213], v151 offset:4096
	ds_read_b128 v[214:217], v151 offset:5120
	ds_read_b128 v[218:221], v151 offset:6144
	ds_read_b128 v[222:225], v151 offset:7168
	global_load_lds_dwordx4 v[160:161], off
	v_lshl_add_u64 v[160:161], s[70:71], 0, v[134:135]
	s_mov_b32 m0, vcc_lo
	s_nop 0
	global_load_lds_dwordx4 v[160:161], off
	s_waitcnt vmcnt(8)
	s_waitcnt lgkmcnt(0)
	s_barrier
	s_setprio 1
	s_waitcnt lgkmcnt(0)
	v_mfma_f32_16x16x32_bf16 v[126:129], v[152:155], v[190:193], v[126:129]
	v_mfma_f32_16x16x32_bf16 v[126:129], v[156:159], v[194:197], v[126:129]
	v_mfma_f32_16x16x32_bf16 v[122:125], v[170:173], v[194:197], v[122:125]
	v_mfma_f32_16x16x32_bf16 v[122:125], v[166:169], v[190:193], v[122:125]
	v_mfma_f32_16x16x32_bf16 v[114:117], v[174:177], v[190:193], v[114:117]
	v_mfma_f32_16x16x32_bf16 v[114:117], v[178:181], v[194:197], v[114:117]
	v_mfma_f32_16x16x32_bf16 v[106:109], v[186:189], v[194:197], v[106:109]
	v_mfma_f32_16x16x32_bf16 v[106:109], v[182:185], v[190:193], v[106:109]
	v_mfma_f32_16x16x32_bf16 v[90:93], v[182:185], v[202:205], v[90:93]
	v_mfma_f32_16x16x32_bf16 v[90:93], v[186:189], v[206:209], v[90:93]
	v_mfma_f32_16x16x32_bf16 v[98:101], v[178:181], v[206:209], v[98:101]
	v_mfma_f32_16x16x32_bf16 v[98:101], v[174:177], v[202:205], v[98:101]
	v_mfma_f32_16x16x32_bf16 v[110:113], v[166:169], v[202:205], v[110:113]
	v_mfma_f32_16x16x32_bf16 v[110:113], v[170:173], v[206:209], v[110:113]
	v_mfma_f32_16x16x32_bf16 v[118:121], v[156:159], v[206:209], v[118:121]
	v_mfma_f32_16x16x32_bf16 v[118:121], v[152:155], v[202:205], v[118:121]
	v_mfma_f32_16x16x32_bf16 v[102:105], v[152:155], v[210:213], v[102:105]
	v_mfma_f32_16x16x32_bf16 v[102:105], v[156:159], v[214:217], v[102:105]
	v_mfma_f32_16x16x32_bf16 v[94:97], v[170:173], v[214:217], v[94:97]
	v_mfma_f32_16x16x32_bf16 v[94:97], v[166:169], v[210:213], v[94:97]
	v_mfma_f32_16x16x32_bf16 v[82:85], v[174:177], v[210:213], v[82:85]
	v_mfma_f32_16x16x32_bf16 v[82:85], v[178:181], v[214:217], v[82:85]
	v_mfma_f32_16x16x32_bf16 v[74:77], v[186:189], v[214:217], v[74:77]
	v_mfma_f32_16x16x32_bf16 v[74:77], v[182:185], v[210:213], v[74:77]
	v_mfma_f32_16x16x32_bf16 v[66:69], v[182:185], v[218:221], v[66:69]
	v_mfma_f32_16x16x32_bf16 v[66:69], v[186:189], v[222:225], v[66:69]
	v_mfma_f32_16x16x32_bf16 v[70:73], v[178:181], v[222:225], v[70:73]
	v_mfma_f32_16x16x32_bf16 v[70:73], v[174:177], v[218:221], v[70:73]
	v_mfma_f32_16x16x32_bf16 v[78:81], v[166:169], v[218:221], v[78:81]
	v_mfma_f32_16x16x32_bf16 v[78:81], v[170:173], v[222:225], v[78:81]
	v_mfma_f32_16x16x32_bf16 v[86:89], v[156:159], v[222:225], v[86:89]
	v_mfma_f32_16x16x32_bf16 v[86:89], v[152:155], v[218:221], v[86:89]
	s_setprio 0
	s_barrier
	s_mov_b32 m0, s97
	v_lshl_add_u64 v[160:161], s[66:67], 0, v[136:137]
	ds_read_b128 v[190:193], v151 offset:16384
	ds_read_b128 v[194:197], v151 offset:17408
	ds_read_b128 v[202:205], v151 offset:18432
	ds_read_b128 v[206:209], v151 offset:19456
	ds_read_b128 v[210:213], v151 offset:20480
	ds_read_b128 v[214:217], v151 offset:21504
	ds_read_b128 v[218:221], v151 offset:22528
	ds_read_b128 v[222:225], v151 offset:23552
	global_load_lds_dwordx4 v[160:161], off
	v_lshl_add_u64 v[198:199], s[66:67], 0, v[132:133]
	s_mov_b32 m0, s94
	v_lshl_add_u64 v[226:227], s[68:69], 0, v[136:137]
	global_load_lds_dwordx4 v[198:199], off
	s_mov_b32 m0, s96
	v_lshl_add_u64 v[228:229], s[64:65], 0, v[134:135]
	global_load_lds_dwordx4 v[226:227], off
	v_lshl_add_u64 v[226:227], s[68:69], 0, v[132:133]
	s_mov_b32 m0, s95
	s_nop 0
	global_load_lds_dwordx4 v[226:227], off
	v_lshl_add_u64 v[226:227], s[64:65], 0, v[138:139]
	s_mov_b32 m0, s74
	s_nop 0
	global_load_lds_dwordx4 v[226:227], off
	s_mov_b32 m0, s75
	s_nop 0
	global_load_lds_dwordx4 v[228:229], off
	s_waitcnt vmcnt(8)
	s_waitcnt lgkmcnt(0)
	s_barrier
	s_setprio 1
	s_waitcnt lgkmcnt(0)
	v_mfma_f32_16x16x32_bf16 v[62:65], v[152:155], v[190:193], v[62:65]
	v_mfma_f32_16x16x32_bf16 v[62:65], v[156:159], v[194:197], v[62:65]
	v_mfma_f32_16x16x32_bf16 v[58:61], v[170:173], v[194:197], v[58:61]
	v_mfma_f32_16x16x32_bf16 v[58:61], v[166:169], v[190:193], v[58:61]
	v_mfma_f32_16x16x32_bf16 v[50:53], v[174:177], v[190:193], v[50:53]
	v_mfma_f32_16x16x32_bf16 v[50:53], v[178:181], v[194:197], v[50:53]
	v_mfma_f32_16x16x32_bf16 v[42:45], v[186:189], v[194:197], v[42:45]
	v_mfma_f32_16x16x32_bf16 v[42:45], v[182:185], v[190:193], v[42:45]
	v_mfma_f32_16x16x32_bf16 v[26:29], v[182:185], v[202:205], v[26:29]
	v_mfma_f32_16x16x32_bf16 v[26:29], v[186:189], v[206:209], v[26:29]
	v_mfma_f32_16x16x32_bf16 v[34:37], v[178:181], v[206:209], v[34:37]
	v_mfma_f32_16x16x32_bf16 v[34:37], v[174:177], v[202:205], v[34:37]
	v_mfma_f32_16x16x32_bf16 v[46:49], v[166:169], v[202:205], v[46:49]
	v_mfma_f32_16x16x32_bf16 v[46:49], v[170:173], v[206:209], v[46:49]
	v_mfma_f32_16x16x32_bf16 v[54:57], v[156:159], v[206:209], v[54:57]
	v_mfma_f32_16x16x32_bf16 v[54:57], v[152:155], v[202:205], v[54:57]
	v_mfma_f32_16x16x32_bf16 v[38:41], v[152:155], v[210:213], v[38:41]
	v_mfma_f32_16x16x32_bf16 v[38:41], v[156:159], v[214:217], v[38:41]
	v_mfma_f32_16x16x32_bf16 v[30:33], v[170:173], v[214:217], v[30:33]
	v_mfma_f32_16x16x32_bf16 v[30:33], v[166:169], v[210:213], v[30:33]
	v_mfma_f32_16x16x32_bf16 v[18:21], v[174:177], v[210:213], v[18:21]
	v_mfma_f32_16x16x32_bf16 v[18:21], v[178:181], v[214:217], v[18:21]
	v_mfma_f32_16x16x32_bf16 v[10:13], v[186:189], v[214:217], v[10:13]
	v_mfma_f32_16x16x32_bf16 v[10:13], v[182:185], v[210:213], v[10:13]
	v_mfma_f32_16x16x32_bf16 v[2:5], v[182:185], v[218:221], v[2:5]
	v_mfma_f32_16x16x32_bf16 v[2:5], v[186:189], v[222:225], v[2:5]
	v_mfma_f32_16x16x32_bf16 v[6:9], v[178:181], v[222:225], v[6:9]
	v_mfma_f32_16x16x32_bf16 v[6:9], v[174:177], v[218:221], v[6:9]
	v_mfma_f32_16x16x32_bf16 v[14:17], v[166:169], v[218:221], v[14:17]
	v_mfma_f32_16x16x32_bf16 v[14:17], v[170:173], v[222:225], v[14:17]
	v_mfma_f32_16x16x32_bf16 v[22:25], v[156:159], v[222:225], v[22:25]
	v_mfma_f32_16x16x32_bf16 v[22:25], v[152:155], v[218:221], v[22:25]
	s_setprio 0
	s_barrier
	v_add_u32_e32 v165, s93, v145
	ds_read_b128 v[152:155], v165
	ds_read_b128 v[156:159], v165 offset:1024
	ds_read_b128 v[166:169], v165 offset:2048
	ds_read_b128 v[170:173], v165 offset:3072
	v_add_u32_e32 v165, s92, v145
	ds_read_b128 v[174:177], v165
	ds_read_b128 v[178:181], v165 offset:1024
	ds_read_b128 v[182:185], v165 offset:2048
	ds_read_b128 v[186:189], v165 offset:3072
	s_mov_b32 m0, s76
	v_lshl_add_u64 v[230:231], s[62:63], 0, v[138:139]
	ds_read_b128 v[190:193], v151 offset:32768
	ds_read_b128 v[194:197], v151 offset:33792
	ds_read_b128 v[202:205], v151 offset:34816
	ds_read_b128 v[206:209], v151 offset:35840
	ds_read_b128 v[210:213], v151 offset:36864
	ds_read_b128 v[214:217], v151 offset:37888
	ds_read_b128 v[218:221], v151 offset:38912
	ds_read_b128 v[222:225], v151 offset:39936
	global_load_lds_dwordx4 v[230:231], off
	v_lshl_add_u64 v[230:231], s[62:63], 0, v[134:135]
	s_mov_b32 m0, s77
	s_nop 0
	global_load_lds_dwordx4 v[230:231], off
	s_waitcnt vmcnt(8)
	s_waitcnt lgkmcnt(0)
	s_barrier
	s_setprio 1
	s_waitcnt lgkmcnt(0)
	v_mfma_f32_16x16x32_bf16 v[126:129], v[152:155], v[190:193], v[126:129]
	v_mfma_f32_16x16x32_bf16 v[126:129], v[156:159], v[194:197], v[126:129]
	v_mfma_f32_16x16x32_bf16 v[122:125], v[170:173], v[194:197], v[122:125]
	v_mfma_f32_16x16x32_bf16 v[122:125], v[166:169], v[190:193], v[122:125]
	v_mfma_f32_16x16x32_bf16 v[114:117], v[174:177], v[190:193], v[114:117]
	v_mfma_f32_16x16x32_bf16 v[114:117], v[178:181], v[194:197], v[114:117]
	v_mfma_f32_16x16x32_bf16 v[106:109], v[186:189], v[194:197], v[106:109]
	v_mfma_f32_16x16x32_bf16 v[106:109], v[182:185], v[190:193], v[106:109]
	v_mfma_f32_16x16x32_bf16 v[90:93], v[182:185], v[202:205], v[90:93]
	v_mfma_f32_16x16x32_bf16 v[90:93], v[186:189], v[206:209], v[90:93]
	v_mfma_f32_16x16x32_bf16 v[98:101], v[178:181], v[206:209], v[98:101]
	v_mfma_f32_16x16x32_bf16 v[98:101], v[174:177], v[202:205], v[98:101]
	v_mfma_f32_16x16x32_bf16 v[110:113], v[166:169], v[202:205], v[110:113]
	v_mfma_f32_16x16x32_bf16 v[110:113], v[170:173], v[206:209], v[110:113]
	v_mfma_f32_16x16x32_bf16 v[118:121], v[156:159], v[206:209], v[118:121]
	v_mfma_f32_16x16x32_bf16 v[118:121], v[152:155], v[202:205], v[118:121]
	v_mfma_f32_16x16x32_bf16 v[102:105], v[152:155], v[210:213], v[102:105]
	v_mfma_f32_16x16x32_bf16 v[102:105], v[156:159], v[214:217], v[102:105]
	v_mfma_f32_16x16x32_bf16 v[94:97], v[170:173], v[214:217], v[94:97]
	v_mfma_f32_16x16x32_bf16 v[94:97], v[166:169], v[210:213], v[94:97]
	v_mfma_f32_16x16x32_bf16 v[82:85], v[174:177], v[210:213], v[82:85]
	v_mfma_f32_16x16x32_bf16 v[82:85], v[178:181], v[214:217], v[82:85]
	v_mfma_f32_16x16x32_bf16 v[74:77], v[186:189], v[214:217], v[74:77]
	v_mfma_f32_16x16x32_bf16 v[74:77], v[182:185], v[210:213], v[74:77]
	v_mfma_f32_16x16x32_bf16 v[66:69], v[182:185], v[218:221], v[66:69]
	v_mfma_f32_16x16x32_bf16 v[66:69], v[186:189], v[222:225], v[66:69]
	v_mfma_f32_16x16x32_bf16 v[70:73], v[178:181], v[222:225], v[70:73]
	v_mfma_f32_16x16x32_bf16 v[70:73], v[174:177], v[218:221], v[70:73]
	v_mfma_f32_16x16x32_bf16 v[78:81], v[166:169], v[218:221], v[78:81]
	v_mfma_f32_16x16x32_bf16 v[78:81], v[170:173], v[222:225], v[78:81]
	v_mfma_f32_16x16x32_bf16 v[86:89], v[156:159], v[222:225], v[86:89]
	v_mfma_f32_16x16x32_bf16 v[86:89], v[152:155], v[218:221], v[86:89]
	s_setprio 0
	s_barrier
	s_mov_b32 m0, s91
	v_lshl_add_u64 v[160:161], v[160:161], 0, s[14:15]
	ds_read_b128 v[190:193], v151 offset:49152
	ds_read_b128 v[194:197], v151 offset:50176
	ds_read_b128 v[202:205], v151 offset:51200
	ds_read_b128 v[206:209], v151 offset:52224
	ds_read_b128 v[210:213], v151 offset:53248
	ds_read_b128 v[214:217], v151 offset:54272
	ds_read_b128 v[218:221], v151 offset:55296
	ds_read_b128 v[222:225], v151 offset:56320
	global_load_lds_dwordx4 v[160:161], off
	v_lshl_add_u64 v[160:161], v[198:199], 0, s[14:15]
	s_mov_b32 m0, s89
	s_nop 0
	global_load_lds_dwordx4 v[160:161], off
	v_lshl_add_u64 v[160:161], s[60:61], 0, v[136:137]
	s_mov_b32 m0, s90
	s_nop 0
	global_load_lds_dwordx4 v[160:161], off
	v_lshl_add_u64 v[160:161], s[60:61], 0, v[132:133]
	s_mov_b32 m0, s44
	s_nop 0
	global_load_lds_dwordx4 v[160:161], off
	v_lshl_add_u64 v[160:161], v[226:227], 0, s[14:15]
	s_mov_b32 m0, s79
	s_nop 0
	global_load_lds_dwordx4 v[160:161], off
	v_lshl_add_u64 v[160:161], v[228:229], 0, s[14:15]
	s_mov_b32 m0, s80
	s_nop 0
	global_load_lds_dwordx4 v[160:161], off
	s_waitcnt vmcnt(8)
	s_waitcnt lgkmcnt(0)
	s_barrier
	s_setprio 1
	s_waitcnt lgkmcnt(0)
	v_mfma_f32_16x16x32_bf16 v[62:65], v[152:155], v[190:193], v[62:65]
	v_mfma_f32_16x16x32_bf16 v[62:65], v[156:159], v[194:197], v[62:65]
	v_mfma_f32_16x16x32_bf16 v[58:61], v[170:173], v[194:197], v[58:61]
	v_mfma_f32_16x16x32_bf16 v[58:61], v[166:169], v[190:193], v[58:61]
	v_mfma_f32_16x16x32_bf16 v[50:53], v[174:177], v[190:193], v[50:53]
	v_mfma_f32_16x16x32_bf16 v[50:53], v[178:181], v[194:197], v[50:53]
	v_mfma_f32_16x16x32_bf16 v[42:45], v[186:189], v[194:197], v[42:45]
	v_mfma_f32_16x16x32_bf16 v[42:45], v[182:185], v[190:193], v[42:45]
	v_mfma_f32_16x16x32_bf16 v[26:29], v[182:185], v[202:205], v[26:29]
	v_mfma_f32_16x16x32_bf16 v[26:29], v[186:189], v[206:209], v[26:29]
	v_mfma_f32_16x16x32_bf16 v[34:37], v[178:181], v[206:209], v[34:37]
	v_mfma_f32_16x16x32_bf16 v[34:37], v[174:177], v[202:205], v[34:37]
	v_mfma_f32_16x16x32_bf16 v[46:49], v[166:169], v[202:205], v[46:49]
	v_mfma_f32_16x16x32_bf16 v[46:49], v[170:173], v[206:209], v[46:49]
	v_mfma_f32_16x16x32_bf16 v[54:57], v[156:159], v[206:209], v[54:57]
	v_mfma_f32_16x16x32_bf16 v[54:57], v[152:155], v[202:205], v[54:57]
	v_mfma_f32_16x16x32_bf16 v[38:41], v[152:155], v[210:213], v[38:41]
	v_mfma_f32_16x16x32_bf16 v[38:41], v[156:159], v[214:217], v[38:41]
	v_mfma_f32_16x16x32_bf16 v[30:33], v[170:173], v[214:217], v[30:33]
	v_mfma_f32_16x16x32_bf16 v[30:33], v[166:169], v[210:213], v[30:33]
	v_mfma_f32_16x16x32_bf16 v[18:21], v[174:177], v[210:213], v[18:21]
	v_mfma_f32_16x16x32_bf16 v[18:21], v[178:181], v[214:217], v[18:21]
	v_mfma_f32_16x16x32_bf16 v[10:13], v[186:189], v[214:217], v[10:13]
	v_mfma_f32_16x16x32_bf16 v[10:13], v[182:185], v[210:213], v[10:13]
	v_mfma_f32_16x16x32_bf16 v[2:5], v[182:185], v[218:221], v[2:5]
	v_mfma_f32_16x16x32_bf16 v[2:5], v[186:189], v[222:225], v[2:5]
	v_mfma_f32_16x16x32_bf16 v[6:9], v[178:181], v[222:225], v[6:9]
	v_mfma_f32_16x16x32_bf16 v[6:9], v[174:177], v[218:221], v[6:9]
	v_mfma_f32_16x16x32_bf16 v[14:17], v[166:169], v[218:221], v[14:17]
	v_mfma_f32_16x16x32_bf16 v[14:17], v[170:173], v[222:225], v[14:17]
	v_mfma_f32_16x16x32_bf16 v[22:25], v[156:159], v[222:225], v[22:25]
	v_mfma_f32_16x16x32_bf16 v[22:25], v[152:155], v[218:221], v[22:25]
	s_setprio 0
	s_barrier
	s_movk_i32 s44, 0x100
	s_andn2_b64 vcc, exec, s[58:59]
	s_mov_b64 s[60:61], -1
	s_mov_b64 s[58:59], 0
	s_cbranch_vccz .LBB0_1701
	s_and_b64 vcc, exec, s[16:17]
	s_cbranch_vccz .LBB0_1704
	s_barrier

.LBB0_1902:
	ds_read_b128 v[148:151], v156
	ds_read_b128 v[166:169], v156 offset:1024
	ds_read_b128 v[170:173], v156 offset:2048
	ds_read_b128 v[174:177], v156 offset:3072
	ds_read_b128 v[178:181], v157
	ds_read_b128 v[182:185], v157 offset:1024
	ds_read_b128 v[186:189], v157 offset:2048
	ds_read_b128 v[190:193], v157 offset:3072
	s_add_i32 s92, s58, 2
	s_add_u32 s36, s56, 0xffd50080
	s_addc_u32 s37, s57, -1
	s_cmp_eq_u32 s89, s58
	s_cselect_b32 s58, s54, s90
	s_cselect_b32 s61, s53, s37
	s_cselect_b32 s60, s52, s36
	s_cselect_b32 s59, s55, s91
	v_lshl_add_u64 v[152:153], s[56:57], 0, v[142:143]
	s_add_i32 m0, s67, 0xc000
	ds_read_b128 v[194:197], v158
	ds_read_b128 v[202:205], v158 offset:1024
	ds_read_b128 v[206:209], v158 offset:2048
	ds_read_b128 v[210:213], v158 offset:3072
	ds_read_b128 v[214:217], v158 offset:4096
	ds_read_b128 v[218:221], v158 offset:5120
	ds_read_b128 v[222:225], v158 offset:6144
	ds_read_b128 v[226:229], v158 offset:7168
	global_load_lds_dwordx4 v[152:153], off
	v_lshl_add_u64 v[152:153], s[56:57], 0, v[144:145]
	s_add_i32 m0, s67, 0xe000
	s_nop 0
	global_load_lds_dwordx4 v[152:153], off
	s_waitcnt vmcnt(8)
	s_waitcnt lgkmcnt(0)
	s_barrier
	s_setprio 1
	s_waitcnt lgkmcnt(0)
	v_mfma_f32_16x16x32_bf16 v[126:129], v[148:151], v[194:197], v[126:129]
	v_mfma_f32_16x16x32_bf16 v[126:129], v[166:169], v[202:205], v[126:129]
	v_mfma_f32_16x16x32_bf16 v[122:125], v[174:177], v[202:205], v[122:125]
	v_mfma_f32_16x16x32_bf16 v[122:125], v[170:173], v[194:197], v[122:125]
	v_mfma_f32_16x16x32_bf16 v[118:121], v[178:181], v[194:197], v[118:121]
	v_mfma_f32_16x16x32_bf16 v[118:121], v[182:185], v[202:205], v[118:121]
	v_mfma_f32_16x16x32_bf16 v[114:117], v[190:193], v[202:205], v[114:117]
	v_mfma_f32_16x16x32_bf16 v[114:117], v[186:189], v[194:197], v[114:117]
	v_mfma_f32_16x16x32_bf16 v[98:101], v[186:189], v[206:209], v[98:101]
	v_mfma_f32_16x16x32_bf16 v[98:101], v[190:193], v[210:213], v[98:101]
	v_mfma_f32_16x16x32_bf16 v[102:105], v[182:185], v[210:213], v[102:105]
	v_mfma_f32_16x16x32_bf16 v[102:105], v[178:181], v[206:209], v[102:105]
	v_mfma_f32_16x16x32_bf16 v[106:109], v[170:173], v[206:209], v[106:109]
	v_mfma_f32_16x16x32_bf16 v[106:109], v[174:177], v[210:213], v[106:109]
	v_mfma_f32_16x16x32_bf16 v[110:113], v[166:169], v[210:213], v[110:113]
	v_mfma_f32_16x16x32_bf16 v[110:113], v[148:151], v[206:209], v[110:113]
	v_mfma_f32_16x16x32_bf16 v[94:97], v[148:151], v[214:217], v[94:97]
	v_mfma_f32_16x16x32_bf16 v[94:97], v[166:169], v[218:221], v[94:97]
	v_mfma_f32_16x16x32_bf16 v[90:93], v[174:177], v[218:221], v[90:93]
	v_mfma_f32_16x16x32_bf16 v[90:93], v[170:173], v[214:217], v[90:93]
	v_mfma_f32_16x16x32_bf16 v[86:89], v[178:181], v[214:217], v[86:89]
	v_mfma_f32_16x16x32_bf16 v[86:89], v[182:185], v[218:221], v[86:89]
	v_mfma_f32_16x16x32_bf16 v[82:85], v[190:193], v[218:221], v[82:85]
	v_mfma_f32_16x16x32_bf16 v[82:85], v[186:189], v[214:217], v[82:85]
	v_mfma_f32_16x16x32_bf16 v[66:69], v[186:189], v[222:225], v[66:69]
	v_mfma_f32_16x16x32_bf16 v[66:69], v[190:193], v[226:229], v[66:69]
	v_mfma_f32_16x16x32_bf16 v[70:73], v[182:185], v[226:229], v[70:73]
	v_mfma_f32_16x16x32_bf16 v[70:73], v[178:181], v[222:225], v[70:73]
	v_mfma_f32_16x16x32_bf16 v[74:77], v[170:173], v[222:225], v[74:77]
	v_mfma_f32_16x16x32_bf16 v[74:77], v[174:177], v[226:229], v[74:77]
	v_mfma_f32_16x16x32_bf16 v[78:81], v[166:169], v[226:229], v[78:81]
	v_mfma_f32_16x16x32_bf16 v[78:81], v[148:151], v[222:225], v[78:81]
	s_setprio 0
	s_barrier
	s_add_i32 s36, s77, s64
	v_lshl_add_u64 v[152:153], s[58:59], 0, v[134:135]
	s_mov_b32 m0, s36
	ds_read_b128 v[194:197], v158 offset:16384
	ds_read_b128 v[202:205], v158 offset:17408
	ds_read_b128 v[206:209], v158 offset:18432
	ds_read_b128 v[210:213], v158 offset:19456
	ds_read_b128 v[214:217], v158 offset:20480
	ds_read_b128 v[218:221], v158 offset:21504
	ds_read_b128 v[222:225], v158 offset:22528
	ds_read_b128 v[226:229], v158 offset:23552
	global_load_lds_dwordx4 v[152:153], off
	s_add_i32 m0, s36, 0x2000
	s_add_u32 s94, s58, 0x2b0000
	v_lshl_add_u64 v[160:161], s[58:59], 0, v[138:139]
	s_addc_u32 s95, s59, 0
	s_add_i32 s36, s78, s64
	global_load_lds_dwordx4 v[160:161], off
	v_lshl_add_u64 v[198:199], s[94:95], 0, v[134:135]
	s_mov_b32 m0, s36
	v_lshl_add_u64 v[230:231], s[60:61], 0, v[136:137]
	global_load_lds_dwordx4 v[198:199], off
	v_lshl_add_u64 v[198:199], s[94:95], 0, v[138:139]
	s_add_i32 m0, s36, 0x2000
	s_nop 0
	global_load_lds_dwordx4 v[198:199], off
	v_lshl_add_u64 v[198:199], s[60:61], 0, v[132:133]
	s_mov_b32 m0, s67
	s_nop 0
	global_load_lds_dwordx4 v[198:199], off
	s_mov_b32 m0, s68
	s_nop 0
	global_load_lds_dwordx4 v[230:231], off
	s_waitcnt vmcnt(8)
	s_waitcnt lgkmcnt(0)
	s_barrier
	s_setprio 1
	s_waitcnt lgkmcnt(0)
	v_mfma_f32_16x16x32_bf16 v[62:65], v[148:151], v[194:197], v[62:65]
	v_mfma_f32_16x16x32_bf16 v[62:65], v[166:169], v[202:205], v[62:65]
	v_mfma_f32_16x16x32_bf16 v[58:61], v[174:177], v[202:205], v[58:61]
	v_mfma_f32_16x16x32_bf16 v[58:61], v[170:173], v[194:197], v[58:61]
	v_mfma_f32_16x16x32_bf16 v[54:57], v[178:181], v[194:197], v[54:57]
	v_mfma_f32_16x16x32_bf16 v[54:57], v[182:185], v[202:205], v[54:57]
	v_mfma_f32_16x16x32_bf16 v[50:53], v[190:193], v[202:205], v[50:53]
	v_mfma_f32_16x16x32_bf16 v[50:53], v[186:189], v[194:197], v[50:53]
	v_mfma_f32_16x16x32_bf16 v[34:37], v[186:189], v[206:209], v[34:37]
	v_mfma_f32_16x16x32_bf16 v[34:37], v[190:193], v[210:213], v[34:37]
	v_mfma_f32_16x16x32_bf16 v[38:41], v[182:185], v[210:213], v[38:41]
	v_mfma_f32_16x16x32_bf16 v[38:41], v[178:181], v[206:209], v[38:41]
	v_mfma_f32_16x16x32_bf16 v[42:45], v[170:173], v[206:209], v[42:45]
	v_mfma_f32_16x16x32_bf16 v[42:45], v[174:177], v[210:213], v[42:45]
	v_mfma_f32_16x16x32_bf16 v[46:49], v[166:169], v[210:213], v[46:49]
	v_mfma_f32_16x16x32_bf16 v[46:49], v[148:151], v[206:209], v[46:49]
	v_mfma_f32_16x16x32_bf16 v[30:33], v[148:151], v[214:217], v[30:33]
	v_mfma_f32_16x16x32_bf16 v[30:33], v[166:169], v[218:221], v[30:33]
	v_mfma_f32_16x16x32_bf16 v[26:29], v[174:177], v[218:221], v[26:29]
	v_mfma_f32_16x16x32_bf16 v[26:29], v[170:173], v[214:217], v[26:29]
	v_mfma_f32_16x16x32_bf16 v[22:25], v[178:181], v[214:217], v[22:25]
	v_mfma_f32_16x16x32_bf16 v[22:25], v[182:185], v[218:221], v[22:25]
	v_mfma_f32_16x16x32_bf16 v[18:21], v[190:193], v[218:221], v[18:21]
	v_mfma_f32_16x16x32_bf16 v[18:21], v[186:189], v[214:217], v[18:21]
	v_mfma_f32_16x16x32_bf16 v[2:5], v[186:189], v[222:225], v[2:5]
	v_mfma_f32_16x16x32_bf16 v[2:5], v[190:193], v[226:229], v[2:5]
	v_mfma_f32_16x16x32_bf16 v[6:9], v[182:185], v[226:229], v[6:9]
	v_mfma_f32_16x16x32_bf16 v[6:9], v[178:181], v[222:225], v[6:9]
	v_mfma_f32_16x16x32_bf16 v[10:13], v[170:173], v[222:225], v[10:13]
	v_mfma_f32_16x16x32_bf16 v[10:13], v[174:177], v[226:229], v[10:13]
	v_mfma_f32_16x16x32_bf16 v[14:17], v[166:169], v[226:229], v[14:17]
	v_mfma_f32_16x16x32_bf16 v[14:17], v[148:151], v[222:225], v[14:17]
	s_setprio 0
	s_barrier
	s_add_i32 s36, 0, 0x18000
	v_add_u32_e32 v140, s36, v154
	s_add_i32 s37, 0, 0x1c000
	ds_read_b128 v[148:151], v140
	ds_read_b128 v[166:169], v140 offset:1024
	ds_read_b128 v[170:173], v140 offset:2048
	ds_read_b128 v[174:177], v140 offset:3072
	v_add_u32_e32 v140, s37, v154
	ds_read_b128 v[178:181], v140
	ds_read_b128 v[182:185], v140 offset:1024
	ds_read_b128 v[186:189], v140 offset:2048
	ds_read_b128 v[190:193], v140 offset:3072
	s_add_u32 s60, s60, 0x2b0000
	s_addc_u32 s61, s61, 0
	s_mov_b32 m0, s69
	v_lshl_add_u64 v[232:233], s[60:61], 0, v[132:133]
	ds_read_b128 v[194:197], v158 offset:32768
	ds_read_b128 v[202:205], v158 offset:33792
	ds_read_b128 v[206:209], v158 offset:34816
	ds_read_b128 v[210:213], v158 offset:35840
	ds_read_b128 v[214:217], v158 offset:36864
	ds_read_b128 v[218:221], v158 offset:37888
	ds_read_b128 v[222:225], v158 offset:38912
	ds_read_b128 v[226:229], v158 offset:39936
	global_load_lds_dwordx4 v[232:233], off
	v_lshl_add_u64 v[232:233], s[60:61], 0, v[136:137]
	s_mov_b32 m0, s70
	s_nop 0
	global_load_lds_dwordx4 v[232:233], off
	s_waitcnt vmcnt(8)
	s_waitcnt lgkmcnt(0)
	s_barrier
	s_setprio 1
	s_waitcnt lgkmcnt(0)
	v_mfma_f32_16x16x32_bf16 v[126:129], v[148:151], v[194:197], v[126:129]
	v_mfma_f32_16x16x32_bf16 v[126:129], v[166:169], v[202:205], v[126:129]
	v_mfma_f32_16x16x32_bf16 v[122:125], v[174:177], v[202:205], v[122:125]
	v_mfma_f32_16x16x32_bf16 v[122:125], v[170:173], v[194:197], v[122:125]
	v_mfma_f32_16x16x32_bf16 v[118:121], v[178:181], v[194:197], v[118:121]
	v_mfma_f32_16x16x32_bf16 v[118:121], v[182:185], v[202:205], v[118:121]
	v_mfma_f32_16x16x32_bf16 v[114:117], v[190:193], v[202:205], v[114:117]
	v_mfma_f32_16x16x32_bf16 v[114:117], v[186:189], v[194:197], v[114:117]
	v_mfma_f32_16x16x32_bf16 v[98:101], v[186:189], v[206:209], v[98:101]
	v_mfma_f32_16x16x32_bf16 v[98:101], v[190:193], v[210:213], v[98:101]
	v_mfma_f32_16x16x32_bf16 v[102:105], v[182:185], v[210:213], v[102:105]
	v_mfma_f32_16x16x32_bf16 v[102:105], v[178:181], v[206:209], v[102:105]
	v_mfma_f32_16x16x32_bf16 v[106:109], v[170:173], v[206:209], v[106:109]
	v_mfma_f32_16x16x32_bf16 v[106:109], v[174:177], v[210:213], v[106:109]
	v_mfma_f32_16x16x32_bf16 v[110:113], v[166:169], v[210:213], v[110:113]
	v_mfma_f32_16x16x32_bf16 v[110:113], v[148:151], v[206:209], v[110:113]
	v_mfma_f32_16x16x32_bf16 v[94:97], v[148:151], v[214:217], v[94:97]
	v_mfma_f32_16x16x32_bf16 v[94:97], v[166:169], v[218:221], v[94:97]
	v_mfma_f32_16x16x32_bf16 v[90:93], v[174:177], v[218:221], v[90:93]
	v_mfma_f32_16x16x32_bf16 v[90:93], v[170:173], v[214:217], v[90:93]
	v_mfma_f32_16x16x32_bf16 v[86:89], v[178:181], v[214:217], v[86:89]
	v_mfma_f32_16x16x32_bf16 v[86:89], v[182:185], v[218:221], v[86:89]
	v_mfma_f32_16x16x32_bf16 v[82:85], v[190:193], v[218:221], v[82:85]
	v_mfma_f32_16x16x32_bf16 v[82:85], v[186:189], v[214:217], v[82:85]
	v_mfma_f32_16x16x32_bf16 v[66:69], v[186:189], v[222:225], v[66:69]
	v_mfma_f32_16x16x32_bf16 v[66:69], v[190:193], v[226:229], v[66:69]
	v_mfma_f32_16x16x32_bf16 v[70:73], v[182:185], v[226:229], v[70:73]
	v_mfma_f32_16x16x32_bf16 v[70:73], v[178:181], v[222:225], v[70:73]
	v_mfma_f32_16x16x32_bf16 v[74:77], v[170:173], v[222:225], v[74:77]
	v_mfma_f32_16x16x32_bf16 v[74:77], v[174:177], v[226:229], v[74:77]
	v_mfma_f32_16x16x32_bf16 v[78:81], v[166:169], v[226:229], v[78:81]
	v_mfma_f32_16x16x32_bf16 v[78:81], v[148:151], v[222:225], v[78:81]
	s_setprio 0
	s_barrier
	s_add_i32 s36, s36, s64
	v_lshl_add_u64 v[152:153], v[152:153], 0, s[20:21]
	s_mov_b32 m0, s36
	ds_read_b128 v[194:197], v158 offset:49152
	ds_read_b128 v[202:205], v158 offset:50176
	ds_read_b128 v[206:209], v158 offset:51200
	ds_read_b128 v[210:213], v158 offset:52224
	ds_read_b128 v[214:217], v158 offset:53248
	ds_read_b128 v[218:221], v158 offset:54272
	ds_read_b128 v[222:225], v158 offset:55296
	ds_read_b128 v[226:229], v158 offset:56320
	global_load_lds_dwordx4 v[152:153], off
	s_add_i32 m0, s36, 0x2000
	s_add_u32 s58, s58, 0x2b0080
	v_lshl_add_u64 v[152:153], v[160:161], 0, s[20:21]
	s_addc_u32 s59, s59, 0
	s_add_i32 s36, s37, s64
	global_load_lds_dwordx4 v[152:153], off
	v_lshl_add_u64 v[152:153], s[58:59], 0, v[134:135]
	s_mov_b32 m0, s36
	s_nop 0
	global_load_lds_dwordx4 v[152:153], off
	v_lshl_add_u64 v[152:153], s[58:59], 0, v[138:139]
	s_add_i32 m0, s36, 0x2000
	s_nop 0
	global_load_lds_dwordx4 v[152:153], off
	v_lshl_add_u64 v[152:153], v[198:199], 0, s[20:21]
	s_mov_b32 m0, s73
	s_nop 0
	global_load_lds_dwordx4 v[152:153], off
	v_lshl_add_u64 v[152:153], v[230:231], 0, s[20:21]
	s_mov_b32 m0, s74
	s_nop 0
	global_load_lds_dwordx4 v[152:153], off
	s_waitcnt vmcnt(8)
	s_waitcnt lgkmcnt(0)
	s_barrier
	s_setprio 1
	s_waitcnt lgkmcnt(0)
	v_mfma_f32_16x16x32_bf16 v[62:65], v[148:151], v[194:197], v[62:65]
	v_mfma_f32_16x16x32_bf16 v[62:65], v[166:169], v[202:205], v[62:65]
	v_mfma_f32_16x16x32_bf16 v[58:61], v[174:177], v[202:205], v[58:61]
	v_mfma_f32_16x16x32_bf16 v[58:61], v[170:173], v[194:197], v[58:61]
	v_mfma_f32_16x16x32_bf16 v[54:57], v[178:181], v[194:197], v[54:57]
	v_mfma_f32_16x16x32_bf16 v[54:57], v[182:185], v[202:205], v[54:57]
	v_mfma_f32_16x16x32_bf16 v[50:53], v[190:193], v[202:205], v[50:53]
	v_mfma_f32_16x16x32_bf16 v[50:53], v[186:189], v[194:197], v[50:53]
	v_mfma_f32_16x16x32_bf16 v[34:37], v[186:189], v[206:209], v[34:37]
	v_mfma_f32_16x16x32_bf16 v[34:37], v[190:193], v[210:213], v[34:37]
	v_mfma_f32_16x16x32_bf16 v[38:41], v[182:185], v[210:213], v[38:41]
	v_mfma_f32_16x16x32_bf16 v[38:41], v[178:181], v[206:209], v[38:41]
	v_mfma_f32_16x16x32_bf16 v[42:45], v[170:173], v[206:209], v[42:45]
	v_mfma_f32_16x16x32_bf16 v[42:45], v[174:177], v[210:213], v[42:45]
	v_mfma_f32_16x16x32_bf16 v[46:49], v[166:169], v[210:213], v[46:49]
	v_mfma_f32_16x16x32_bf16 v[46:49], v[148:151], v[206:209], v[46:49]
	v_mfma_f32_16x16x32_bf16 v[30:33], v[148:151], v[214:217], v[30:33]
	v_mfma_f32_16x16x32_bf16 v[30:33], v[166:169], v[218:221], v[30:33]
	v_mfma_f32_16x16x32_bf16 v[26:29], v[174:177], v[218:221], v[26:29]
	v_mfma_f32_16x16x32_bf16 v[26:29], v[170:173], v[214:217], v[26:29]
	v_mfma_f32_16x16x32_bf16 v[22:25], v[178:181], v[214:217], v[22:25]
	v_mfma_f32_16x16x32_bf16 v[22:25], v[182:185], v[218:221], v[22:25]
	v_mfma_f32_16x16x32_bf16 v[18:21], v[190:193], v[218:221], v[18:21]
	v_mfma_f32_16x16x32_bf16 v[18:21], v[186:189], v[214:217], v[18:21]
	v_mfma_f32_16x16x32_bf16 v[2:5], v[186:189], v[222:225], v[2:5]
	v_mfma_f32_16x16x32_bf16 v[2:5], v[190:193], v[226:229], v[2:5]
	v_mfma_f32_16x16x32_bf16 v[6:9], v[182:185], v[226:229], v[6:9]
	v_mfma_f32_16x16x32_bf16 v[6:9], v[178:181], v[222:225], v[6:9]
	v_mfma_f32_16x16x32_bf16 v[10:13], v[170:173], v[222:225], v[10:13]
	v_mfma_f32_16x16x32_bf16 v[10:13], v[174:177], v[226:229], v[10:13]
	v_mfma_f32_16x16x32_bf16 v[14:17], v[166:169], v[226:229], v[14:17]
	v_mfma_f32_16x16x32_bf16 v[14:17], v[148:151], v[222:225], v[14:17]
	s_setprio 0
	s_barrier
	s_add_u32 s56, s56, 0x100
	s_addc_u32 s57, s57, 0
	s_add_u32 s90, s90, 0x100
	s_addc_u32 s91, s91, 0
	s_cmp_ge_i32 s92, s39
	s_mov_b32 s58, s92
	s_cbranch_scc0 .LBB0_1902
	s_and_b64 vcc, exec, s[24:25]
	s_cbranch_vccz .LBB0_1905

.LBB0_2138:
	ds_read_b128 v[146:149], v157
	ds_read_b128 v[164:167], v157 offset:1024
	ds_read_b128 v[168:171], v157 offset:2048
	ds_read_b128 v[172:175], v157 offset:3072
	ds_read_b128 v[176:179], v158
	ds_read_b128 v[180:183], v158 offset:1024
	ds_read_b128 v[184:187], v158 offset:2048
	ds_read_b128 v[188:191], v158 offset:3072
	s_add_u32 s24, s22, 0xfff00080
	s_addc_u32 s25, s23, -1
	s_cmp_eq_u32 s54, 60
	s_cselect_b32 s35, s15, s25
	s_cselect_b32 s34, s50, s24
	s_cselect_b32 s25, s13, s53
	s_cselect_b32 s24, s51, s52
	v_lshl_add_u64 v[150:151], s[22:23], 0, v[138:139]
	s_add_i32 m0, s21, 0xc000
	ds_read_b128 v[192:195], v159
	ds_read_b128 v[196:199], v159 offset:1024
	ds_read_b128 v[200:203], v159 offset:2048
	ds_read_b128 v[204:207], v159 offset:3072
	ds_read_b128 v[208:211], v159 offset:4096
	ds_read_b128 v[212:215], v159 offset:5120
	ds_read_b128 v[216:219], v159 offset:6144
	ds_read_b128 v[220:223], v159 offset:7168
	global_load_lds_dwordx4 v[150:151], off
	v_lshl_add_u64 v[150:151], s[22:23], 0, v[140:141]
	s_add_i32 m0, s21, 0xe000
	s_nop 0
	global_load_lds_dwordx4 v[150:151], off
	s_waitcnt vmcnt(8)
	s_waitcnt lgkmcnt(0)
	s_barrier
	s_setprio 1
	s_waitcnt lgkmcnt(0)
	v_mfma_f32_16x16x32_bf16 v[126:129], v[146:149], v[192:195], v[126:129]
	v_mfma_f32_16x16x32_bf16 v[126:129], v[164:167], v[196:199], v[126:129]
	v_mfma_f32_16x16x32_bf16 v[122:125], v[172:175], v[196:199], v[122:125]
	v_mfma_f32_16x16x32_bf16 v[122:125], v[168:171], v[192:195], v[122:125]
	v_mfma_f32_16x16x32_bf16 v[118:121], v[176:179], v[192:195], v[118:121]
	v_mfma_f32_16x16x32_bf16 v[118:121], v[180:183], v[196:199], v[118:121]
	v_mfma_f32_16x16x32_bf16 v[114:117], v[188:191], v[196:199], v[114:117]
	v_mfma_f32_16x16x32_bf16 v[114:117], v[184:187], v[192:195], v[114:117]
	v_mfma_f32_16x16x32_bf16 v[98:101], v[184:187], v[200:203], v[98:101]
	v_mfma_f32_16x16x32_bf16 v[98:101], v[188:191], v[204:207], v[98:101]
	v_mfma_f32_16x16x32_bf16 v[102:105], v[180:183], v[204:207], v[102:105]
	v_mfma_f32_16x16x32_bf16 v[102:105], v[176:179], v[200:203], v[102:105]
	v_mfma_f32_16x16x32_bf16 v[106:109], v[168:171], v[200:203], v[106:109]
	v_mfma_f32_16x16x32_bf16 v[106:109], v[172:175], v[204:207], v[106:109]
	v_mfma_f32_16x16x32_bf16 v[110:113], v[164:167], v[204:207], v[110:113]
	v_mfma_f32_16x16x32_bf16 v[110:113], v[146:149], v[200:203], v[110:113]
	v_mfma_f32_16x16x32_bf16 v[94:97], v[146:149], v[208:211], v[94:97]
	v_mfma_f32_16x16x32_bf16 v[94:97], v[164:167], v[212:215], v[94:97]
	v_mfma_f32_16x16x32_bf16 v[90:93], v[172:175], v[212:215], v[90:93]
	v_mfma_f32_16x16x32_bf16 v[90:93], v[168:171], v[208:211], v[90:93]
	v_mfma_f32_16x16x32_bf16 v[86:89], v[176:179], v[208:211], v[86:89]
	v_mfma_f32_16x16x32_bf16 v[86:89], v[180:183], v[212:215], v[86:89]
	v_mfma_f32_16x16x32_bf16 v[82:85], v[188:191], v[212:215], v[82:85]
	v_mfma_f32_16x16x32_bf16 v[82:85], v[184:187], v[208:211], v[82:85]
	v_mfma_f32_16x16x32_bf16 v[66:69], v[184:187], v[216:219], v[66:69]
	v_mfma_f32_16x16x32_bf16 v[66:69], v[188:191], v[220:223], v[66:69]
	v_mfma_f32_16x16x32_bf16 v[70:73], v[180:183], v[220:223], v[70:73]
	v_mfma_f32_16x16x32_bf16 v[70:73], v[176:179], v[216:219], v[70:73]
	v_mfma_f32_16x16x32_bf16 v[74:77], v[168:171], v[216:219], v[74:77]
	v_mfma_f32_16x16x32_bf16 v[74:77], v[172:175], v[220:223], v[74:77]
	v_mfma_f32_16x16x32_bf16 v[78:81], v[164:167], v[220:223], v[78:81]
	v_mfma_f32_16x16x32_bf16 v[78:81], v[146:149], v[216:219], v[78:81]
	s_setprio 0
	s_barrier
	s_add_i32 s55, s47, s27
	v_lshl_add_u64 v[150:151], s[24:25], 0, v[134:135]
	s_mov_b32 m0, s55
	ds_read_b128 v[192:195], v159 offset:16384
	ds_read_b128 v[196:199], v159 offset:17408
	ds_read_b128 v[200:203], v159 offset:18432
	ds_read_b128 v[204:207], v159 offset:19456
	ds_read_b128 v[208:211], v159 offset:20480
	ds_read_b128 v[212:215], v159 offset:21504
	ds_read_b128 v[216:219], v159 offset:22528
	ds_read_b128 v[220:223], v159 offset:23552
	global_load_lds_dwordx4 v[150:151], off
	s_add_i32 m0, s55, 0x2000
	s_add_u32 s56, s24, 0x100000
	v_lshl_add_u64 v[160:161], s[24:25], 0, v[130:131]
	s_addc_u32 s57, s25, 0
	s_add_i32 s55, s48, s27
	global_load_lds_dwordx4 v[160:161], off
	v_lshl_add_u64 v[224:225], s[56:57], 0, v[134:135]
	s_mov_b32 m0, s55
	v_lshl_add_u64 v[226:227], s[34:35], 0, v[132:133]
	global_load_lds_dwordx4 v[224:225], off
	v_lshl_add_u64 v[224:225], s[56:57], 0, v[130:131]
	s_add_i32 m0, s55, 0x2000
	s_nop 0
	global_load_lds_dwordx4 v[224:225], off
	v_lshl_add_u64 v[224:225], s[34:35], 0, v[136:137]
	s_mov_b32 m0, s21
	s_nop 0
	global_load_lds_dwordx4 v[224:225], off
	s_mov_b32 m0, s40
	s_nop 0
	global_load_lds_dwordx4 v[226:227], off
	s_waitcnt vmcnt(8)
	s_waitcnt lgkmcnt(0)
	s_barrier
	s_setprio 1
	s_waitcnt lgkmcnt(0)
	v_mfma_f32_16x16x32_bf16 v[62:65], v[146:149], v[192:195], v[62:65]
	v_mfma_f32_16x16x32_bf16 v[62:65], v[164:167], v[196:199], v[62:65]
	v_mfma_f32_16x16x32_bf16 v[58:61], v[172:175], v[196:199], v[58:61]
	v_mfma_f32_16x16x32_bf16 v[58:61], v[168:171], v[192:195], v[58:61]
	v_mfma_f32_16x16x32_bf16 v[54:57], v[176:179], v[192:195], v[54:57]
	v_mfma_f32_16x16x32_bf16 v[54:57], v[180:183], v[196:199], v[54:57]
	v_mfma_f32_16x16x32_bf16 v[50:53], v[188:191], v[196:199], v[50:53]
	v_mfma_f32_16x16x32_bf16 v[50:53], v[184:187], v[192:195], v[50:53]
	v_mfma_f32_16x16x32_bf16 v[34:37], v[184:187], v[200:203], v[34:37]
	v_mfma_f32_16x16x32_bf16 v[34:37], v[188:191], v[204:207], v[34:37]
	v_mfma_f32_16x16x32_bf16 v[38:41], v[180:183], v[204:207], v[38:41]
	v_mfma_f32_16x16x32_bf16 v[38:41], v[176:179], v[200:203], v[38:41]
	v_mfma_f32_16x16x32_bf16 v[42:45], v[168:171], v[200:203], v[42:45]
	v_mfma_f32_16x16x32_bf16 v[42:45], v[172:175], v[204:207], v[42:45]
	v_mfma_f32_16x16x32_bf16 v[46:49], v[164:167], v[204:207], v[46:49]
	v_mfma_f32_16x16x32_bf16 v[46:49], v[146:149], v[200:203], v[46:49]
	v_mfma_f32_16x16x32_bf16 v[30:33], v[146:149], v[208:211], v[30:33]
	v_mfma_f32_16x16x32_bf16 v[30:33], v[164:167], v[212:215], v[30:33]
	v_mfma_f32_16x16x32_bf16 v[26:29], v[172:175], v[212:215], v[26:29]
	v_mfma_f32_16x16x32_bf16 v[26:29], v[168:171], v[208:211], v[26:29]
	v_mfma_f32_16x16x32_bf16 v[22:25], v[176:179], v[208:211], v[22:25]
	v_mfma_f32_16x16x32_bf16 v[22:25], v[180:183], v[212:215], v[22:25]
	v_mfma_f32_16x16x32_bf16 v[18:21], v[188:191], v[212:215], v[18:21]
	v_mfma_f32_16x16x32_bf16 v[18:21], v[184:187], v[208:211], v[18:21]
	v_mfma_f32_16x16x32_bf16 v[2:5], v[184:187], v[216:219], v[2:5]
	v_mfma_f32_16x16x32_bf16 v[2:5], v[188:191], v[220:223], v[2:5]
	v_mfma_f32_16x16x32_bf16 v[6:9], v[180:183], v[220:223], v[6:9]
	v_mfma_f32_16x16x32_bf16 v[6:9], v[176:179], v[216:219], v[6:9]
	v_mfma_f32_16x16x32_bf16 v[10:13], v[168:171], v[216:219], v[10:13]
	v_mfma_f32_16x16x32_bf16 v[10:13], v[172:175], v[220:223], v[10:13]
	v_mfma_f32_16x16x32_bf16 v[14:17], v[164:167], v[220:223], v[14:17]
	v_mfma_f32_16x16x32_bf16 v[14:17], v[146:149], v[216:219], v[14:17]
	s_setprio 0
	s_barrier
	s_add_i32 s55, 0, 0x18000
	v_add_u32_e32 v162, s55, v155
	s_add_i32 s56, 0, 0x1c000
	ds_read_b128 v[146:149], v162
	ds_read_b128 v[164:167], v162 offset:1024
	ds_read_b128 v[168:171], v162 offset:2048
	ds_read_b128 v[172:175], v162 offset:3072
	v_add_u32_e32 v162, s56, v155
	ds_read_b128 v[176:179], v162
	ds_read_b128 v[180:183], v162 offset:1024
	ds_read_b128 v[184:187], v162 offset:2048
	ds_read_b128 v[188:191], v162 offset:3072
	s_add_u32 s34, s34, 0x100000
	s_addc_u32 s35, s35, 0
	s_mov_b32 m0, s41
	v_lshl_add_u64 v[228:229], s[34:35], 0, v[136:137]
	ds_read_b128 v[192:195], v159 offset:32768
	ds_read_b128 v[196:199], v159 offset:33792
	ds_read_b128 v[200:203], v159 offset:34816
	ds_read_b128 v[204:207], v159 offset:35840
	ds_read_b128 v[208:211], v159 offset:36864
	ds_read_b128 v[212:215], v159 offset:37888
	ds_read_b128 v[216:219], v159 offset:38912
	ds_read_b128 v[220:223], v159 offset:39936
	global_load_lds_dwordx4 v[228:229], off
	v_lshl_add_u64 v[228:229], s[34:35], 0, v[132:133]
	s_mov_b32 m0, s42
	s_nop 0
	global_load_lds_dwordx4 v[228:229], off
	s_waitcnt vmcnt(8)
	s_waitcnt lgkmcnt(0)
	s_barrier
	s_setprio 1
	s_waitcnt lgkmcnt(0)
	v_mfma_f32_16x16x32_bf16 v[126:129], v[146:149], v[192:195], v[126:129]
	v_mfma_f32_16x16x32_bf16 v[126:129], v[164:167], v[196:199], v[126:129]
	v_mfma_f32_16x16x32_bf16 v[122:125], v[172:175], v[196:199], v[122:125]
	v_mfma_f32_16x16x32_bf16 v[122:125], v[168:171], v[192:195], v[122:125]
	v_mfma_f32_16x16x32_bf16 v[118:121], v[176:179], v[192:195], v[118:121]
	v_mfma_f32_16x16x32_bf16 v[118:121], v[180:183], v[196:199], v[118:121]
	v_mfma_f32_16x16x32_bf16 v[114:117], v[188:191], v[196:199], v[114:117]
	v_mfma_f32_16x16x32_bf16 v[114:117], v[184:187], v[192:195], v[114:117]
	v_mfma_f32_16x16x32_bf16 v[98:101], v[184:187], v[200:203], v[98:101]
	v_mfma_f32_16x16x32_bf16 v[98:101], v[188:191], v[204:207], v[98:101]
	v_mfma_f32_16x16x32_bf16 v[102:105], v[180:183], v[204:207], v[102:105]
	v_mfma_f32_16x16x32_bf16 v[102:105], v[176:179], v[200:203], v[102:105]
	v_mfma_f32_16x16x32_bf16 v[106:109], v[168:171], v[200:203], v[106:109]
	v_mfma_f32_16x16x32_bf16 v[106:109], v[172:175], v[204:207], v[106:109]
	v_mfma_f32_16x16x32_bf16 v[110:113], v[164:167], v[204:207], v[110:113]
	v_mfma_f32_16x16x32_bf16 v[110:113], v[146:149], v[200:203], v[110:113]
	v_mfma_f32_16x16x32_bf16 v[94:97], v[146:149], v[208:211], v[94:97]
	v_mfma_f32_16x16x32_bf16 v[94:97], v[164:167], v[212:215], v[94:97]
	v_mfma_f32_16x16x32_bf16 v[90:93], v[172:175], v[212:215], v[90:93]
	v_mfma_f32_16x16x32_bf16 v[90:93], v[168:171], v[208:211], v[90:93]
	v_mfma_f32_16x16x32_bf16 v[86:89], v[176:179], v[208:211], v[86:89]
	v_mfma_f32_16x16x32_bf16 v[86:89], v[180:183], v[212:215], v[86:89]
	v_mfma_f32_16x16x32_bf16 v[82:85], v[188:191], v[212:215], v[82:85]
	v_mfma_f32_16x16x32_bf16 v[82:85], v[184:187], v[208:211], v[82:85]
	v_mfma_f32_16x16x32_bf16 v[66:69], v[184:187], v[216:219], v[66:69]
	v_mfma_f32_16x16x32_bf16 v[66:69], v[188:191], v[220:223], v[66:69]
	v_mfma_f32_16x16x32_bf16 v[70:73], v[180:183], v[220:223], v[70:73]
	v_mfma_f32_16x16x32_bf16 v[70:73], v[176:179], v[216:219], v[70:73]
	v_mfma_f32_16x16x32_bf16 v[74:77], v[168:171], v[216:219], v[74:77]
	v_mfma_f32_16x16x32_bf16 v[74:77], v[172:175], v[220:223], v[74:77]
	v_mfma_f32_16x16x32_bf16 v[78:81], v[164:167], v[220:223], v[78:81]
	v_mfma_f32_16x16x32_bf16 v[78:81], v[146:149], v[216:219], v[78:81]
	s_setprio 0
	s_barrier
	s_add_i32 s34, s55, s27
	v_lshl_add_u64 v[150:151], v[150:151], 0, s[8:9]
	s_mov_b32 m0, s34
	ds_read_b128 v[192:195], v159 offset:49152
	ds_read_b128 v[196:199], v159 offset:50176
	ds_read_b128 v[200:203], v159 offset:51200
	ds_read_b128 v[204:207], v159 offset:52224
	ds_read_b128 v[208:211], v159 offset:53248
	ds_read_b128 v[212:215], v159 offset:54272
	ds_read_b128 v[216:219], v159 offset:55296
	ds_read_b128 v[220:223], v159 offset:56320
	global_load_lds_dwordx4 v[150:151], off
	s_add_i32 m0, s34, 0x2000
	s_add_u32 s24, s24, 0x100080
	v_lshl_add_u64 v[150:151], v[160:161], 0, s[8:9]
	s_addc_u32 s25, s25, 0
	s_add_i32 s34, s56, s27
	global_load_lds_dwordx4 v[150:151], off
	v_lshl_add_u64 v[150:151], s[24:25], 0, v[134:135]
	s_mov_b32 m0, s34
	s_nop 0
	global_load_lds_dwordx4 v[150:151], off
	v_lshl_add_u64 v[150:151], s[24:25], 0, v[130:131]
	s_add_i32 m0, s34, 0x2000
	s_nop 0
	global_load_lds_dwordx4 v[150:151], off
	v_lshl_add_u64 v[150:151], v[224:225], 0, s[8:9]
	s_mov_b32 m0, s44
	s_nop 0
	global_load_lds_dwordx4 v[150:151], off
	v_lshl_add_u64 v[150:151], v[226:227], 0, s[8:9]
	s_mov_b32 m0, s45
	s_nop 0
	global_load_lds_dwordx4 v[150:151], off
	s_waitcnt vmcnt(8)
	s_waitcnt lgkmcnt(0)
	s_barrier
	s_setprio 1
	s_waitcnt lgkmcnt(0)
	v_mfma_f32_16x16x32_bf16 v[62:65], v[146:149], v[192:195], v[62:65]
	v_mfma_f32_16x16x32_bf16 v[62:65], v[164:167], v[196:199], v[62:65]
	v_mfma_f32_16x16x32_bf16 v[58:61], v[172:175], v[196:199], v[58:61]
	v_mfma_f32_16x16x32_bf16 v[58:61], v[168:171], v[192:195], v[58:61]
	v_mfma_f32_16x16x32_bf16 v[54:57], v[176:179], v[192:195], v[54:57]
	v_mfma_f32_16x16x32_bf16 v[54:57], v[180:183], v[196:199], v[54:57]
	v_mfma_f32_16x16x32_bf16 v[50:53], v[188:191], v[196:199], v[50:53]
	v_mfma_f32_16x16x32_bf16 v[50:53], v[184:187], v[192:195], v[50:53]
	v_mfma_f32_16x16x32_bf16 v[34:37], v[184:187], v[200:203], v[34:37]
	v_mfma_f32_16x16x32_bf16 v[34:37], v[188:191], v[204:207], v[34:37]
	v_mfma_f32_16x16x32_bf16 v[38:41], v[180:183], v[204:207], v[38:41]
	v_mfma_f32_16x16x32_bf16 v[38:41], v[176:179], v[200:203], v[38:41]
	v_mfma_f32_16x16x32_bf16 v[42:45], v[168:171], v[200:203], v[42:45]
	v_mfma_f32_16x16x32_bf16 v[42:45], v[172:175], v[204:207], v[42:45]
	v_mfma_f32_16x16x32_bf16 v[46:49], v[164:167], v[204:207], v[46:49]
	v_mfma_f32_16x16x32_bf16 v[46:49], v[146:149], v[200:203], v[46:49]
	v_mfma_f32_16x16x32_bf16 v[30:33], v[146:149], v[208:211], v[30:33]
	v_mfma_f32_16x16x32_bf16 v[30:33], v[164:167], v[212:215], v[30:33]
	v_mfma_f32_16x16x32_bf16 v[26:29], v[172:175], v[212:215], v[26:29]
	v_mfma_f32_16x16x32_bf16 v[26:29], v[168:171], v[208:211], v[26:29]
	v_mfma_f32_16x16x32_bf16 v[22:25], v[176:179], v[208:211], v[22:25]
	v_mfma_f32_16x16x32_bf16 v[22:25], v[180:183], v[212:215], v[22:25]
	v_mfma_f32_16x16x32_bf16 v[18:21], v[188:191], v[212:215], v[18:21]
	v_mfma_f32_16x16x32_bf16 v[18:21], v[184:187], v[208:211], v[18:21]
	v_mfma_f32_16x16x32_bf16 v[2:5], v[184:187], v[216:219], v[2:5]
	v_mfma_f32_16x16x32_bf16 v[2:5], v[188:191], v[220:223], v[2:5]
	v_mfma_f32_16x16x32_bf16 v[6:9], v[180:183], v[220:223], v[6:9]
	v_mfma_f32_16x16x32_bf16 v[6:9], v[176:179], v[216:219], v[6:9]
	v_mfma_f32_16x16x32_bf16 v[10:13], v[168:171], v[216:219], v[10:13]
	v_mfma_f32_16x16x32_bf16 v[10:13], v[172:175], v[220:223], v[10:13]
	v_mfma_f32_16x16x32_bf16 v[14:17], v[164:167], v[220:223], v[14:17]
	v_mfma_f32_16x16x32_bf16 v[14:17], v[146:149], v[216:219], v[14:17]
	s_setprio 0
	s_barrier
	s_add_i32 s54, s54, 2
	s_add_u32 s22, s22, 0x100
	s_addc_u32 s23, s23, 0
	s_add_u32 s52, s52, 0x100
	s_addc_u32 s53, s53, 0
	s_cmp_gt_u32 s54, 61
	s_cbranch_scc0 .LBB0_2138
	s_and_b64 vcc, exec, s[10:11]
	s_cbranch_vccz .LBB0_2141
	s_barrier

.LBB0_2158:
	ds_read_b128 v[146:149], v157
	ds_read_b128 v[164:167], v157 offset:1024
	ds_read_b128 v[168:171], v157 offset:2048
	ds_read_b128 v[172:175], v157 offset:3072
	ds_read_b128 v[176:179], v158
	ds_read_b128 v[180:183], v158 offset:1024
	ds_read_b128 v[184:187], v158 offset:2048
	ds_read_b128 v[188:191], v158 offset:3072
	s_add_u32 s26, s24, 0xfff00080
	s_addc_u32 s27, s25, -1
	s_cmp_eq_u32 s52, 60
	s_cselect_b32 s35, s17, s27
	s_cselect_b32 s34, s48, s26
	s_cselect_b32 s27, s15, s51
	s_cselect_b32 s26, s49, s50
	v_lshl_add_u64 v[150:151], s[24:25], 0, v[138:139]
	s_add_i32 m0, s23, 0xc000
	ds_read_b128 v[192:195], v159
	ds_read_b128 v[196:199], v159 offset:1024
	ds_read_b128 v[200:203], v159 offset:2048
	ds_read_b128 v[204:207], v159 offset:3072
	ds_read_b128 v[208:211], v159 offset:4096
	ds_read_b128 v[212:215], v159 offset:5120
	ds_read_b128 v[216:219], v159 offset:6144
	ds_read_b128 v[220:223], v159 offset:7168
	global_load_lds_dwordx4 v[150:151], off
	v_lshl_add_u64 v[150:151], s[24:25], 0, v[140:141]
	s_add_i32 m0, s23, 0xe000
	s_nop 0
	global_load_lds_dwordx4 v[150:151], off
	s_waitcnt vmcnt(8)
	s_waitcnt lgkmcnt(0)
	s_barrier
	s_setprio 1
	s_waitcnt lgkmcnt(0)
	v_mfma_f32_16x16x32_bf16 v[126:129], v[146:149], v[192:195], v[126:129]
	v_mfma_f32_16x16x32_bf16 v[126:129], v[164:167], v[196:199], v[126:129]
	v_mfma_f32_16x16x32_bf16 v[122:125], v[172:175], v[196:199], v[122:125]
	v_mfma_f32_16x16x32_bf16 v[122:125], v[168:171], v[192:195], v[122:125]
	v_mfma_f32_16x16x32_bf16 v[118:121], v[176:179], v[192:195], v[118:121]
	v_mfma_f32_16x16x32_bf16 v[118:121], v[180:183], v[196:199], v[118:121]
	v_mfma_f32_16x16x32_bf16 v[114:117], v[188:191], v[196:199], v[114:117]
	v_mfma_f32_16x16x32_bf16 v[114:117], v[184:187], v[192:195], v[114:117]
	v_mfma_f32_16x16x32_bf16 v[98:101], v[184:187], v[200:203], v[98:101]
	v_mfma_f32_16x16x32_bf16 v[98:101], v[188:191], v[204:207], v[98:101]
	v_mfma_f32_16x16x32_bf16 v[102:105], v[180:183], v[204:207], v[102:105]
	v_mfma_f32_16x16x32_bf16 v[102:105], v[176:179], v[200:203], v[102:105]
	v_mfma_f32_16x16x32_bf16 v[106:109], v[168:171], v[200:203], v[106:109]
	v_mfma_f32_16x16x32_bf16 v[106:109], v[172:175], v[204:207], v[106:109]
	v_mfma_f32_16x16x32_bf16 v[110:113], v[164:167], v[204:207], v[110:113]
	v_mfma_f32_16x16x32_bf16 v[110:113], v[146:149], v[200:203], v[110:113]
	v_mfma_f32_16x16x32_bf16 v[94:97], v[146:149], v[208:211], v[94:97]
	v_mfma_f32_16x16x32_bf16 v[94:97], v[164:167], v[212:215], v[94:97]
	v_mfma_f32_16x16x32_bf16 v[90:93], v[172:175], v[212:215], v[90:93]
	v_mfma_f32_16x16x32_bf16 v[90:93], v[168:171], v[208:211], v[90:93]
	v_mfma_f32_16x16x32_bf16 v[86:89], v[176:179], v[208:211], v[86:89]
	v_mfma_f32_16x16x32_bf16 v[86:89], v[180:183], v[212:215], v[86:89]
	v_mfma_f32_16x16x32_bf16 v[82:85], v[188:191], v[212:215], v[82:85]
	v_mfma_f32_16x16x32_bf16 v[82:85], v[184:187], v[208:211], v[82:85]
	v_mfma_f32_16x16x32_bf16 v[66:69], v[184:187], v[216:219], v[66:69]
	v_mfma_f32_16x16x32_bf16 v[66:69], v[188:191], v[220:223], v[66:69]
	v_mfma_f32_16x16x32_bf16 v[70:73], v[180:183], v[220:223], v[70:73]
	v_mfma_f32_16x16x32_bf16 v[70:73], v[176:179], v[216:219], v[70:73]
	v_mfma_f32_16x16x32_bf16 v[74:77], v[168:171], v[216:219], v[74:77]
	v_mfma_f32_16x16x32_bf16 v[74:77], v[172:175], v[220:223], v[74:77]
	v_mfma_f32_16x16x32_bf16 v[78:81], v[164:167], v[220:223], v[78:81]
	v_mfma_f32_16x16x32_bf16 v[78:81], v[146:149], v[216:219], v[78:81]
	s_setprio 0
	s_barrier
	s_add_i32 s53, s45, s38
	v_lshl_add_u64 v[150:151], s[26:27], 0, v[132:133]
	s_mov_b32 m0, s53
	ds_read_b128 v[192:195], v159 offset:16384
	ds_read_b128 v[196:199], v159 offset:17408
	ds_read_b128 v[200:203], v159 offset:18432
	ds_read_b128 v[204:207], v159 offset:19456
	ds_read_b128 v[208:211], v159 offset:20480
	ds_read_b128 v[212:215], v159 offset:21504
	ds_read_b128 v[216:219], v159 offset:22528
	ds_read_b128 v[220:223], v159 offset:23552
	global_load_lds_dwordx4 v[150:151], off
	s_add_i32 m0, s53, 0x2000
	s_add_u32 s54, s26, 0x100000
	v_lshl_add_u64 v[160:161], s[26:27], 0, v[134:135]
	s_addc_u32 s55, s27, 0
	s_add_i32 s53, s46, s38
	global_load_lds_dwordx4 v[160:161], off
	v_lshl_add_u64 v[224:225], s[54:55], 0, v[132:133]
	s_mov_b32 m0, s53
	v_lshl_add_u64 v[226:227], s[34:35], 0, v[136:137]
	global_load_lds_dwordx4 v[224:225], off
	v_lshl_add_u64 v[224:225], s[54:55], 0, v[134:135]
	s_add_i32 m0, s53, 0x2000
	s_nop 0
	global_load_lds_dwordx4 v[224:225], off
	v_lshl_add_u64 v[224:225], s[34:35], 0, v[130:131]
	s_mov_b32 m0, s23
	s_nop 0
	global_load_lds_dwordx4 v[224:225], off
	s_mov_b32 m0, s40
	s_nop 0
	global_load_lds_dwordx4 v[226:227], off
	s_waitcnt vmcnt(8)
	s_waitcnt lgkmcnt(0)
	s_barrier
	s_setprio 1
	s_waitcnt lgkmcnt(0)
	v_mfma_f32_16x16x32_bf16 v[62:65], v[146:149], v[192:195], v[62:65]
	v_mfma_f32_16x16x32_bf16 v[62:65], v[164:167], v[196:199], v[62:65]
	v_mfma_f32_16x16x32_bf16 v[58:61], v[172:175], v[196:199], v[58:61]
	v_mfma_f32_16x16x32_bf16 v[58:61], v[168:171], v[192:195], v[58:61]
	v_mfma_f32_16x16x32_bf16 v[54:57], v[176:179], v[192:195], v[54:57]
	v_mfma_f32_16x16x32_bf16 v[54:57], v[180:183], v[196:199], v[54:57]
	v_mfma_f32_16x16x32_bf16 v[50:53], v[188:191], v[196:199], v[50:53]
	v_mfma_f32_16x16x32_bf16 v[50:53], v[184:187], v[192:195], v[50:53]
	v_mfma_f32_16x16x32_bf16 v[34:37], v[184:187], v[200:203], v[34:37]
	v_mfma_f32_16x16x32_bf16 v[34:37], v[188:191], v[204:207], v[34:37]
	v_mfma_f32_16x16x32_bf16 v[38:41], v[180:183], v[204:207], v[38:41]
	v_mfma_f32_16x16x32_bf16 v[38:41], v[176:179], v[200:203], v[38:41]
	v_mfma_f32_16x16x32_bf16 v[42:45], v[168:171], v[200:203], v[42:45]
	v_mfma_f32_16x16x32_bf16 v[42:45], v[172:175], v[204:207], v[42:45]
	v_mfma_f32_16x16x32_bf16 v[46:49], v[164:167], v[204:207], v[46:49]
	v_mfma_f32_16x16x32_bf16 v[46:49], v[146:149], v[200:203], v[46:49]
	v_mfma_f32_16x16x32_bf16 v[30:33], v[146:149], v[208:211], v[30:33]
	v_mfma_f32_16x16x32_bf16 v[30:33], v[164:167], v[212:215], v[30:33]
	v_mfma_f32_16x16x32_bf16 v[26:29], v[172:175], v[212:215], v[26:29]
	v_mfma_f32_16x16x32_bf16 v[26:29], v[168:171], v[208:211], v[26:29]
	v_mfma_f32_16x16x32_bf16 v[22:25], v[176:179], v[208:211], v[22:25]
	v_mfma_f32_16x16x32_bf16 v[22:25], v[180:183], v[212:215], v[22:25]
	v_mfma_f32_16x16x32_bf16 v[18:21], v[188:191], v[212:215], v[18:21]
	v_mfma_f32_16x16x32_bf16 v[18:21], v[184:187], v[208:211], v[18:21]
	v_mfma_f32_16x16x32_bf16 v[2:5], v[184:187], v[216:219], v[2:5]
	v_mfma_f32_16x16x32_bf16 v[2:5], v[188:191], v[220:223], v[2:5]
	v_mfma_f32_16x16x32_bf16 v[6:9], v[180:183], v[220:223], v[6:9]
	v_mfma_f32_16x16x32_bf16 v[6:9], v[176:179], v[216:219], v[6:9]
	v_mfma_f32_16x16x32_bf16 v[10:13], v[168:171], v[216:219], v[10:13]
	v_mfma_f32_16x16x32_bf16 v[10:13], v[172:175], v[220:223], v[10:13]
	v_mfma_f32_16x16x32_bf16 v[14:17], v[164:167], v[220:223], v[14:17]
	v_mfma_f32_16x16x32_bf16 v[14:17], v[146:149], v[216:219], v[14:17]
	s_setprio 0
	s_barrier
	s_add_i32 s53, 0, 0x18000
	v_add_u32_e32 v162, s53, v155
	s_add_i32 s54, 0, 0x1c000
	ds_read_b128 v[146:149], v162
	ds_read_b128 v[164:167], v162 offset:1024
	ds_read_b128 v[168:171], v162 offset:2048
	ds_read_b128 v[172:175], v162 offset:3072
	v_add_u32_e32 v162, s54, v155
	ds_read_b128 v[176:179], v162
	ds_read_b128 v[180:183], v162 offset:1024
	ds_read_b128 v[184:187], v162 offset:2048
	ds_read_b128 v[188:191], v162 offset:3072
	s_add_u32 s34, s34, 0x100000
	s_addc_u32 s35, s35, 0
	s_mov_b32 m0, s41
	v_lshl_add_u64 v[228:229], s[34:35], 0, v[130:131]
	ds_read_b128 v[192:195], v159 offset:32768
	ds_read_b128 v[196:199], v159 offset:33792
	ds_read_b128 v[200:203], v159 offset:34816
	ds_read_b128 v[204:207], v159 offset:35840
	ds_read_b128 v[208:211], v159 offset:36864
	ds_read_b128 v[212:215], v159 offset:37888
	ds_read_b128 v[216:219], v159 offset:38912
	ds_read_b128 v[220:223], v159 offset:39936
	global_load_lds_dwordx4 v[228:229], off
	v_lshl_add_u64 v[228:229], s[34:35], 0, v[136:137]
	s_mov_b32 m0, s42
	s_nop 0
	global_load_lds_dwordx4 v[228:229], off
	s_waitcnt vmcnt(8)
	s_waitcnt lgkmcnt(0)
	s_barrier
	s_setprio 1
	s_waitcnt lgkmcnt(0)
	v_mfma_f32_16x16x32_bf16 v[126:129], v[146:149], v[192:195], v[126:129]
	v_mfma_f32_16x16x32_bf16 v[126:129], v[164:167], v[196:199], v[126:129]
	v_mfma_f32_16x16x32_bf16 v[122:125], v[172:175], v[196:199], v[122:125]
	v_mfma_f32_16x16x32_bf16 v[122:125], v[168:171], v[192:195], v[122:125]
	v_mfma_f32_16x16x32_bf16 v[118:121], v[176:179], v[192:195], v[118:121]
	v_mfma_f32_16x16x32_bf16 v[118:121], v[180:183], v[196:199], v[118:121]
	v_mfma_f32_16x16x32_bf16 v[114:117], v[188:191], v[196:199], v[114:117]
	v_mfma_f32_16x16x32_bf16 v[114:117], v[184:187], v[192:195], v[114:117]
	v_mfma_f32_16x16x32_bf16 v[98:101], v[184:187], v[200:203], v[98:101]
	v_mfma_f32_16x16x32_bf16 v[98:101], v[188:191], v[204:207], v[98:101]
	v_mfma_f32_16x16x32_bf16 v[102:105], v[180:183], v[204:207], v[102:105]
	v_mfma_f32_16x16x32_bf16 v[102:105], v[176:179], v[200:203], v[102:105]
	v_mfma_f32_16x16x32_bf16 v[106:109], v[168:171], v[200:203], v[106:109]
	v_mfma_f32_16x16x32_bf16 v[106:109], v[172:175], v[204:207], v[106:109]
	v_mfma_f32_16x16x32_bf16 v[110:113], v[164:167], v[204:207], v[110:113]
	v_mfma_f32_16x16x32_bf16 v[110:113], v[146:149], v[200:203], v[110:113]
	v_mfma_f32_16x16x32_bf16 v[94:97], v[146:149], v[208:211], v[94:97]
	v_mfma_f32_16x16x32_bf16 v[94:97], v[164:167], v[212:215], v[94:97]
	v_mfma_f32_16x16x32_bf16 v[90:93], v[172:175], v[212:215], v[90:93]
	v_mfma_f32_16x16x32_bf16 v[90:93], v[168:171], v[208:211], v[90:93]
	v_mfma_f32_16x16x32_bf16 v[86:89], v[176:179], v[208:211], v[86:89]
	v_mfma_f32_16x16x32_bf16 v[86:89], v[180:183], v[212:215], v[86:89]
	v_mfma_f32_16x16x32_bf16 v[82:85], v[188:191], v[212:215], v[82:85]
	v_mfma_f32_16x16x32_bf16 v[82:85], v[184:187], v[208:211], v[82:85]
	v_mfma_f32_16x16x32_bf16 v[66:69], v[184:187], v[216:219], v[66:69]
	v_mfma_f32_16x16x32_bf16 v[66:69], v[188:191], v[220:223], v[66:69]
	v_mfma_f32_16x16x32_bf16 v[70:73], v[180:183], v[220:223], v[70:73]
	v_mfma_f32_16x16x32_bf16 v[70:73], v[176:179], v[216:219], v[70:73]
	v_mfma_f32_16x16x32_bf16 v[74:77], v[168:171], v[216:219], v[74:77]
	v_mfma_f32_16x16x32_bf16 v[74:77], v[172:175], v[220:223], v[74:77]
	v_mfma_f32_16x16x32_bf16 v[78:81], v[164:167], v[220:223], v[78:81]
	v_mfma_f32_16x16x32_bf16 v[78:81], v[146:149], v[216:219], v[78:81]
	s_setprio 0
	s_barrier
	s_add_i32 s34, s53, s38
	v_lshl_add_u64 v[150:151], v[150:151], 0, s[10:11]
	s_mov_b32 m0, s34
	ds_read_b128 v[192:195], v159 offset:49152
	ds_read_b128 v[196:199], v159 offset:50176
	ds_read_b128 v[200:203], v159 offset:51200
	ds_read_b128 v[204:207], v159 offset:52224
	ds_read_b128 v[208:211], v159 offset:53248
	ds_read_b128 v[212:215], v159 offset:54272
	ds_read_b128 v[216:219], v159 offset:55296
	ds_read_b128 v[220:223], v159 offset:56320
	global_load_lds_dwordx4 v[150:151], off
	s_add_i32 m0, s34, 0x2000
	s_add_u32 s26, s26, 0x100080
	v_lshl_add_u64 v[150:151], v[160:161], 0, s[10:11]
	s_addc_u32 s27, s27, 0
	s_add_i32 s34, s54, s38
	global_load_lds_dwordx4 v[150:151], off
	v_lshl_add_u64 v[150:151], s[26:27], 0, v[132:133]
	s_mov_b32 m0, s34
	s_nop 0
	global_load_lds_dwordx4 v[150:151], off
	v_lshl_add_u64 v[150:151], s[26:27], 0, v[134:135]
	s_add_i32 m0, s34, 0x2000
	s_nop 0
	global_load_lds_dwordx4 v[150:151], off
	v_lshl_add_u64 v[150:151], v[224:225], 0, s[10:11]
	s_mov_b32 m0, s43
	s_nop 0
	global_load_lds_dwordx4 v[150:151], off
	v_lshl_add_u64 v[150:151], v[226:227], 0, s[10:11]
	s_mov_b32 m0, s44
	s_nop 0
	global_load_lds_dwordx4 v[150:151], off
	s_waitcnt vmcnt(8)
	s_waitcnt lgkmcnt(0)
	s_barrier
	s_setprio 1
	s_waitcnt lgkmcnt(0)
	v_mfma_f32_16x16x32_bf16 v[62:65], v[146:149], v[192:195], v[62:65]
	v_mfma_f32_16x16x32_bf16 v[62:65], v[164:167], v[196:199], v[62:65]
	v_mfma_f32_16x16x32_bf16 v[58:61], v[172:175], v[196:199], v[58:61]
	v_mfma_f32_16x16x32_bf16 v[58:61], v[168:171], v[192:195], v[58:61]
	v_mfma_f32_16x16x32_bf16 v[54:57], v[176:179], v[192:195], v[54:57]
	v_mfma_f32_16x16x32_bf16 v[54:57], v[180:183], v[196:199], v[54:57]
	v_mfma_f32_16x16x32_bf16 v[50:53], v[188:191], v[196:199], v[50:53]
	v_mfma_f32_16x16x32_bf16 v[50:53], v[184:187], v[192:195], v[50:53]
	v_mfma_f32_16x16x32_bf16 v[34:37], v[184:187], v[200:203], v[34:37]
	v_mfma_f32_16x16x32_bf16 v[34:37], v[188:191], v[204:207], v[34:37]
	v_mfma_f32_16x16x32_bf16 v[38:41], v[180:183], v[204:207], v[38:41]
	v_mfma_f32_16x16x32_bf16 v[38:41], v[176:179], v[200:203], v[38:41]
	v_mfma_f32_16x16x32_bf16 v[42:45], v[168:171], v[200:203], v[42:45]
	v_mfma_f32_16x16x32_bf16 v[42:45], v[172:175], v[204:207], v[42:45]
	v_mfma_f32_16x16x32_bf16 v[46:49], v[164:167], v[204:207], v[46:49]
	v_mfma_f32_16x16x32_bf16 v[46:49], v[146:149], v[200:203], v[46:49]
	v_mfma_f32_16x16x32_bf16 v[30:33], v[146:149], v[208:211], v[30:33]
	v_mfma_f32_16x16x32_bf16 v[30:33], v[164:167], v[212:215], v[30:33]
	v_mfma_f32_16x16x32_bf16 v[26:29], v[172:175], v[212:215], v[26:29]
	v_mfma_f32_16x16x32_bf16 v[26:29], v[168:171], v[208:211], v[26:29]
	v_mfma_f32_16x16x32_bf16 v[22:25], v[176:179], v[208:211], v[22:25]
	v_mfma_f32_16x16x32_bf16 v[22:25], v[180:183], v[212:215], v[22:25]
	v_mfma_f32_16x16x32_bf16 v[18:21], v[188:191], v[212:215], v[18:21]
	v_mfma_f32_16x16x32_bf16 v[18:21], v[184:187], v[208:211], v[18:21]
	v_mfma_f32_16x16x32_bf16 v[2:5], v[184:187], v[216:219], v[2:5]
	v_mfma_f32_16x16x32_bf16 v[2:5], v[188:191], v[220:223], v[2:5]
	v_mfma_f32_16x16x32_bf16 v[6:9], v[180:183], v[220:223], v[6:9]
	v_mfma_f32_16x16x32_bf16 v[6:9], v[176:179], v[216:219], v[6:9]
	v_mfma_f32_16x16x32_bf16 v[10:13], v[168:171], v[216:219], v[10:13]
	v_mfma_f32_16x16x32_bf16 v[10:13], v[172:175], v[220:223], v[10:13]
	v_mfma_f32_16x16x32_bf16 v[14:17], v[164:167], v[220:223], v[14:17]
	v_mfma_f32_16x16x32_bf16 v[14:17], v[146:149], v[216:219], v[14:17]
	s_setprio 0
	s_barrier
	s_add_i32 s52, s52, 2
	s_add_u32 s24, s24, 0x100
	s_addc_u32 s25, s25, 0
	s_add_u32 s50, s50, 0x100
	s_addc_u32 s51, s51, 0
	s_cmp_gt_u32 s52, 61
	s_cbranch_scc0 .LBB0_2158
	s_and_b64 vcc, exec, s[12:13]
	s_cbranch_vccz .LBB0_2161
	s_barrier
